# GEMM epilogues with per-row scale (6 instances): the 8 serialized scale loads (each followed by vmcnt(0) that also waited for the previous stores) hoisted to the epilogue start
# baseline (speedup 1.0000x reference)
; #define PG8_STAGE(bufoff, gbase, voff) do { _Pragma("unroll") for (int _i = 0; _i < 2; ++_i) \
;         __builtin_amdgcn_global_load_lds((const unsigned*)((const char*)(gbase) + (voff)[_i]), (LAS unsigned*)(lds + (bufoff) + ldsw + _i * 8192), 16, 0, 0); } while (0)
; #define PG8_LDA(dst, b, h) do { _Pragma("unroll") for (int m = 0; m < 4; ++m) _Pragma("unroll") for (int k = 0; k < 2; ++k) dst[m][k] = *(const LAS bf16x8*)(lds + PG8_SA(b, h) + aoff + m * 2048 + k * 1024); } while (0)
; #define PG8_LDB(dst, b, h) do { _Pragma("unroll") for (int n = 0; n < 2; ++n) _Pragma("unroll") for (int k = 0; k < 2; ++k) dst[n][k] = *(const LAS bf16x8*)(lds + PG8_SB(b, h) + boff + n * 2048 + k * 1024); } while (0)
; #define PG8_MMA(ai, bj, At, Bt) do { __builtin_amdgcn_s_setprio(1); _Pragma("unroll") for (int m = 0; m < 4; ++m) _Pragma("unroll") for (int n = 0; n < 2; ++n) _Pragma("unroll") for (int k = 0; k < 2; ++k) \
;         acc[ai][bj][m][n] = __builtin_amdgcn_mfma_f32_16x16x32_bf16(Bt[n][k], At[m][k], acc[ai][bj][m][n], 0, 0, 0); __builtin_amdgcn_s_setprio(0); } while (0)
; #define PG8_WAIT_L(n) asm volatile("s_waitcnt lgkmcnt(" #n ")" ::: "memory")
; #define PG8_BAR __builtin_amdgcn_s_barrier()
; #define PG8_SCHED __builtin_amdgcn_sched_barrier(0)
; template <class PT, class Epi>
; __device__ __forceinline__ void gemm_phase_once(LAS unsigned char* lds, const PT& S, const Epi& E, bool epi_on) {
;     ...
;             PG8_LDB(B0, 0, 0); PG8_SCHED; PG8_LDA(At, 0, 0); PG8_STAGE(PG8_SA(1, 1), a1 + hstepA, voffA);
;             PG8_WAIT_L(8); PG8_BAR; PG8_WAIT_L(0); PG8_MMA(0, 0, At, B0); PG8_BAR; PG8_SCHED;
;             PG8_LDB(B1, 0, 1); PG8_STAGE(PG8_SB(0, 0), b2, voffB);
;             PG8_BAR; PG8_WAIT_L(0); PG8_MMA(0, 1, At, B1); PG8_BAR;
;             PG8_LDA(At, 0, 1); PG8_STAGE(PG8_SA(0, 0), a2, voffA);
;             PG8_BAR; PG8_WAIT_L(0); PG8_MMA(1, 0, At, B0); PG8_BAR; PG8_SCHED;
.LBB0_328:
	ds_read_b128 v[142:145], v148
	ds_read_b128 v[152:155], v148 offset:1024
	ds_read_b128 v[156:159], v148 offset:2048
	ds_read_b128 v[160:163], v148 offset:3072
	s_add_u32 s22, s20, 0xfff80080
	s_addc_u32 s23, s21, -1
	s_cmp_eq_u32 s45, 28
	s_cselect_b32 s25, s7, s23
	s_cselect_b32 s24, s41, s22
	s_cselect_b32 s23, s11, s44
	s_cselect_b32 s22, s42, s43
	v_lshl_add_u64 v[198:199], s[20:21], 0, v[138:139]
	s_add_i32 m0, s28, 0xc000
	ds_read_b128 v[166:169], v149
	ds_read_b128 v[170:173], v149 offset:1024
	ds_read_b128 v[174:177], v149 offset:2048
	ds_read_b128 v[178:181], v149 offset:3072
	ds_read_b128 v[182:185], v149 offset:4096
	ds_read_b128 v[186:189], v149 offset:5120
	ds_read_b128 v[190:193], v149 offset:6144
	ds_read_b128 v[194:197], v149 offset:7168
	global_load_lds_dwordx4 v[198:199], off
	v_lshl_add_u64 v[198:199], s[20:21], 0, v[140:141]
	s_add_i32 m0, s28, 0xe000
	s_nop 0
	global_load_lds_dwordx4 v[198:199], off
	s_waitcnt lgkmcnt(8)
	s_barrier
	s_waitcnt lgkmcnt(0)
	s_setprio 1
	s_waitcnt lgkmcnt(0)
	v_mfma_f32_16x16x32_bf16 v[126:129], v[142:145], v[166:169], v[126:129]
	v_mfma_f32_16x16x32_bf16 v[122:125], v[156:159], v[166:169], v[122:125]
	v_mfma_f32_16x16x32_bf16 v[110:113], v[142:145], v[174:177], v[110:113]
	v_mfma_f32_16x16x32_bf16 v[106:109], v[156:159], v[174:177], v[106:109]
	v_mfma_f32_16x16x32_bf16 v[94:97], v[142:145], v[182:185], v[94:97]
	v_mfma_f32_16x16x32_bf16 v[90:93], v[156:159], v[182:185], v[90:93]
	v_mfma_f32_16x16x32_bf16 v[78:81], v[142:145], v[190:193], v[78:81]
	v_mfma_f32_16x16x32_bf16 v[74:77], v[156:159], v[190:193], v[74:77]
	v_mfma_f32_16x16x32_bf16 v[126:129], v[152:155], v[170:173], v[126:129]
	v_mfma_f32_16x16x32_bf16 v[122:125], v[160:163], v[170:173], v[122:125]
	v_mfma_f32_16x16x32_bf16 v[110:113], v[152:155], v[178:181], v[110:113]
	v_mfma_f32_16x16x32_bf16 v[106:109], v[160:163], v[178:181], v[106:109]
	v_mfma_f32_16x16x32_bf16 v[94:97], v[152:155], v[186:189], v[94:97]
	v_mfma_f32_16x16x32_bf16 v[90:93], v[160:163], v[186:189], v[90:93]
	v_mfma_f32_16x16x32_bf16 v[78:81], v[152:155], v[194:197], v[78:81]
	v_mfma_f32_16x16x32_bf16 v[74:77], v[160:163], v[194:197], v[74:77]
	s_setprio 0
	s_barrier
	s_add_i32 s46, s37, s26
	v_lshl_add_u64 v[214:215], s[22:23], 0, v[134:135]
	s_mov_b32 m0, s46
	ds_read_b128 v[198:201], v150
	ds_read_b128 v[202:205], v150 offset:1024
	ds_read_b128 v[206:209], v150 offset:2048
	ds_read_b128 v[210:213], v150 offset:3072
	global_load_lds_dwordx4 v[214:215], off
	v_lshl_add_u64 v[216:217], s[22:23], 0, v[130:131]
	s_add_i32 m0, s46, 0x2000
	s_nop 0
	global_load_lds_dwordx4 v[216:217], off
	s_barrier
	s_waitcnt lgkmcnt(0)
	s_setprio 1
	s_waitcnt lgkmcnt(0)
	v_mfma_f32_16x16x32_bf16 v[118:121], v[198:201], v[166:169], v[118:121]
	v_mfma_f32_16x16x32_bf16 v[114:117], v[206:209], v[166:169], v[114:117]
	v_mfma_f32_16x16x32_bf16 v[102:105], v[198:201], v[174:177], v[102:105]
	v_mfma_f32_16x16x32_bf16 v[98:101], v[206:209], v[174:177], v[98:101]
	v_mfma_f32_16x16x32_bf16 v[86:89], v[198:201], v[182:185], v[86:89]
	v_mfma_f32_16x16x32_bf16 v[82:85], v[206:209], v[182:185], v[82:85]
	v_mfma_f32_16x16x32_bf16 v[70:73], v[198:201], v[190:193], v[70:73]
	v_mfma_f32_16x16x32_bf16 v[66:69], v[206:209], v[190:193], v[66:69]
	v_mfma_f32_16x16x32_bf16 v[118:121], v[202:205], v[170:173], v[118:121]
	v_mfma_f32_16x16x32_bf16 v[114:117], v[210:213], v[170:173], v[114:117]
	v_mfma_f32_16x16x32_bf16 v[102:105], v[202:205], v[178:181], v[102:105]
	v_mfma_f32_16x16x32_bf16 v[98:101], v[210:213], v[178:181], v[98:101]
	v_mfma_f32_16x16x32_bf16 v[86:89], v[202:205], v[186:189], v[86:89]
	v_mfma_f32_16x16x32_bf16 v[82:85], v[210:213], v[186:189], v[82:85]
	v_mfma_f32_16x16x32_bf16 v[70:73], v[202:205], v[194:197], v[70:73]
	v_mfma_f32_16x16x32_bf16 v[66:69], v[210:213], v[194:197], v[66:69]
	s_setprio 0
	s_mov_b32 m0, s28
	v_lshl_add_u64 v[218:219], s[24:25], 0, v[136:137]
	s_barrier
	ds_read_b128 v[166:169], v149 offset:16384
	ds_read_b128 v[170:173], v149 offset:17408
	ds_read_b128 v[174:177], v149 offset:18432
	ds_read_b128 v[178:181], v149 offset:19456
	ds_read_b128 v[182:185], v149 offset:20480
	ds_read_b128 v[186:189], v149 offset:21504
	ds_read_b128 v[190:193], v149 offset:22528
	ds_read_b128 v[194:197], v149 offset:23552
	global_load_lds_dwordx4 v[218:219], off
	v_lshl_add_u64 v[220:221], s[24:25], 0, v[132:133]
	s_mov_b32 m0, s19
	s_nop 0
	global_load_lds_dwordx4 v[220:221], off
	s_barrier
	s_waitcnt lgkmcnt(0)
	s_setprio 1
	s_waitcnt lgkmcnt(0)
	v_mfma_f32_16x16x32_bf16 v[62:65], v[142:145], v[166:169], v[62:65]
	v_mfma_f32_16x16x32_bf16 v[58:61], v[156:159], v[166:169], v[58:61]
	v_mfma_f32_16x16x32_bf16 v[46:49], v[142:145], v[174:177], v[46:49]
	v_mfma_f32_16x16x32_bf16 v[42:45], v[156:159], v[174:177], v[42:45]
	v_mfma_f32_16x16x32_bf16 v[30:33], v[142:145], v[182:185], v[30:33]
	v_mfma_f32_16x16x32_bf16 v[26:29], v[156:159], v[182:185], v[26:29]
	v_mfma_f32_16x16x32_bf16 v[14:17], v[142:145], v[190:193], v[14:17]
	v_mfma_f32_16x16x32_bf16 v[10:13], v[156:159], v[190:193], v[10:13]
	v_mfma_f32_16x16x32_bf16 v[62:65], v[152:155], v[170:173], v[62:65]
	v_mfma_f32_16x16x32_bf16 v[58:61], v[160:163], v[170:173], v[58:61]
	v_mfma_f32_16x16x32_bf16 v[46:49], v[152:155], v[178:181], v[46:49]
	v_mfma_f32_16x16x32_bf16 v[42:45], v[160:163], v[178:181], v[42:45]
	v_mfma_f32_16x16x32_bf16 v[30:33], v[152:155], v[186:189], v[30:33]
	v_mfma_f32_16x16x32_bf16 v[26:29], v[160:163], v[186:189], v[26:29]
	v_mfma_f32_16x16x32_bf16 v[14:17], v[152:155], v[194:197], v[14:17]
	v_mfma_f32_16x16x32_bf16 v[10:13], v[160:163], v[194:197], v[10:13]
	s_setprio 0
	s_barrier
; #define PG8_STAGE(bufoff, gbase, voff) do { _Pragma("unroll") for (int _i = 0; _i < 2; ++_i) \
;         __builtin_amdgcn_global_load_lds((const unsigned*)((const char*)(gbase) + (voff)[_i]), (LAS unsigned*)(lds + (bufoff) + ldsw + _i * 8192), 16, 0, 0); } while (0)
; #define PG8_LDA(dst, b, h) do { _Pragma("unroll") for (int m = 0; m < 4; ++m) _Pragma("unroll") for (int k = 0; k < 2; ++k) dst[m][k] = *(const LAS bf16x8*)(lds + PG8_SA(b, h) + aoff + m * 2048 + k * 1024); } while (0)
; #define PG8_LDB(dst, b, h) do { _Pragma("unroll") for (int n = 0; n < 2; ++n) _Pragma("unroll") for (int k = 0; k < 2; ++k) dst[n][k] = *(const LAS bf16x8*)(lds + PG8_SB(b, h) + boff + n * 2048 + k * 1024); } while (0)
; #define PG8_MMA(ai, bj, At, Bt) do { __builtin_amdgcn_s_setprio(1); _Pragma("unroll") for (int m = 0; m < 4; ++m) _Pragma("unroll") for (int n = 0; n < 2; ++n) _Pragma("unroll") for (int k = 0; k < 2; ++k) \
;         acc[ai][bj][m][n] = __builtin_amdgcn_mfma_f32_16x16x32_bf16(Bt[n][k], At[m][k], acc[ai][bj][m][n], 0, 0, 0); __builtin_amdgcn_s_setprio(0); } while (0)
; #define PG8_WAIT_V(n) asm volatile("s_waitcnt vmcnt(" #n ")" ::: "memory")
; #define PG8_WAIT_L(n) asm volatile("s_waitcnt lgkmcnt(" #n ")" ::: "memory")
; #define PG8_BAR __builtin_amdgcn_s_barrier()
; #define PG8_SCHED __builtin_amdgcn_sched_barrier(0)
; template <class PT, class Epi>
; __device__ __forceinline__ void gemm_phase_once(LAS unsigned char* lds, const PT& S, const Epi& E, bool epi_on) {
;     ...
;             PG8_STAGE(PG8_SB(0, 1), b2 + hstepB, voffB);
;             PG8_WAIT_V(6); PG8_BAR; PG8_MMA(1, 1, At, B1); PG8_BAR;
;             PG8_LDB(B0, 1, 0); PG8_SCHED; PG8_LDA(At, 1, 0); PG8_STAGE(PG8_SA(0, 1), a2 + hstepA, voffA);
;             PG8_WAIT_L(8); PG8_BAR; PG8_WAIT_L(0); PG8_MMA(0, 0, At, B0); PG8_BAR; PG8_SCHED;
;             PG8_LDB(B1, 1, 1); PG8_STAGE(PG8_SB(1, 0), b3, voffB);
;             PG8_BAR; PG8_WAIT_L(0); PG8_MMA(0, 1, At, B1); PG8_BAR;
;             PG8_LDA(At, 1, 1); PG8_STAGE(PG8_SA(1, 0), a3, voffA);
;             PG8_BAR; PG8_WAIT_L(0); PG8_MMA(1, 0, At, B0); PG8_BAR; PG8_SCHED;
	s_add_u32 s46, s22, 0x80000
	s_addc_u32 s47, s23, 0
	s_add_i32 s48, s38, s26
	v_lshl_add_u64 v[142:143], s[46:47], 0, v[134:135]
	s_mov_b32 m0, s48
	s_nop 0
	global_load_lds_dwordx4 v[142:143], off
	v_lshl_add_u64 v[142:143], s[46:47], 0, v[130:131]
	s_add_i32 m0, s48, 0x2000
	s_nop 0
	global_load_lds_dwordx4 v[142:143], off
	s_waitcnt vmcnt(6)
	s_barrier
	s_setprio 1
	v_mfma_f32_16x16x32_bf16 v[54:57], v[198:201], v[166:169], v[54:57]
	v_mfma_f32_16x16x32_bf16 v[50:53], v[206:209], v[166:169], v[50:53]
	v_mfma_f32_16x16x32_bf16 v[38:41], v[198:201], v[174:177], v[38:41]
	v_mfma_f32_16x16x32_bf16 v[34:37], v[206:209], v[174:177], v[34:37]
	v_mfma_f32_16x16x32_bf16 v[22:25], v[198:201], v[182:185], v[22:25]
	v_mfma_f32_16x16x32_bf16 v[18:21], v[206:209], v[182:185], v[18:21]
	v_mfma_f32_16x16x32_bf16 v[6:9], v[198:201], v[190:193], v[6:9]
	v_mfma_f32_16x16x32_bf16 v[2:5], v[206:209], v[190:193], v[2:5]
	v_mfma_f32_16x16x32_bf16 v[54:57], v[202:205], v[170:173], v[54:57]
	v_mfma_f32_16x16x32_bf16 v[50:53], v[210:213], v[170:173], v[50:53]
	v_mfma_f32_16x16x32_bf16 v[38:41], v[202:205], v[178:181], v[38:41]
	v_mfma_f32_16x16x32_bf16 v[34:37], v[210:213], v[178:181], v[34:37]
	v_mfma_f32_16x16x32_bf16 v[22:25], v[202:205], v[186:189], v[22:25]
	v_mfma_f32_16x16x32_bf16 v[18:21], v[210:213], v[186:189], v[18:21]
	v_mfma_f32_16x16x32_bf16 v[6:9], v[202:205], v[194:197], v[6:9]
	v_mfma_f32_16x16x32_bf16 v[2:5], v[210:213], v[194:197], v[2:5]
	s_setprio 0
	s_add_i32 s46, 0, 0x18000
	v_add_u32_e32 v151, s46, v146
	s_barrier
	ds_read_b128 v[142:145], v151
	ds_read_b128 v[152:155], v151 offset:1024
	ds_read_b128 v[156:159], v151 offset:2048
	ds_read_b128 v[160:163], v151 offset:3072
	s_add_u32 s24, s24, 0x80000
	s_addc_u32 s25, s25, 0
	s_mov_b32 m0, s29
	v_lshl_add_u64 v[198:199], s[24:25], 0, v[136:137]
	ds_read_b128 v[166:169], v149 offset:32768
	ds_read_b128 v[170:173], v149 offset:33792
	ds_read_b128 v[174:177], v149 offset:34816
	ds_read_b128 v[178:181], v149 offset:35840
	ds_read_b128 v[182:185], v149 offset:36864
	ds_read_b128 v[186:189], v149 offset:37888
	ds_read_b128 v[190:193], v149 offset:38912
	ds_read_b128 v[194:197], v149 offset:39936
	global_load_lds_dwordx4 v[198:199], off
	v_lshl_add_u64 v[198:199], s[24:25], 0, v[132:133]
	s_mov_b32 m0, s30
	s_nop 0
	global_load_lds_dwordx4 v[198:199], off
	s_waitcnt lgkmcnt(8)
	s_barrier
	s_waitcnt lgkmcnt(0)
	s_setprio 1
	s_waitcnt lgkmcnt(0)
	v_mfma_f32_16x16x32_bf16 v[126:129], v[142:145], v[166:169], v[126:129]
	v_mfma_f32_16x16x32_bf16 v[122:125], v[156:159], v[166:169], v[122:125]
	v_mfma_f32_16x16x32_bf16 v[110:113], v[142:145], v[174:177], v[110:113]
	v_mfma_f32_16x16x32_bf16 v[106:109], v[156:159], v[174:177], v[106:109]
	v_mfma_f32_16x16x32_bf16 v[94:97], v[142:145], v[182:185], v[94:97]
	v_mfma_f32_16x16x32_bf16 v[90:93], v[156:159], v[182:185], v[90:93]
	v_mfma_f32_16x16x32_bf16 v[78:81], v[142:145], v[190:193], v[78:81]
	v_mfma_f32_16x16x32_bf16 v[74:77], v[156:159], v[190:193], v[74:77]
	v_mfma_f32_16x16x32_bf16 v[126:129], v[152:155], v[170:173], v[126:129]
	v_mfma_f32_16x16x32_bf16 v[122:125], v[160:163], v[170:173], v[122:125]
	v_mfma_f32_16x16x32_bf16 v[110:113], v[152:155], v[178:181], v[110:113]
	v_mfma_f32_16x16x32_bf16 v[106:109], v[160:163], v[178:181], v[106:109]
	v_mfma_f32_16x16x32_bf16 v[94:97], v[152:155], v[186:189], v[94:97]
	v_mfma_f32_16x16x32_bf16 v[90:93], v[160:163], v[186:189], v[90:93]
	v_mfma_f32_16x16x32_bf16 v[78:81], v[152:155], v[194:197], v[78:81]
	v_mfma_f32_16x16x32_bf16 v[74:77], v[160:163], v[194:197], v[74:77]
	s_setprio 0
	s_barrier
	s_add_i32 s24, 0, 0x1c000
	s_add_i32 s25, s46, s26
	v_add_u32_e32 v151, s24, v146
	v_lshl_add_u64 v[214:215], v[214:215], 0, s[8:9]
	s_mov_b32 m0, s25
	ds_read_b128 v[198:201], v151
	ds_read_b128 v[202:205], v151 offset:1024
	ds_read_b128 v[206:209], v151 offset:2048
	ds_read_b128 v[210:213], v151 offset:3072
	global_load_lds_dwordx4 v[214:215], off
	v_lshl_add_u64 v[214:215], v[216:217], 0, s[8:9]
	s_add_i32 m0, s25, 0x2000
	s_nop 0
	global_load_lds_dwordx4 v[214:215], off
	s_barrier
	s_waitcnt lgkmcnt(0)
	s_setprio 1
	s_waitcnt lgkmcnt(0)
	v_mfma_f32_16x16x32_bf16 v[118:121], v[198:201], v[166:169], v[118:121]
	v_mfma_f32_16x16x32_bf16 v[114:117], v[206:209], v[166:169], v[114:117]
	v_mfma_f32_16x16x32_bf16 v[102:105], v[198:201], v[174:177], v[102:105]
	v_mfma_f32_16x16x32_bf16 v[98:101], v[206:209], v[174:177], v[98:101]
	v_mfma_f32_16x16x32_bf16 v[86:89], v[198:201], v[182:185], v[86:89]
	v_mfma_f32_16x16x32_bf16 v[82:85], v[206:209], v[182:185], v[82:85]
	v_mfma_f32_16x16x32_bf16 v[70:73], v[198:201], v[190:193], v[70:73]
	v_mfma_f32_16x16x32_bf16 v[66:69], v[206:209], v[190:193], v[66:69]
	v_mfma_f32_16x16x32_bf16 v[118:121], v[202:205], v[170:173], v[118:121]
	v_mfma_f32_16x16x32_bf16 v[114:117], v[210:213], v[170:173], v[114:117]
	v_mfma_f32_16x16x32_bf16 v[102:105], v[202:205], v[178:181], v[102:105]
	v_mfma_f32_16x16x32_bf16 v[98:101], v[210:213], v[178:181], v[98:101]
	v_mfma_f32_16x16x32_bf16 v[86:89], v[202:205], v[186:189], v[86:89]
	v_mfma_f32_16x16x32_bf16 v[82:85], v[210:213], v[186:189], v[82:85]
	v_mfma_f32_16x16x32_bf16 v[70:73], v[202:205], v[194:197], v[70:73]
	v_mfma_f32_16x16x32_bf16 v[66:69], v[210:213], v[194:197], v[66:69]
	s_setprio 0
	s_mov_b32 m0, s34
	v_lshl_add_u64 v[214:215], v[218:219], 0, s[8:9]
	s_barrier
	ds_read_b128 v[166:169], v149 offset:49152
	ds_read_b128 v[170:173], v149 offset:50176
	ds_read_b128 v[174:177], v149 offset:51200
	ds_read_b128 v[178:181], v149 offset:52224
	ds_read_b128 v[182:185], v149 offset:53248
	ds_read_b128 v[186:189], v149 offset:54272
	ds_read_b128 v[190:193], v149 offset:55296
	ds_read_b128 v[194:197], v149 offset:56320
	global_load_lds_dwordx4 v[214:215], off
	v_lshl_add_u64 v[214:215], v[220:221], 0, s[8:9]
	s_mov_b32 m0, s35
	s_nop 0
	global_load_lds_dwordx4 v[214:215], off
	s_barrier
; #define PG8_STAGE(bufoff, gbase, voff) do { _Pragma("unroll") for (int _i = 0; _i < 2; ++_i) \
;         __builtin_amdgcn_global_load_lds((const unsigned*)((const char*)(gbase) + (voff)[_i]), (LAS unsigned*)(lds + (bufoff) + ldsw + _i * 8192), 16, 0, 0); } while (0)
; #define PG8_MMA(ai, bj, At, Bt) do { __builtin_amdgcn_s_setprio(1); _Pragma("unroll") for (int m = 0; m < 4; ++m) _Pragma("unroll") for (int n = 0; n < 2; ++n) _Pragma("unroll") for (int k = 0; k < 2; ++k) \
;         acc[ai][bj][m][n] = __builtin_amdgcn_mfma_f32_16x16x32_bf16(Bt[n][k], At[m][k], acc[ai][bj][m][n], 0, 0, 0); __builtin_amdgcn_s_setprio(0); } while (0)
; #define PG8_WAIT_V(n) asm volatile("s_waitcnt vmcnt(" #n ")" ::: "memory")
; #define PG8_WAIT_L(n) asm volatile("s_waitcnt lgkmcnt(" #n ")" ::: "memory")
; #define PG8_BAR __builtin_amdgcn_s_barrier()
; #define PG8_SCHED __builtin_amdgcn_sched_barrier(0)
;     __device__ __forceinline__ void operator()(const f32x4 (&acc)[2][2][4][2], const Unit& u, int wr, int wc, int fr, int fq) const {
;         const int row0 = u.pm * BM + wr * 64 + fr, col0 = u.pn * BM + wc * 32 + 8 * fq;
; #pragma unroll
;         for (int ai = 0; ai < 2; ++ai)
; #pragma unroll
;             for (int m = 0; m < 4; ++m) { const int row = row0 + ai * HALF + m * 16; const float rs = rowscale ? rowscale[row] : 1.f;
; #pragma unroll
;                 for (int bj = 0; bj < 2; ++bj) f(row, col0 + bj * HALF, acc[ai][bj][m][0] * rs, acc[ai][bj][m][1] * rs); }
; template <class PT, class Epi>
; __device__ __forceinline__ void gemm_phase_once(LAS unsigned char* lds, const PT& S, const Epi& E, bool epi_on) {
;     ...
;             PG8_BAR; PG8_WAIT_L(0); PG8_MMA(1, 0, At, B0); PG8_BAR; PG8_SCHED;
;             PG8_STAGE(PG8_SB(1, 1), b3 + hstepB, voffB);
;             PG8_WAIT_V(6); PG8_BAR; PG8_MMA(1, 1, At, B1); PG8_BAR;
	s_waitcnt lgkmcnt(0)
	s_setprio 1
	s_waitcnt lgkmcnt(0)
	v_mfma_f32_16x16x32_bf16 v[62:65], v[142:145], v[166:169], v[62:65]
	v_mfma_f32_16x16x32_bf16 v[58:61], v[156:159], v[166:169], v[58:61]
	v_mfma_f32_16x16x32_bf16 v[46:49], v[142:145], v[174:177], v[46:49]
	v_mfma_f32_16x16x32_bf16 v[42:45], v[156:159], v[174:177], v[42:45]
	v_mfma_f32_16x16x32_bf16 v[30:33], v[142:145], v[182:185], v[30:33]
	v_mfma_f32_16x16x32_bf16 v[26:29], v[156:159], v[182:185], v[26:29]
	v_mfma_f32_16x16x32_bf16 v[14:17], v[142:145], v[190:193], v[14:17]
	v_mfma_f32_16x16x32_bf16 v[10:13], v[156:159], v[190:193], v[10:13]
	v_mfma_f32_16x16x32_bf16 v[62:65], v[152:155], v[170:173], v[62:65]
	v_mfma_f32_16x16x32_bf16 v[58:61], v[160:163], v[170:173], v[58:61]
	v_mfma_f32_16x16x32_bf16 v[46:49], v[152:155], v[178:181], v[46:49]
	v_mfma_f32_16x16x32_bf16 v[42:45], v[160:163], v[178:181], v[42:45]
	v_mfma_f32_16x16x32_bf16 v[30:33], v[152:155], v[186:189], v[30:33]
	v_mfma_f32_16x16x32_bf16 v[26:29], v[160:163], v[186:189], v[26:29]
	v_mfma_f32_16x16x32_bf16 v[14:17], v[152:155], v[194:197], v[14:17]
	v_mfma_f32_16x16x32_bf16 v[10:13], v[160:163], v[194:197], v[10:13]
	s_setprio 0
	s_barrier
	s_add_u32 s22, s22, 0x80080
	s_addc_u32 s23, s23, 0
	s_add_i32 s24, s24, s26
	v_lshl_add_u64 v[142:143], s[22:23], 0, v[134:135]
	s_mov_b32 m0, s24
	s_nop 0
	global_load_lds_dwordx4 v[142:143], off
	v_lshl_add_u64 v[142:143], s[22:23], 0, v[130:131]
	s_add_i32 m0, s24, 0x2000
	s_nop 0
	global_load_lds_dwordx4 v[142:143], off
	s_waitcnt vmcnt(6)
	s_barrier
	s_setprio 1
	v_mfma_f32_16x16x32_bf16 v[54:57], v[198:201], v[166:169], v[54:57]
	v_mfma_f32_16x16x32_bf16 v[50:53], v[206:209], v[166:169], v[50:53]
	v_mfma_f32_16x16x32_bf16 v[38:41], v[198:201], v[174:177], v[38:41]
	v_mfma_f32_16x16x32_bf16 v[34:37], v[206:209], v[174:177], v[34:37]
	v_mfma_f32_16x16x32_bf16 v[22:25], v[198:201], v[182:185], v[22:25]
	v_mfma_f32_16x16x32_bf16 v[18:21], v[206:209], v[182:185], v[18:21]
	v_mfma_f32_16x16x32_bf16 v[6:9], v[198:201], v[190:193], v[6:9]
	v_mfma_f32_16x16x32_bf16 v[2:5], v[206:209], v[190:193], v[2:5]
	v_mfma_f32_16x16x32_bf16 v[54:57], v[202:205], v[170:173], v[54:57]
	v_mfma_f32_16x16x32_bf16 v[50:53], v[210:213], v[170:173], v[50:53]
	v_mfma_f32_16x16x32_bf16 v[38:41], v[202:205], v[178:181], v[38:41]
	v_mfma_f32_16x16x32_bf16 v[34:37], v[210:213], v[178:181], v[34:37]
	v_mfma_f32_16x16x32_bf16 v[22:25], v[202:205], v[186:189], v[22:25]
	v_mfma_f32_16x16x32_bf16 v[18:21], v[210:213], v[186:189], v[18:21]
	v_mfma_f32_16x16x32_bf16 v[6:9], v[202:205], v[194:197], v[6:9]
	v_mfma_f32_16x16x32_bf16 v[2:5], v[210:213], v[194:197], v[2:5]
	s_setprio 0
	s_add_i32 s45, s45, 2
	s_add_u32 s20, s20, 0x100
	s_addc_u32 s21, s21, 0
	s_add_u32 s43, s43, 0x100
	s_addc_u32 s44, s44, 0
	s_cmp_lt_u32 s45, 30
	s_barrier
	s_cbranch_scc1 .LBB0_328
	v_lshl_add_u32 v142, s18, 8, v1
	v_ashrrev_i32_e32 v143, 31, v142
	v_lshl_add_u64 v[144:145], v[142:143], 2, s[90:91]
	global_load_dword v154, v[144:145], off
	global_load_dword v143, v[144:145], off offset:64
	global_load_dword v151, v[144:145], off offset:128
	global_load_dword v158, v[144:145], off offset:192
	global_load_dword v159, v[144:145], off offset:512
	global_load_dword v160, v[144:145], off offset:576
	global_load_dword v161, v[144:145], off offset:640
	global_load_dword v162, v[144:145], off offset:704
	v_readlane_b32 s4, v254, 10
	v_lshl_or_b32 v152, s40, 8, v147
	v_readlane_b32 s5, v254, 11
	v_ashrrev_i32_e32 v153, 31, v152
	s_andn2_b64 vcc, exec, s[14:15]
	s_mov_b32 s40, s10
	s_mov_b32 s18, s6
	s_mov_b64 s[22:23], s[16:17]
	s_waitcnt vmcnt(0)
	v_pk_mul_f32 v[128:129], v[128:129], v[154:155] op_sel_hi:[1,0]
	v_pk_mul_f32 v[126:127], v[126:127], v[154:155] op_sel_hi:[1,0]
	v_pk_mul_f32 v[122:123], v[122:123], v[154:155] op_sel_hi:[1,0]
	v_pk_mul_f32 v[124:125], v[124:125], v[154:155] op_sel_hi:[1,0]
	v_cvt_pk_bf16_f32 v126, v126, v127
	v_cvt_pk_bf16_f32 v127, v128, v129
	v_cvt_pk_bf16_f32 v128, v122, v123
	v_mov_b64_e32 v[122:123], s[4:5]
	v_cvt_pk_bf16_f32 v129, v124, v125
	v_mad_i64_i32 v[156:157], s[20:21], v142, s39, v[122:123]
	v_lshlrev_b64 v[124:125], 1, v[152:153]
	v_lshl_add_u64 v[152:153], v[156:157], 0, v[124:125]
	global_store_dwordx4 v[152:153], v[126:129], off
	v_pk_mul_f32 v[118:119], v[118:119], v[154:155] op_sel_hi:[1,0]
	v_pk_mul_f32 v[120:121], v[120:121], v[154:155] op_sel_hi:[1,0]
	v_pk_mul_f32 v[126:127], v[116:117], v[154:155] op_sel_hi:[1,0]
	v_pk_mul_f32 v[116:117], v[114:115], v[154:155] op_sel_hi:[1,0]
	v_cvt_pk_bf16_f32 v114, v118, v119
	v_cvt_pk_bf16_f32 v115, v120, v121
	s_nop 0
	v_cvt_pk_bf16_f32 v116, v116, v117
	v_cvt_pk_bf16_f32 v117, v126, v127
	global_store_dwordx4 v[152:153], v[114:117], off offset:256
	s_nop 1
	v_or_b32_e32 v114, 16, v142
	v_ashrrev_i32_e32 v115, 31, v114
	v_lshl_add_u64 v[116:117], v[114:115], 2, s[90:91]
	s_nop 1
	v_mov_b32_e32 v116, v143
	v_pk_mul_f32 v[110:111], v[110:111], v[116:117] op_sel_hi:[1,0]
	v_pk_mul_f32 v[118:119], v[108:109], v[116:117] op_sel_hi:[1,0]
	v_pk_mul_f32 v[108:109], v[106:107], v[116:117] op_sel_hi:[1,0]
	v_cvt_pk_bf16_f32 v106, v110, v111
	v_mad_i64_i32 v[110:111], s[20:21], v114, s39, v[122:123]
	v_pk_mul_f32 v[112:113], v[112:113], v[116:117] op_sel_hi:[1,0]
	v_lshl_add_u64 v[110:111], v[110:111], 0, v[124:125]
	v_cvt_pk_bf16_f32 v107, v112, v113
	v_cvt_pk_bf16_f32 v108, v108, v109
	v_cvt_pk_bf16_f32 v109, v118, v119
	global_store_dwordx4 v[110:111], v[106:109], off
	v_pk_mul_f32 v[102:103], v[102:103], v[116:117] op_sel_hi:[1,0]
	v_pk_mul_f32 v[104:105], v[104:105], v[116:117] op_sel_hi:[1,0]
	v_pk_mul_f32 v[106:107], v[100:101], v[116:117] op_sel_hi:[1,0]
;     __device__ __forceinline__ void operator()(const f32x4 (&acc)[2][2][4][2], const Unit& u, int wr, int wc, int fr, int fq) const {
;         const int row0 = u.pm * BM + wr * 64 + fr, col0 = u.pn * BM + wc * 32 + 8 * fq;
; #pragma unroll
;         for (int ai = 0; ai < 2; ++ai)
; #pragma unroll
;             for (int m = 0; m < 4; ++m) { const int row = row0 + ai * HALF + m * 16; const float rs = rowscale ? rowscale[row] : 1.f;
; #pragma unroll
;                 for (int bj = 0; bj < 2; ++bj) f(row, col0 + bj * HALF, acc[ai][bj][m][0] * rs, acc[ai][bj][m][1] * rs); }
	v_pk_mul_f32 v[100:101], v[98:99], v[116:117] op_sel_hi:[1,0]
	v_cvt_pk_bf16_f32 v98, v102, v103
	v_cvt_pk_bf16_f32 v99, v104, v105
	s_nop 0
	v_cvt_pk_bf16_f32 v100, v100, v101
	v_cvt_pk_bf16_f32 v101, v106, v107
	global_store_dwordx4 v[110:111], v[98:101], off offset:256
	s_nop 1
	v_or_b32_e32 v98, 32, v142
	v_ashrrev_i32_e32 v99, 31, v98
	v_lshl_add_u64 v[100:101], v[98:99], 2, s[90:91]
	s_nop 1
	v_mov_b32_e32 v100, v151
	v_pk_mul_f32 v[94:95], v[94:95], v[100:101] op_sel_hi:[1,0]
	v_pk_mul_f32 v[102:103], v[92:93], v[100:101] op_sel_hi:[1,0]
	v_pk_mul_f32 v[92:93], v[90:91], v[100:101] op_sel_hi:[1,0]
	v_cvt_pk_bf16_f32 v90, v94, v95
	v_mad_i64_i32 v[94:95], s[20:21], v98, s39, v[122:123]
	v_pk_mul_f32 v[96:97], v[96:97], v[100:101] op_sel_hi:[1,0]
	v_lshl_add_u64 v[94:95], v[94:95], 0, v[124:125]
	v_cvt_pk_bf16_f32 v91, v96, v97
	v_cvt_pk_bf16_f32 v92, v92, v93
	v_cvt_pk_bf16_f32 v93, v102, v103
	global_store_dwordx4 v[94:95], v[90:93], off
	v_pk_mul_f32 v[86:87], v[86:87], v[100:101] op_sel_hi:[1,0]
	v_pk_mul_f32 v[88:89], v[88:89], v[100:101] op_sel_hi:[1,0]
	v_pk_mul_f32 v[90:91], v[84:85], v[100:101] op_sel_hi:[1,0]
	v_pk_mul_f32 v[84:85], v[82:83], v[100:101] op_sel_hi:[1,0]
	v_cvt_pk_bf16_f32 v82, v86, v87
	v_cvt_pk_bf16_f32 v83, v88, v89
	s_nop 0
	v_cvt_pk_bf16_f32 v84, v84, v85
	v_cvt_pk_bf16_f32 v85, v90, v91
	global_store_dwordx4 v[94:95], v[82:85], off offset:256
	s_nop 1
	v_or_b32_e32 v82, 48, v142
	v_ashrrev_i32_e32 v83, 31, v82
	v_lshl_add_u64 v[84:85], v[82:83], 2, s[90:91]
	s_nop 1
	v_mov_b32_e32 v84, v158
	v_pk_mul_f32 v[78:79], v[78:79], v[84:85] op_sel_hi:[1,0]
	v_pk_mul_f32 v[86:87], v[76:77], v[84:85] op_sel_hi:[1,0]
	v_pk_mul_f32 v[76:77], v[74:75], v[84:85] op_sel_hi:[1,0]
	v_cvt_pk_bf16_f32 v74, v78, v79
	v_mad_i64_i32 v[78:79], s[20:21], v82, s39, v[122:123]
	v_pk_mul_f32 v[80:81], v[80:81], v[84:85] op_sel_hi:[1,0]
	v_lshl_add_u64 v[78:79], v[78:79], 0, v[124:125]
	v_cvt_pk_bf16_f32 v75, v80, v81
	v_cvt_pk_bf16_f32 v76, v76, v77
	v_cvt_pk_bf16_f32 v77, v86, v87
	global_store_dwordx4 v[78:79], v[74:77], off
	v_pk_mul_f32 v[72:73], v[72:73], v[84:85] op_sel_hi:[1,0]
	v_pk_mul_f32 v[70:71], v[70:71], v[84:85] op_sel_hi:[1,0]
	v_pk_mul_f32 v[74:75], v[68:69], v[84:85] op_sel_hi:[1,0]
	v_pk_mul_f32 v[68:69], v[66:67], v[84:85] op_sel_hi:[1,0]
	v_cvt_pk_bf16_f32 v66, v70, v71
	v_cvt_pk_bf16_f32 v67, v72, v73
	s_nop 0
	v_cvt_pk_bf16_f32 v68, v68, v69
	v_cvt_pk_bf16_f32 v69, v74, v75
	global_store_dwordx4 v[78:79], v[66:69], off offset:256
	s_nop 1
	v_mov_b32_e32 v66, v159
	s_nop 0
	v_add_u32_e32 v67, 0x80, v142
	v_pk_mul_f32 v[62:63], v[62:63], v[66:67] op_sel_hi:[1,0]
	v_pk_mul_f32 v[68:69], v[60:61], v[66:67] op_sel_hi:[1,0]
	v_pk_mul_f32 v[60:61], v[58:59], v[66:67] op_sel_hi:[1,0]
	v_cvt_pk_bf16_f32 v58, v62, v63
	v_mad_i64_i32 v[62:63], s[20:21], v67, s39, v[122:123]
	v_pk_mul_f32 v[64:65], v[64:65], v[66:67] op_sel_hi:[1,0]
	v_lshl_add_u64 v[62:63], v[62:63], 0, v[124:125]
	v_cvt_pk_bf16_f32 v59, v64, v65
	v_cvt_pk_bf16_f32 v60, v60, v61
	v_cvt_pk_bf16_f32 v61, v68, v69
	global_store_dwordx4 v[62:63], v[58:61], off
	v_pk_mul_f32 v[56:57], v[56:57], v[66:67] op_sel_hi:[1,0]
	v_pk_mul_f32 v[54:55], v[54:55], v[66:67] op_sel_hi:[1,0]
	v_pk_mul_f32 v[58:59], v[52:53], v[66:67] op_sel_hi:[1,0]
	v_pk_mul_f32 v[52:53], v[50:51], v[66:67] op_sel_hi:[1,0]
	v_cvt_pk_bf16_f32 v50, v54, v55
	v_cvt_pk_bf16_f32 v51, v56, v57
	s_nop 0
	v_cvt_pk_bf16_f32 v52, v52, v53
	v_cvt_pk_bf16_f32 v53, v58, v59
	global_store_dwordx4 v[62:63], v[50:53], off offset:256
	s_nop 1
	v_mov_b32_e32 v50, v160
	s_nop 0
	v_add_u32_e32 v51, 0x90, v142
	v_pk_mul_f32 v[46:47], v[46:47], v[50:51] op_sel_hi:[1,0]
	v_pk_mul_f32 v[52:53], v[44:45], v[50:51] op_sel_hi:[1,0]
	v_pk_mul_f32 v[44:45], v[42:43], v[50:51] op_sel_hi:[1,0]
	v_cvt_pk_bf16_f32 v42, v46, v47
	v_mad_i64_i32 v[46:47], s[20:21], v51, s39, v[122:123]
	v_pk_mul_f32 v[48:49], v[48:49], v[50:51] op_sel_hi:[1,0]
	v_lshl_add_u64 v[46:47], v[46:47], 0, v[124:125]
	v_cvt_pk_bf16_f32 v43, v48, v49
	v_cvt_pk_bf16_f32 v44, v44, v45
	v_cvt_pk_bf16_f32 v45, v52, v53
	global_store_dwordx4 v[46:47], v[42:45], off
	v_pk_mul_f32 v[40:41], v[40:41], v[50:51] op_sel_hi:[1,0]
	v_pk_mul_f32 v[38:39], v[38:39], v[50:51] op_sel_hi:[1,0]
	v_pk_mul_f32 v[42:43], v[36:37], v[50:51] op_sel_hi:[1,0]
	v_pk_mul_f32 v[36:37], v[34:35], v[50:51] op_sel_hi:[1,0]
	v_cvt_pk_bf16_f32 v34, v38, v39
	v_cvt_pk_bf16_f32 v35, v40, v41
	s_nop 0
	v_cvt_pk_bf16_f32 v36, v36, v37
	v_cvt_pk_bf16_f32 v37, v42, v43
	global_store_dwordx4 v[46:47], v[34:37], off offset:256
	s_nop 1
	v_mov_b32_e32 v34, v161
	s_nop 0
	v_add_u32_e32 v35, 0xa0, v142
	v_pk_mul_f32 v[30:31], v[30:31], v[34:35] op_sel_hi:[1,0]
	v_pk_mul_f32 v[36:37], v[28:29], v[34:35] op_sel_hi:[1,0]
	v_pk_mul_f32 v[28:29], v[26:27], v[34:35] op_sel_hi:[1,0]
	v_cvt_pk_bf16_f32 v26, v30, v31
	v_mad_i64_i32 v[30:31], s[20:21], v35, s39, v[122:123]
	v_pk_mul_f32 v[32:33], v[32:33], v[34:35] op_sel_hi:[1,0]
	v_lshl_add_u64 v[30:31], v[30:31], 0, v[124:125]
	v_cvt_pk_bf16_f32 v27, v32, v33
	v_cvt_pk_bf16_f32 v28, v28, v29
	v_cvt_pk_bf16_f32 v29, v36, v37
	global_store_dwordx4 v[30:31], v[26:29], off
	v_pk_mul_f32 v[24:25], v[24:25], v[34:35] op_sel_hi:[1,0]
	v_pk_mul_f32 v[22:23], v[22:23], v[34:35] op_sel_hi:[1,0]
	v_pk_mul_f32 v[26:27], v[20:21], v[34:35] op_sel_hi:[1,0]
	v_pk_mul_f32 v[20:21], v[18:19], v[34:35] op_sel_hi:[1,0]
	v_cvt_pk_bf16_f32 v18, v22, v23
	v_cvt_pk_bf16_f32 v19, v24, v25
	s_nop 0
	v_cvt_pk_bf16_f32 v20, v20, v21
	v_cvt_pk_bf16_f32 v21, v26, v27
	global_store_dwordx4 v[30:31], v[18:21], off offset:256
	s_nop 1
	v_mov_b32_e32 v18, v162
	s_nop 0
	v_add_u32_e32 v19, 0xb0, v142
	v_pk_mul_f32 v[14:15], v[14:15], v[18:19] op_sel_hi:[1,0]
	v_pk_mul_f32 v[20:21], v[12:13], v[18:19] op_sel_hi:[1,0]
	v_pk_mul_f32 v[12:13], v[10:11], v[18:19] op_sel_hi:[1,0]
	v_cvt_pk_bf16_f32 v10, v14, v15
	v_mad_i64_i32 v[14:15], s[20:21], v19, s39, v[122:123]
	v_pk_mul_f32 v[16:17], v[16:17], v[18:19] op_sel_hi:[1,0]
	v_lshl_add_u64 v[14:15], v[14:15], 0, v[124:125]
	v_cvt_pk_bf16_f32 v11, v16, v17
	v_cvt_pk_bf16_f32 v12, v12, v13
	v_cvt_pk_bf16_f32 v13, v20, v21
	global_store_dwordx4 v[14:15], v[10:13], off
	s_mov_b64 s[20:21], s[12:13]
	v_pk_mul_f32 v[8:9], v[8:9], v[18:19] op_sel_hi:[1,0]
	v_pk_mul_f32 v[10:11], v[4:5], v[18:19] op_sel_hi:[1,0]
	v_pk_mul_f32 v[4:5], v[2:3], v[18:19] op_sel_hi:[1,0]
	v_pk_mul_f32 v[6:7], v[6:7], v[18:19] op_sel_hi:[1,0]
	s_nop 0
	v_cvt_pk_bf16_f32 v2, v6, v7
	v_cvt_pk_bf16_f32 v3, v8, v9
	v_cvt_pk_bf16_f32 v4, v4, v5
	v_cvt_pk_bf16_f32 v5, v10, v11
	global_store_dwordx4 v[14:15], v[2:5], off offset:256
	s_cbranch_vccnz .LBB0_324
	s_waitcnt vmcnt(0)
	s_cmpk_gt_u32 s1, 0xff
	s_cbranch_scc1 .LBB0_332
	s_barrier

; #define PG8_STAGE(bufoff, gbase, voff) do { _Pragma("unroll") for (int _i = 0; _i < 2; ++_i) \
;         __builtin_amdgcn_global_load_lds((const unsigned*)((const char*)(gbase) + (voff)[_i]), (LAS unsigned*)(lds + (bufoff) + ldsw + _i * 8192), 16, 0, 0); } while (0)
; #define PG8_LDA(dst, b, h) do { _Pragma("unroll") for (int m = 0; m < 4; ++m) _Pragma("unroll") for (int k = 0; k < 2; ++k) dst[m][k] = *(const LAS bf16x8*)(lds + PG8_SA(b, h) + aoff + m * 2048 + k * 1024); } while (0)
; #define PG8_LDB(dst, b, h) do { _Pragma("unroll") for (int n = 0; n < 2; ++n) _Pragma("unroll") for (int k = 0; k < 2; ++k) dst[n][k] = *(const LAS bf16x8*)(lds + PG8_SB(b, h) + boff + n * 2048 + k * 1024); } while (0)
; #define PG8_MMA(ai, bj, At, Bt) do { __builtin_amdgcn_s_setprio(1); _Pragma("unroll") for (int m = 0; m < 4; ++m) _Pragma("unroll") for (int n = 0; n < 2; ++n) _Pragma("unroll") for (int k = 0; k < 2; ++k) \
;         acc[ai][bj][m][n] = __builtin_amdgcn_mfma_f32_16x16x32_bf16(Bt[n][k], At[m][k], acc[ai][bj][m][n], 0, 0, 0); __builtin_amdgcn_s_setprio(0); } while (0)
; #define PG8_WAIT_L(n) asm volatile("s_waitcnt lgkmcnt(" #n ")" ::: "memory")
; #define PG8_BAR __builtin_amdgcn_s_barrier()
; #define PG8_SCHED __builtin_amdgcn_sched_barrier(0)
; template <class PT, class Epi>
; __device__ __forceinline__ void gemm_phase_once(LAS unsigned char* lds, const PT& S, const Epi& E, bool epi_on) {
;     ...
;             PG8_LDB(B0, 0, 0); PG8_SCHED; PG8_LDA(At, 0, 0); PG8_STAGE(PG8_SA(1, 1), a1 + hstepA, voffA);
;             PG8_WAIT_L(8); PG8_BAR; PG8_WAIT_L(0); PG8_MMA(0, 0, At, B0); PG8_BAR; PG8_SCHED;
;             PG8_LDB(B1, 0, 1); PG8_STAGE(PG8_SB(0, 0), b2, voffB);
;             PG8_BAR; PG8_WAIT_L(0); PG8_MMA(0, 1, At, B1); PG8_BAR;
;             PG8_LDA(At, 0, 1); PG8_STAGE(PG8_SA(0, 0), a2, voffA);
;             PG8_BAR; PG8_WAIT_L(0); PG8_MMA(1, 0, At, B0); PG8_BAR; PG8_SCHED;
.LBB0_757:
	ds_read_b128 v[146:149], v162
	ds_read_b128 v[168:171], v162 offset:1024
	ds_read_b128 v[172:175], v162 offset:2048
	ds_read_b128 v[176:179], v162 offset:3072
	s_add_u32 s20, s18, 0xfff80080
	s_addc_u32 s21, s19, -1
	s_cmp_eq_u32 s43, 28
	s_cselect_b32 s23, s11, s21
	s_cselect_b32 s22, s39, s20
	s_cselect_b32 s21, s9, s42
	s_cselect_b32 s20, s40, s41
	v_lshl_add_u64 v[212:213], s[18:19], 0, v[138:139]
	s_add_i32 m0, s27, 0xc000
	ds_read_b128 v[180:183], v163
	ds_read_b128 v[184:187], v163 offset:1024
	ds_read_b128 v[188:191], v163 offset:2048
	ds_read_b128 v[192:195], v163 offset:3072
	ds_read_b128 v[196:199], v163 offset:4096
	ds_read_b128 v[200:203], v163 offset:5120
	ds_read_b128 v[204:207], v163 offset:6144
	ds_read_b128 v[208:211], v163 offset:7168
	global_load_lds_dwordx4 v[212:213], off
	v_lshl_add_u64 v[212:213], s[18:19], 0, v[140:141]
	s_add_i32 m0, s27, 0xe000
	s_nop 0
	global_load_lds_dwordx4 v[212:213], off
	s_waitcnt lgkmcnt(8)
	s_barrier
	s_waitcnt lgkmcnt(0)
	s_setprio 1
	s_waitcnt lgkmcnt(0)
	v_mfma_f32_16x16x32_bf16 v[126:129], v[146:149], v[180:183], v[126:129]
	v_mfma_f32_16x16x32_bf16 v[122:125], v[172:175], v[180:183], v[122:125]
	v_mfma_f32_16x16x32_bf16 v[110:113], v[146:149], v[188:191], v[110:113]
	v_mfma_f32_16x16x32_bf16 v[106:109], v[172:175], v[188:191], v[106:109]
	v_mfma_f32_16x16x32_bf16 v[94:97], v[146:149], v[196:199], v[94:97]
	v_mfma_f32_16x16x32_bf16 v[90:93], v[172:175], v[196:199], v[90:93]
	v_mfma_f32_16x16x32_bf16 v[78:81], v[146:149], v[204:207], v[78:81]
	v_mfma_f32_16x16x32_bf16 v[74:77], v[172:175], v[204:207], v[74:77]
	v_mfma_f32_16x16x32_bf16 v[126:129], v[168:171], v[184:187], v[126:129]
	v_mfma_f32_16x16x32_bf16 v[122:125], v[176:179], v[184:187], v[122:125]
	v_mfma_f32_16x16x32_bf16 v[110:113], v[168:171], v[192:195], v[110:113]
	v_mfma_f32_16x16x32_bf16 v[106:109], v[176:179], v[192:195], v[106:109]
	v_mfma_f32_16x16x32_bf16 v[94:97], v[168:171], v[200:203], v[94:97]
	v_mfma_f32_16x16x32_bf16 v[90:93], v[176:179], v[200:203], v[90:93]
	v_mfma_f32_16x16x32_bf16 v[78:81], v[168:171], v[208:211], v[78:81]
	v_mfma_f32_16x16x32_bf16 v[74:77], v[176:179], v[208:211], v[74:77]
	s_setprio 0
	s_barrier
	s_add_i32 s44, s36, s26
	v_lshl_add_u64 v[228:229], s[20:21], 0, v[132:133]
	s_mov_b32 m0, s44
	ds_read_b128 v[212:215], v167
	ds_read_b128 v[216:219], v167 offset:1024
	ds_read_b128 v[220:223], v167 offset:2048
	ds_read_b128 v[224:227], v167 offset:3072
	global_load_lds_dwordx4 v[228:229], off
	v_lshl_add_u64 v[230:231], s[20:21], 0, v[136:137]
	s_add_i32 m0, s44, 0x2000
	s_nop 0
	global_load_lds_dwordx4 v[230:231], off
	s_barrier
	s_waitcnt lgkmcnt(0)
	s_setprio 1
	s_waitcnt lgkmcnt(0)
	v_mfma_f32_16x16x32_bf16 v[118:121], v[212:215], v[180:183], v[118:121]
	v_mfma_f32_16x16x32_bf16 v[114:117], v[220:223], v[180:183], v[114:117]
	v_mfma_f32_16x16x32_bf16 v[102:105], v[212:215], v[188:191], v[102:105]
	v_mfma_f32_16x16x32_bf16 v[98:101], v[220:223], v[188:191], v[98:101]
	v_mfma_f32_16x16x32_bf16 v[86:89], v[212:215], v[196:199], v[86:89]
	v_mfma_f32_16x16x32_bf16 v[82:85], v[220:223], v[196:199], v[82:85]
	v_mfma_f32_16x16x32_bf16 v[70:73], v[212:215], v[204:207], v[70:73]
	v_mfma_f32_16x16x32_bf16 v[66:69], v[220:223], v[204:207], v[66:69]
	v_mfma_f32_16x16x32_bf16 v[118:121], v[216:219], v[184:187], v[118:121]
	v_mfma_f32_16x16x32_bf16 v[114:117], v[224:227], v[184:187], v[114:117]
	v_mfma_f32_16x16x32_bf16 v[102:105], v[216:219], v[192:195], v[102:105]
	v_mfma_f32_16x16x32_bf16 v[98:101], v[224:227], v[192:195], v[98:101]
	v_mfma_f32_16x16x32_bf16 v[86:89], v[216:219], v[200:203], v[86:89]
	v_mfma_f32_16x16x32_bf16 v[82:85], v[224:227], v[200:203], v[82:85]
	v_mfma_f32_16x16x32_bf16 v[70:73], v[216:219], v[208:211], v[70:73]
	v_mfma_f32_16x16x32_bf16 v[66:69], v[224:227], v[208:211], v[66:69]
	s_setprio 0
	s_mov_b32 m0, s27
	v_lshl_add_u64 v[232:233], s[22:23], 0, v[130:131]
	s_barrier
	ds_read_b128 v[180:183], v163 offset:16384
	ds_read_b128 v[184:187], v163 offset:17408
	ds_read_b128 v[188:191], v163 offset:18432
	ds_read_b128 v[192:195], v163 offset:19456
	ds_read_b128 v[196:199], v163 offset:20480
	ds_read_b128 v[200:203], v163 offset:21504
	ds_read_b128 v[204:207], v163 offset:22528
	ds_read_b128 v[208:211], v163 offset:23552
	global_load_lds_dwordx4 v[232:233], off
	v_lshl_add_u64 v[234:235], s[22:23], 0, v[134:135]
	s_mov_b32 m0, s17
	s_nop 0
	global_load_lds_dwordx4 v[234:235], off
	s_barrier
	s_waitcnt lgkmcnt(0)
	s_setprio 1
	s_waitcnt lgkmcnt(0)
	v_mfma_f32_16x16x32_bf16 v[62:65], v[146:149], v[180:183], v[62:65]
	v_mfma_f32_16x16x32_bf16 v[58:61], v[172:175], v[180:183], v[58:61]
	v_mfma_f32_16x16x32_bf16 v[46:49], v[146:149], v[188:191], v[46:49]
	v_mfma_f32_16x16x32_bf16 v[42:45], v[172:175], v[188:191], v[42:45]
	v_mfma_f32_16x16x32_bf16 v[30:33], v[146:149], v[196:199], v[30:33]
	v_mfma_f32_16x16x32_bf16 v[26:29], v[172:175], v[196:199], v[26:29]
	v_mfma_f32_16x16x32_bf16 v[14:17], v[146:149], v[204:207], v[14:17]
	v_mfma_f32_16x16x32_bf16 v[10:13], v[172:175], v[204:207], v[10:13]
	v_mfma_f32_16x16x32_bf16 v[62:65], v[168:171], v[184:187], v[62:65]
	v_mfma_f32_16x16x32_bf16 v[58:61], v[176:179], v[184:187], v[58:61]
	v_mfma_f32_16x16x32_bf16 v[46:49], v[168:171], v[192:195], v[46:49]
	v_mfma_f32_16x16x32_bf16 v[42:45], v[176:179], v[192:195], v[42:45]
	v_mfma_f32_16x16x32_bf16 v[30:33], v[168:171], v[200:203], v[30:33]
	v_mfma_f32_16x16x32_bf16 v[26:29], v[176:179], v[200:203], v[26:29]
	v_mfma_f32_16x16x32_bf16 v[14:17], v[168:171], v[208:211], v[14:17]
	v_mfma_f32_16x16x32_bf16 v[10:13], v[176:179], v[208:211], v[10:13]
	s_setprio 0
	s_barrier
; #define PG8_STAGE(bufoff, gbase, voff) do { _Pragma("unroll") for (int _i = 0; _i < 2; ++_i) \
;         __builtin_amdgcn_global_load_lds((const unsigned*)((const char*)(gbase) + (voff)[_i]), (LAS unsigned*)(lds + (bufoff) + ldsw + _i * 8192), 16, 0, 0); } while (0)
; #define PG8_LDA(dst, b, h) do { _Pragma("unroll") for (int m = 0; m < 4; ++m) _Pragma("unroll") for (int k = 0; k < 2; ++k) dst[m][k] = *(const LAS bf16x8*)(lds + PG8_SA(b, h) + aoff + m * 2048 + k * 1024); } while (0)
; #define PG8_LDB(dst, b, h) do { _Pragma("unroll") for (int n = 0; n < 2; ++n) _Pragma("unroll") for (int k = 0; k < 2; ++k) dst[n][k] = *(const LAS bf16x8*)(lds + PG8_SB(b, h) + boff + n * 2048 + k * 1024); } while (0)
; #define PG8_MMA(ai, bj, At, Bt) do { __builtin_amdgcn_s_setprio(1); _Pragma("unroll") for (int m = 0; m < 4; ++m) _Pragma("unroll") for (int n = 0; n < 2; ++n) _Pragma("unroll") for (int k = 0; k < 2; ++k) \
;         acc[ai][bj][m][n] = __builtin_amdgcn_mfma_f32_16x16x32_bf16(Bt[n][k], At[m][k], acc[ai][bj][m][n], 0, 0, 0); __builtin_amdgcn_s_setprio(0); } while (0)
; #define PG8_WAIT_V(n) asm volatile("s_waitcnt vmcnt(" #n ")" ::: "memory")
; #define PG8_WAIT_L(n) asm volatile("s_waitcnt lgkmcnt(" #n ")" ::: "memory")
; #define PG8_BAR __builtin_amdgcn_s_barrier()
; #define PG8_SCHED __builtin_amdgcn_sched_barrier(0)
; template <class PT, class Epi>
; __device__ __forceinline__ void gemm_phase_once(LAS unsigned char* lds, const PT& S, const Epi& E, bool epi_on) {
;     ...
;             PG8_STAGE(PG8_SB(0, 1), b2 + hstepB, voffB);
;             PG8_WAIT_V(6); PG8_BAR; PG8_MMA(1, 1, At, B1); PG8_BAR;
;             PG8_LDB(B0, 1, 0); PG8_SCHED; PG8_LDA(At, 1, 0); PG8_STAGE(PG8_SA(0, 1), a2 + hstepA, voffA);
;             PG8_WAIT_L(8); PG8_BAR; PG8_WAIT_L(0); PG8_MMA(0, 0, At, B0); PG8_BAR; PG8_SCHED;
;             PG8_LDB(B1, 1, 1); PG8_STAGE(PG8_SB(1, 0), b3, voffB);
;             PG8_BAR; PG8_WAIT_L(0); PG8_MMA(0, 1, At, B1); PG8_BAR;
;             PG8_LDA(At, 1, 1); PG8_STAGE(PG8_SA(1, 0), a3, voffA);
;             PG8_BAR; PG8_WAIT_L(0); PG8_MMA(1, 0, At, B0); PG8_BAR; PG8_SCHED;
	s_add_u32 s44, s20, 0x80000
	s_addc_u32 s45, s21, 0
	s_add_i32 s46, s37, s26
	v_lshl_add_u64 v[146:147], s[44:45], 0, v[132:133]
	s_mov_b32 m0, s46
	s_nop 0
	global_load_lds_dwordx4 v[146:147], off
	v_lshl_add_u64 v[146:147], s[44:45], 0, v[136:137]
	s_add_i32 m0, s46, 0x2000
	s_nop 0
	global_load_lds_dwordx4 v[146:147], off
	s_waitcnt vmcnt(6)
	s_barrier
	s_setprio 1
	v_mfma_f32_16x16x32_bf16 v[54:57], v[212:215], v[180:183], v[54:57]
	v_mfma_f32_16x16x32_bf16 v[50:53], v[220:223], v[180:183], v[50:53]
	v_mfma_f32_16x16x32_bf16 v[38:41], v[212:215], v[188:191], v[38:41]
	v_mfma_f32_16x16x32_bf16 v[34:37], v[220:223], v[188:191], v[34:37]
	v_mfma_f32_16x16x32_bf16 v[22:25], v[212:215], v[196:199], v[22:25]
	v_mfma_f32_16x16x32_bf16 v[18:21], v[220:223], v[196:199], v[18:21]
	v_mfma_f32_16x16x32_bf16 v[6:9], v[212:215], v[204:207], v[6:9]
	v_mfma_f32_16x16x32_bf16 v[2:5], v[220:223], v[204:207], v[2:5]
	v_mfma_f32_16x16x32_bf16 v[54:57], v[216:219], v[184:187], v[54:57]
	v_mfma_f32_16x16x32_bf16 v[50:53], v[224:227], v[184:187], v[50:53]
	v_mfma_f32_16x16x32_bf16 v[38:41], v[216:219], v[192:195], v[38:41]
	v_mfma_f32_16x16x32_bf16 v[34:37], v[224:227], v[192:195], v[34:37]
	v_mfma_f32_16x16x32_bf16 v[22:25], v[216:219], v[200:203], v[22:25]
	v_mfma_f32_16x16x32_bf16 v[18:21], v[224:227], v[200:203], v[18:21]
	v_mfma_f32_16x16x32_bf16 v[6:9], v[216:219], v[208:211], v[6:9]
	v_mfma_f32_16x16x32_bf16 v[2:5], v[224:227], v[208:211], v[2:5]
	s_setprio 0
	s_add_i32 s44, 0, 0x18000
	v_add_u32_e32 v165, s44, v160
	s_barrier
	ds_read_b128 v[146:149], v165
	ds_read_b128 v[168:171], v165 offset:1024
	ds_read_b128 v[172:175], v165 offset:2048
	ds_read_b128 v[176:179], v165 offset:3072
	s_add_u32 s22, s22, 0x80000
	s_addc_u32 s23, s23, 0
	s_mov_b32 m0, s28
	v_lshl_add_u64 v[212:213], s[22:23], 0, v[130:131]
	ds_read_b128 v[180:183], v163 offset:32768
	ds_read_b128 v[184:187], v163 offset:33792
	ds_read_b128 v[188:191], v163 offset:34816
	ds_read_b128 v[192:195], v163 offset:35840
	ds_read_b128 v[196:199], v163 offset:36864
	ds_read_b128 v[200:203], v163 offset:37888
	ds_read_b128 v[204:207], v163 offset:38912
	ds_read_b128 v[208:211], v163 offset:39936
	global_load_lds_dwordx4 v[212:213], off
	v_lshl_add_u64 v[212:213], s[22:23], 0, v[134:135]
	s_mov_b32 m0, s29
	s_nop 0
	global_load_lds_dwordx4 v[212:213], off
	s_waitcnt lgkmcnt(8)
	s_barrier
	s_waitcnt lgkmcnt(0)
	s_setprio 1
	s_waitcnt lgkmcnt(0)
	v_mfma_f32_16x16x32_bf16 v[126:129], v[146:149], v[180:183], v[126:129]
	v_mfma_f32_16x16x32_bf16 v[122:125], v[172:175], v[180:183], v[122:125]
	v_mfma_f32_16x16x32_bf16 v[110:113], v[146:149], v[188:191], v[110:113]
	v_mfma_f32_16x16x32_bf16 v[106:109], v[172:175], v[188:191], v[106:109]
	v_mfma_f32_16x16x32_bf16 v[94:97], v[146:149], v[196:199], v[94:97]
	v_mfma_f32_16x16x32_bf16 v[90:93], v[172:175], v[196:199], v[90:93]
	v_mfma_f32_16x16x32_bf16 v[78:81], v[146:149], v[204:207], v[78:81]
	v_mfma_f32_16x16x32_bf16 v[74:77], v[172:175], v[204:207], v[74:77]
	v_mfma_f32_16x16x32_bf16 v[126:129], v[168:171], v[184:187], v[126:129]
	v_mfma_f32_16x16x32_bf16 v[122:125], v[176:179], v[184:187], v[122:125]
	v_mfma_f32_16x16x32_bf16 v[110:113], v[168:171], v[192:195], v[110:113]
	v_mfma_f32_16x16x32_bf16 v[106:109], v[176:179], v[192:195], v[106:109]
	v_mfma_f32_16x16x32_bf16 v[94:97], v[168:171], v[200:203], v[94:97]
	v_mfma_f32_16x16x32_bf16 v[90:93], v[176:179], v[200:203], v[90:93]
	v_mfma_f32_16x16x32_bf16 v[78:81], v[168:171], v[208:211], v[78:81]
	v_mfma_f32_16x16x32_bf16 v[74:77], v[176:179], v[208:211], v[74:77]
	s_setprio 0
	s_barrier
	s_add_i32 s22, 0, 0x1c000
	s_add_i32 s23, s44, s26
	v_add_u32_e32 v165, s22, v160
	v_lshl_add_u64 v[228:229], v[228:229], 0, s[6:7]
	s_mov_b32 m0, s23
	ds_read_b128 v[212:215], v165
	ds_read_b128 v[216:219], v165 offset:1024
	ds_read_b128 v[220:223], v165 offset:2048
	ds_read_b128 v[224:227], v165 offset:3072
	global_load_lds_dwordx4 v[228:229], off
	v_lshl_add_u64 v[228:229], v[230:231], 0, s[6:7]
	s_add_i32 m0, s23, 0x2000
	s_nop 0
	global_load_lds_dwordx4 v[228:229], off
	s_barrier
	s_waitcnt lgkmcnt(0)
	s_setprio 1
	s_waitcnt lgkmcnt(0)
	v_mfma_f32_16x16x32_bf16 v[118:121], v[212:215], v[180:183], v[118:121]
	v_mfma_f32_16x16x32_bf16 v[114:117], v[220:223], v[180:183], v[114:117]
	v_mfma_f32_16x16x32_bf16 v[102:105], v[212:215], v[188:191], v[102:105]
	v_mfma_f32_16x16x32_bf16 v[98:101], v[220:223], v[188:191], v[98:101]
	v_mfma_f32_16x16x32_bf16 v[86:89], v[212:215], v[196:199], v[86:89]
	v_mfma_f32_16x16x32_bf16 v[82:85], v[220:223], v[196:199], v[82:85]
	v_mfma_f32_16x16x32_bf16 v[70:73], v[212:215], v[204:207], v[70:73]
	v_mfma_f32_16x16x32_bf16 v[66:69], v[220:223], v[204:207], v[66:69]
	v_mfma_f32_16x16x32_bf16 v[118:121], v[216:219], v[184:187], v[118:121]
	v_mfma_f32_16x16x32_bf16 v[114:117], v[224:227], v[184:187], v[114:117]
	v_mfma_f32_16x16x32_bf16 v[102:105], v[216:219], v[192:195], v[102:105]
	v_mfma_f32_16x16x32_bf16 v[98:101], v[224:227], v[192:195], v[98:101]
	v_mfma_f32_16x16x32_bf16 v[86:89], v[216:219], v[200:203], v[86:89]
	v_mfma_f32_16x16x32_bf16 v[82:85], v[224:227], v[200:203], v[82:85]
	v_mfma_f32_16x16x32_bf16 v[70:73], v[216:219], v[208:211], v[70:73]
	v_mfma_f32_16x16x32_bf16 v[66:69], v[224:227], v[208:211], v[66:69]
	s_setprio 0
	s_mov_b32 m0, s31
	v_lshl_add_u64 v[228:229], v[232:233], 0, s[6:7]
	s_barrier
	ds_read_b128 v[180:183], v163 offset:49152
	ds_read_b128 v[184:187], v163 offset:50176
	ds_read_b128 v[188:191], v163 offset:51200
	ds_read_b128 v[192:195], v163 offset:52224
	ds_read_b128 v[196:199], v163 offset:53248
	ds_read_b128 v[200:203], v163 offset:54272
	ds_read_b128 v[204:207], v163 offset:55296
	ds_read_b128 v[208:211], v163 offset:56320
	global_load_lds_dwordx4 v[228:229], off
	v_lshl_add_u64 v[228:229], v[234:235], 0, s[6:7]
	s_mov_b32 m0, s34
	s_nop 0
	global_load_lds_dwordx4 v[228:229], off
	s_barrier
; #define PG8_STAGE(bufoff, gbase, voff) do { _Pragma("unroll") for (int _i = 0; _i < 2; ++_i) \
;         __builtin_amdgcn_global_load_lds((const unsigned*)((const char*)(gbase) + (voff)[_i]), (LAS unsigned*)(lds + (bufoff) + ldsw + _i * 8192), 16, 0, 0); } while (0)
; #define PG8_MMA(ai, bj, At, Bt) do { __builtin_amdgcn_s_setprio(1); _Pragma("unroll") for (int m = 0; m < 4; ++m) _Pragma("unroll") for (int n = 0; n < 2; ++n) _Pragma("unroll") for (int k = 0; k < 2; ++k) \
;         acc[ai][bj][m][n] = __builtin_amdgcn_mfma_f32_16x16x32_bf16(Bt[n][k], At[m][k], acc[ai][bj][m][n], 0, 0, 0); __builtin_amdgcn_s_setprio(0); } while (0)
; #define PG8_WAIT_V(n) asm volatile("s_waitcnt vmcnt(" #n ")" ::: "memory")
; #define PG8_WAIT_L(n) asm volatile("s_waitcnt lgkmcnt(" #n ")" ::: "memory")
; #define PG8_BAR __builtin_amdgcn_s_barrier()
; #define PG8_SCHED __builtin_amdgcn_sched_barrier(0)
;     __device__ __forceinline__ void operator()(const f32x4 (&acc)[2][2][4][2], const Unit& u, int wr, int wc, int fr, int fq) const {
;         const int row0 = u.pm * BM + wr * 64 + fr, col0 = u.pn * BM + wc * 32 + 8 * fq;
; #pragma unroll
;         for (int ai = 0; ai < 2; ++ai)
; #pragma unroll
;             for (int m = 0; m < 4; ++m) { const int row = row0 + ai * HALF + m * 16; const float rs = rowscale ? rowscale[row] : 1.f;
; #pragma unroll
;                 for (int bj = 0; bj < 2; ++bj) f(row, col0 + bj * HALF, acc[ai][bj][m][0] * rs, acc[ai][bj][m][1] * rs); }
; template <class PT, class Epi>
; __device__ __forceinline__ void gemm_phase_once(LAS unsigned char* lds, const PT& S, const Epi& E, bool epi_on) {
;     ...
;             PG8_BAR; PG8_WAIT_L(0); PG8_MMA(1, 0, At, B0); PG8_BAR; PG8_SCHED;
;             PG8_STAGE(PG8_SB(1, 1), b3 + hstepB, voffB);
;             PG8_WAIT_V(6); PG8_BAR; PG8_MMA(1, 1, At, B1); PG8_BAR;
	s_waitcnt lgkmcnt(0)
	s_setprio 1
	s_waitcnt lgkmcnt(0)
	v_mfma_f32_16x16x32_bf16 v[62:65], v[146:149], v[180:183], v[62:65]
	v_mfma_f32_16x16x32_bf16 v[58:61], v[172:175], v[180:183], v[58:61]
	v_mfma_f32_16x16x32_bf16 v[46:49], v[146:149], v[188:191], v[46:49]
	v_mfma_f32_16x16x32_bf16 v[42:45], v[172:175], v[188:191], v[42:45]
	v_mfma_f32_16x16x32_bf16 v[30:33], v[146:149], v[196:199], v[30:33]
	v_mfma_f32_16x16x32_bf16 v[26:29], v[172:175], v[196:199], v[26:29]
	v_mfma_f32_16x16x32_bf16 v[14:17], v[146:149], v[204:207], v[14:17]
	v_mfma_f32_16x16x32_bf16 v[10:13], v[172:175], v[204:207], v[10:13]
	v_mfma_f32_16x16x32_bf16 v[62:65], v[168:171], v[184:187], v[62:65]
	v_mfma_f32_16x16x32_bf16 v[58:61], v[176:179], v[184:187], v[58:61]
	v_mfma_f32_16x16x32_bf16 v[46:49], v[168:171], v[192:195], v[46:49]
	v_mfma_f32_16x16x32_bf16 v[42:45], v[176:179], v[192:195], v[42:45]
	v_mfma_f32_16x16x32_bf16 v[30:33], v[168:171], v[200:203], v[30:33]
	v_mfma_f32_16x16x32_bf16 v[26:29], v[176:179], v[200:203], v[26:29]
	v_mfma_f32_16x16x32_bf16 v[14:17], v[168:171], v[208:211], v[14:17]
	v_mfma_f32_16x16x32_bf16 v[10:13], v[176:179], v[208:211], v[10:13]
	s_setprio 0
	s_barrier
	s_add_u32 s20, s20, 0x80080
	s_addc_u32 s21, s21, 0
	s_add_i32 s22, s22, s26
	v_lshl_add_u64 v[146:147], s[20:21], 0, v[132:133]
	s_mov_b32 m0, s22
	s_nop 0
	global_load_lds_dwordx4 v[146:147], off
	v_lshl_add_u64 v[146:147], s[20:21], 0, v[136:137]
	s_add_i32 m0, s22, 0x2000
	s_nop 0
	global_load_lds_dwordx4 v[146:147], off
	s_waitcnt vmcnt(6)
	s_barrier
	s_setprio 1
	v_mfma_f32_16x16x32_bf16 v[54:57], v[212:215], v[180:183], v[54:57]
	v_mfma_f32_16x16x32_bf16 v[50:53], v[220:223], v[180:183], v[50:53]
	v_mfma_f32_16x16x32_bf16 v[38:41], v[212:215], v[188:191], v[38:41]
	v_mfma_f32_16x16x32_bf16 v[34:37], v[220:223], v[188:191], v[34:37]
	v_mfma_f32_16x16x32_bf16 v[22:25], v[212:215], v[196:199], v[22:25]
	v_mfma_f32_16x16x32_bf16 v[18:21], v[220:223], v[196:199], v[18:21]
	v_mfma_f32_16x16x32_bf16 v[6:9], v[212:215], v[204:207], v[6:9]
	v_mfma_f32_16x16x32_bf16 v[2:5], v[220:223], v[204:207], v[2:5]
	v_mfma_f32_16x16x32_bf16 v[54:57], v[216:219], v[184:187], v[54:57]
	v_mfma_f32_16x16x32_bf16 v[50:53], v[224:227], v[184:187], v[50:53]
	v_mfma_f32_16x16x32_bf16 v[38:41], v[216:219], v[192:195], v[38:41]
	v_mfma_f32_16x16x32_bf16 v[34:37], v[224:227], v[192:195], v[34:37]
	v_mfma_f32_16x16x32_bf16 v[22:25], v[216:219], v[200:203], v[22:25]
	v_mfma_f32_16x16x32_bf16 v[18:21], v[224:227], v[200:203], v[18:21]
	v_mfma_f32_16x16x32_bf16 v[6:9], v[216:219], v[208:211], v[6:9]
	v_mfma_f32_16x16x32_bf16 v[2:5], v[224:227], v[208:211], v[2:5]
	s_setprio 0
	s_add_i32 s43, s43, 2
	s_add_u32 s18, s18, 0x100
	s_addc_u32 s19, s19, 0
	s_add_u32 s41, s41, 0x100
	s_addc_u32 s42, s42, 0
	s_cmp_lt_u32 s43, 30
	s_barrier
	s_cbranch_scc1 .LBB0_757
	v_lshl_add_u32 v148, s16, 8, v159
	v_ashrrev_i32_e32 v149, 31, v148
	v_lshl_add_u64 v[146:147], v[148:149], 2, s[90:91]
	global_load_dword v166, v[146:147], off
	global_load_dword v165, v[146:147], off offset:64
	global_load_dword v170, v[146:147], off offset:128
	global_load_dword v171, v[146:147], off offset:192
	global_load_dword v172, v[146:147], off offset:512
	global_load_dword v173, v[146:147], off offset:576
	global_load_dword v174, v[146:147], off offset:640
	global_load_dword v175, v[146:147], off offset:704
	v_lshl_or_b32 v168, s38, 8, v161
	v_readlane_b32 s18, v254, 44
	v_readlane_b32 s19, v254, 45
	v_ashrrev_i32_e32 v169, 31, v168
	s_mov_b32 s9, 0x20000
	s_mov_b32 s38, s8
	s_mov_b32 s16, s10
	s_mov_b64 s[20:21], s[14:15]
	s_waitcnt vmcnt(0)
	v_pk_mul_f32 v[128:129], v[128:129], v[166:167] op_sel_hi:[1,0]
	v_pk_mul_f32 v[126:127], v[126:127], v[166:167] op_sel_hi:[1,0]
	v_pk_mul_f32 v[122:123], v[122:123], v[166:167] op_sel_hi:[1,0]
	v_pk_mul_f32 v[124:125], v[124:125], v[166:167] op_sel_hi:[1,0]
	v_cvt_pk_bf16_f32 v126, v126, v127
	v_cvt_pk_bf16_f32 v127, v128, v129
	v_cvt_pk_bf16_f32 v128, v122, v123
	v_lshlrev_b64 v[122:123], 10, v[148:149]
	v_cvt_pk_bf16_f32 v129, v124, v125
	v_lshl_add_u64 v[122:123], s[18:19], 0, v[122:123]
	v_lshlrev_b64 v[124:125], 1, v[168:169]
	v_lshl_add_u64 v[122:123], v[122:123], 0, v[124:125]
	global_store_dwordx4 v[122:123], v[126:129], off
	v_pk_mul_f32 v[118:119], v[118:119], v[166:167] op_sel_hi:[1,0]
	v_pk_mul_f32 v[120:121], v[120:121], v[166:167] op_sel_hi:[1,0]
	v_pk_mul_f32 v[126:127], v[116:117], v[166:167] op_sel_hi:[1,0]
	v_pk_mul_f32 v[116:117], v[114:115], v[166:167] op_sel_hi:[1,0]
	v_cvt_pk_bf16_f32 v114, v118, v119
	v_cvt_pk_bf16_f32 v115, v120, v121
	s_nop 0
	v_cvt_pk_bf16_f32 v116, v116, v117
	v_cvt_pk_bf16_f32 v117, v126, v127
	global_store_dwordx4 v[122:123], v[114:117], off offset:256
	s_nop 1
	v_or_b32_e32 v114, 16, v148
	v_ashrrev_i32_e32 v115, 31, v114
	v_lshl_add_u64 v[116:117], v[114:115], 2, s[90:91]
	s_nop 1
	v_mov_b32_e32 v116, v165
	v_pk_mul_f32 v[110:111], v[110:111], v[116:117] op_sel_hi:[1,0]
	v_pk_mul_f32 v[118:119], v[108:109], v[116:117] op_sel_hi:[1,0]
	v_pk_mul_f32 v[108:109], v[106:107], v[116:117] op_sel_hi:[1,0]
	v_cvt_pk_bf16_f32 v106, v110, v111
	v_lshlrev_b64 v[110:111], 10, v[114:115]
	v_lshl_add_u64 v[110:111], s[18:19], 0, v[110:111]
	v_pk_mul_f32 v[112:113], v[112:113], v[116:117] op_sel_hi:[1,0]
	v_lshl_add_u64 v[110:111], v[110:111], 0, v[124:125]
	v_cvt_pk_bf16_f32 v107, v112, v113
	v_cvt_pk_bf16_f32 v108, v108, v109
	v_cvt_pk_bf16_f32 v109, v118, v119
	global_store_dwordx4 v[110:111], v[106:109], off
	v_pk_mul_f32 v[102:103], v[102:103], v[116:117] op_sel_hi:[1,0]
	v_pk_mul_f32 v[104:105], v[104:105], v[116:117] op_sel_hi:[1,0]
;     __device__ __forceinline__ void operator()(const f32x4 (&acc)[2][2][4][2], const Unit& u, int wr, int wc, int fr, int fq) const {
;         const int row0 = u.pm * BM + wr * 64 + fr, col0 = u.pn * BM + wc * 32 + 8 * fq;
; #pragma unroll
;         for (int ai = 0; ai < 2; ++ai)
; #pragma unroll
;             for (int m = 0; m < 4; ++m) { const int row = row0 + ai * HALF + m * 16; const float rs = rowscale ? rowscale[row] : 1.f;
; #pragma unroll
;                 for (int bj = 0; bj < 2; ++bj) f(row, col0 + bj * HALF, acc[ai][bj][m][0] * rs, acc[ai][bj][m][1] * rs); }
	v_pk_mul_f32 v[106:107], v[100:101], v[116:117] op_sel_hi:[1,0]
	v_pk_mul_f32 v[100:101], v[98:99], v[116:117] op_sel_hi:[1,0]
	v_cvt_pk_bf16_f32 v98, v102, v103
	v_cvt_pk_bf16_f32 v99, v104, v105
	s_nop 0
	v_cvt_pk_bf16_f32 v100, v100, v101
	v_cvt_pk_bf16_f32 v101, v106, v107
	global_store_dwordx4 v[110:111], v[98:101], off offset:256
	s_nop 1
	v_or_b32_e32 v98, 32, v148
	v_ashrrev_i32_e32 v99, 31, v98
	v_lshl_add_u64 v[100:101], v[98:99], 2, s[90:91]
	s_nop 1
	v_mov_b32_e32 v100, v170
	v_pk_mul_f32 v[94:95], v[94:95], v[100:101] op_sel_hi:[1,0]
	v_pk_mul_f32 v[102:103], v[92:93], v[100:101] op_sel_hi:[1,0]
	v_pk_mul_f32 v[92:93], v[90:91], v[100:101] op_sel_hi:[1,0]
	v_cvt_pk_bf16_f32 v90, v94, v95
	v_lshlrev_b64 v[94:95], 10, v[98:99]
	v_lshl_add_u64 v[94:95], s[18:19], 0, v[94:95]
	v_pk_mul_f32 v[96:97], v[96:97], v[100:101] op_sel_hi:[1,0]
	v_lshl_add_u64 v[94:95], v[94:95], 0, v[124:125]
	v_cvt_pk_bf16_f32 v91, v96, v97
	v_cvt_pk_bf16_f32 v92, v92, v93
	v_cvt_pk_bf16_f32 v93, v102, v103
	global_store_dwordx4 v[94:95], v[90:93], off
	v_pk_mul_f32 v[86:87], v[86:87], v[100:101] op_sel_hi:[1,0]
	v_pk_mul_f32 v[88:89], v[88:89], v[100:101] op_sel_hi:[1,0]
	v_pk_mul_f32 v[90:91], v[84:85], v[100:101] op_sel_hi:[1,0]
	v_pk_mul_f32 v[84:85], v[82:83], v[100:101] op_sel_hi:[1,0]
	v_cvt_pk_bf16_f32 v82, v86, v87
	v_cvt_pk_bf16_f32 v83, v88, v89
	s_nop 0
	v_cvt_pk_bf16_f32 v84, v84, v85
	v_cvt_pk_bf16_f32 v85, v90, v91
	global_store_dwordx4 v[94:95], v[82:85], off offset:256
	s_nop 1
	v_or_b32_e32 v82, 48, v148
	v_ashrrev_i32_e32 v83, 31, v82
	v_lshl_add_u64 v[84:85], v[82:83], 2, s[90:91]
	s_nop 1
	v_mov_b32_e32 v84, v171
	v_pk_mul_f32 v[78:79], v[78:79], v[84:85] op_sel_hi:[1,0]
	v_pk_mul_f32 v[86:87], v[76:77], v[84:85] op_sel_hi:[1,0]
	v_pk_mul_f32 v[76:77], v[74:75], v[84:85] op_sel_hi:[1,0]
	v_cvt_pk_bf16_f32 v74, v78, v79
	v_lshlrev_b64 v[78:79], 10, v[82:83]
	v_lshl_add_u64 v[78:79], s[18:19], 0, v[78:79]
	v_pk_mul_f32 v[80:81], v[80:81], v[84:85] op_sel_hi:[1,0]
	v_lshl_add_u64 v[78:79], v[78:79], 0, v[124:125]
	v_cvt_pk_bf16_f32 v75, v80, v81
	v_cvt_pk_bf16_f32 v76, v76, v77
	v_cvt_pk_bf16_f32 v77, v86, v87
	global_store_dwordx4 v[78:79], v[74:77], off
	v_pk_mul_f32 v[72:73], v[72:73], v[84:85] op_sel_hi:[1,0]
	v_pk_mul_f32 v[70:71], v[70:71], v[84:85] op_sel_hi:[1,0]
	v_pk_mul_f32 v[74:75], v[68:69], v[84:85] op_sel_hi:[1,0]
	v_pk_mul_f32 v[68:69], v[66:67], v[84:85] op_sel_hi:[1,0]
	v_cvt_pk_bf16_f32 v66, v70, v71
	v_cvt_pk_bf16_f32 v67, v72, v73
	s_mov_b64 s[18:19], 0x20000
	v_cvt_pk_bf16_f32 v68, v68, v69
	v_cvt_pk_bf16_f32 v69, v74, v75
	global_store_dwordx4 v[78:79], v[66:69], off offset:256
	s_nop 1
	v_mov_b32_e32 v66, v172
	v_pk_mul_f32 v[64:65], v[64:65], v[66:67] op_sel_hi:[1,0]
	v_pk_mul_f32 v[62:63], v[62:63], v[66:67] op_sel_hi:[1,0]
	v_pk_mul_f32 v[68:69], v[60:61], v[66:67] op_sel_hi:[1,0]
	v_pk_mul_f32 v[60:61], v[58:59], v[66:67] op_sel_hi:[1,0]
	v_cvt_pk_bf16_f32 v58, v62, v63
	v_cvt_pk_bf16_f32 v59, v64, v65
	v_add_co_u32_e32 v64, vcc, s9, v122
	v_cvt_pk_bf16_f32 v60, v60, v61
	v_cvt_pk_bf16_f32 v61, v68, v69
	v_lshl_add_u64 v[62:63], v[122:123], 0, s[18:19]
	s_nop 0
	v_addc_co_u32_e32 v65, vcc, 0, v123, vcc
	global_store_dwordx4 v[64:65], v[58:61], off
	v_pk_mul_f32 v[56:57], v[56:57], v[66:67] op_sel_hi:[1,0]
	v_pk_mul_f32 v[54:55], v[54:55], v[66:67] op_sel_hi:[1,0]
	v_pk_mul_f32 v[58:59], v[52:53], v[66:67] op_sel_hi:[1,0]
	v_pk_mul_f32 v[52:53], v[50:51], v[66:67] op_sel_hi:[1,0]
	v_cvt_pk_bf16_f32 v50, v54, v55
	v_cvt_pk_bf16_f32 v51, v56, v57
	s_mov_b32 s9, 0x24000
	v_cvt_pk_bf16_f32 v52, v52, v53
	v_cvt_pk_bf16_f32 v53, v58, v59
	global_store_dwordx4 v[62:63], v[50:53], off offset:256
	s_nop 1
	v_mov_b32_e32 v50, v173
	s_mov_b64 s[18:19], 0x24000
	v_pk_mul_f32 v[48:49], v[48:49], v[50:51] op_sel_hi:[1,0]
	v_pk_mul_f32 v[46:47], v[46:47], v[50:51] op_sel_hi:[1,0]
	v_pk_mul_f32 v[52:53], v[44:45], v[50:51] op_sel_hi:[1,0]
	v_pk_mul_f32 v[44:45], v[42:43], v[50:51] op_sel_hi:[1,0]
	v_cvt_pk_bf16_f32 v42, v46, v47
	v_cvt_pk_bf16_f32 v43, v48, v49
	v_add_co_u32_e32 v48, vcc, s9, v122
	v_cvt_pk_bf16_f32 v44, v44, v45
	v_cvt_pk_bf16_f32 v45, v52, v53
	v_lshl_add_u64 v[46:47], v[122:123], 0, s[18:19]
	s_nop 0
	v_addc_co_u32_e32 v49, vcc, 0, v123, vcc
	global_store_dwordx4 v[48:49], v[42:45], off
	v_pk_mul_f32 v[40:41], v[40:41], v[50:51] op_sel_hi:[1,0]
	v_pk_mul_f32 v[38:39], v[38:39], v[50:51] op_sel_hi:[1,0]
	v_pk_mul_f32 v[42:43], v[36:37], v[50:51] op_sel_hi:[1,0]
	v_pk_mul_f32 v[36:37], v[34:35], v[50:51] op_sel_hi:[1,0]
	v_cvt_pk_bf16_f32 v34, v38, v39
	v_cvt_pk_bf16_f32 v35, v40, v41
	s_mov_b32 s9, 0x28000
	v_cvt_pk_bf16_f32 v36, v36, v37
	v_cvt_pk_bf16_f32 v37, v42, v43
	global_store_dwordx4 v[46:47], v[34:37], off offset:256
	s_nop 1
	v_mov_b32_e32 v34, v174
	s_mov_b64 s[18:19], 0x28000
	v_pk_mul_f32 v[32:33], v[32:33], v[34:35] op_sel_hi:[1,0]
	v_pk_mul_f32 v[30:31], v[30:31], v[34:35] op_sel_hi:[1,0]
	v_pk_mul_f32 v[36:37], v[28:29], v[34:35] op_sel_hi:[1,0]
	v_pk_mul_f32 v[28:29], v[26:27], v[34:35] op_sel_hi:[1,0]
	v_cvt_pk_bf16_f32 v26, v30, v31
	v_cvt_pk_bf16_f32 v27, v32, v33
	v_add_co_u32_e32 v32, vcc, s9, v122
	v_cvt_pk_bf16_f32 v28, v28, v29
	v_cvt_pk_bf16_f32 v29, v36, v37
	v_lshl_add_u64 v[30:31], v[122:123], 0, s[18:19]
	s_nop 0
	v_addc_co_u32_e32 v33, vcc, 0, v123, vcc
	global_store_dwordx4 v[32:33], v[26:29], off
	v_pk_mul_f32 v[24:25], v[24:25], v[34:35] op_sel_hi:[1,0]
	v_pk_mul_f32 v[22:23], v[22:23], v[34:35] op_sel_hi:[1,0]
	v_pk_mul_f32 v[26:27], v[20:21], v[34:35] op_sel_hi:[1,0]
	v_pk_mul_f32 v[20:21], v[18:19], v[34:35] op_sel_hi:[1,0]
	v_cvt_pk_bf16_f32 v18, v22, v23
	v_cvt_pk_bf16_f32 v19, v24, v25
	s_mov_b32 s9, 0x2c000
	v_cvt_pk_bf16_f32 v20, v20, v21
	v_cvt_pk_bf16_f32 v21, v26, v27
	global_store_dwordx4 v[30:31], v[18:21], off offset:256
	s_nop 1
	v_mov_b32_e32 v18, v175
	s_mov_b64 s[18:19], 0x2c000
	v_pk_mul_f32 v[16:17], v[16:17], v[18:19] op_sel_hi:[1,0]
	v_pk_mul_f32 v[14:15], v[14:15], v[18:19] op_sel_hi:[1,0]
	v_pk_mul_f32 v[20:21], v[12:13], v[18:19] op_sel_hi:[1,0]
	v_pk_mul_f32 v[12:13], v[10:11], v[18:19] op_sel_hi:[1,0]
	v_cvt_pk_bf16_f32 v10, v14, v15
	v_cvt_pk_bf16_f32 v11, v16, v17
	v_add_co_u32_e32 v16, vcc, s9, v122
	v_cvt_pk_bf16_f32 v12, v12, v13
	v_cvt_pk_bf16_f32 v13, v20, v21
	v_lshl_add_u64 v[14:15], v[122:123], 0, s[18:19]
	s_nop 0
	v_addc_co_u32_e32 v17, vcc, 0, v123, vcc
	global_store_dwordx4 v[16:17], v[10:13], off
	s_andn2_b64 vcc, exec, s[0:1]
	s_mov_b64 s[18:19], s[12:13]
	v_pk_mul_f32 v[10:11], v[4:5], v[18:19] op_sel_hi:[1,0]
	v_pk_mul_f32 v[4:5], v[2:3], v[18:19] op_sel_hi:[1,0]
	v_pk_mul_f32 v[8:9], v[8:9], v[18:19] op_sel_hi:[1,0]
	v_pk_mul_f32 v[6:7], v[6:7], v[18:19] op_sel_hi:[1,0]
	s_nop 0
	v_cvt_pk_bf16_f32 v2, v6, v7
	v_cvt_pk_bf16_f32 v3, v8, v9
	v_cvt_pk_bf16_f32 v4, v4, v5
	v_cvt_pk_bf16_f32 v5, v10, v11
	global_store_dwordx4 v[14:15], v[2:5], off offset:256
	s_cbranch_vccnz .LBB0_750
	s_waitcnt vmcnt(0)
	s_cmpk_gt_u32 s24, 0xff
	s_cbranch_scc1 .LBB0_761
	s_barrier

; #define PG8_STAGE(bufoff, gbase, voff) do { _Pragma("unroll") for (int _i = 0; _i < 2; ++_i) \
;         __builtin_amdgcn_global_load_lds((const unsigned*)((const char*)(gbase) + (voff)[_i]), (LAS unsigned*)(lds + (bufoff) + ldsw + _i * 8192), 16, 0, 0); } while (0)
; #define PG8_LDA(dst, b, h) do { _Pragma("unroll") for (int m = 0; m < 4; ++m) _Pragma("unroll") for (int k = 0; k < 2; ++k) dst[m][k] = *(const LAS bf16x8*)(lds + PG8_SA(b, h) + aoff + m * 2048 + k * 1024); } while (0)
; #define PG8_LDB(dst, b, h) do { _Pragma("unroll") for (int n = 0; n < 2; ++n) _Pragma("unroll") for (int k = 0; k < 2; ++k) dst[n][k] = *(const LAS bf16x8*)(lds + PG8_SB(b, h) + boff + n * 2048 + k * 1024); } while (0)
; #define PG8_MMA(ai, bj, At, Bt) do { __builtin_amdgcn_s_setprio(1); _Pragma("unroll") for (int m = 0; m < 4; ++m) _Pragma("unroll") for (int n = 0; n < 2; ++n) _Pragma("unroll") for (int k = 0; k < 2; ++k) \
;         acc[ai][bj][m][n] = __builtin_amdgcn_mfma_f32_16x16x32_bf16(Bt[n][k], At[m][k], acc[ai][bj][m][n], 0, 0, 0); __builtin_amdgcn_s_setprio(0); } while (0)
; #define PG8_WAIT_L(n) asm volatile("s_waitcnt lgkmcnt(" #n ")" ::: "memory")
; #define PG8_BAR __builtin_amdgcn_s_barrier()
; #define PG8_SCHED __builtin_amdgcn_sched_barrier(0)
; template <class PT, class Epi>
; __device__ __forceinline__ void gemm_phase_once(LAS unsigned char* lds, const PT& S, const Epi& E, bool epi_on) {
;     ...
;             PG8_LDB(B0, 0, 0); PG8_SCHED; PG8_LDA(At, 0, 0); PG8_STAGE(PG8_SA(1, 1), a1 + hstepA, voffA);
;             PG8_WAIT_L(8); PG8_BAR; PG8_WAIT_L(0); PG8_MMA(0, 0, At, B0); PG8_BAR; PG8_SCHED;
;             PG8_LDB(B1, 0, 1); PG8_STAGE(PG8_SB(0, 0), b2, voffB);
;             PG8_BAR; PG8_WAIT_L(0); PG8_MMA(0, 1, At, B1); PG8_BAR;
;             PG8_LDA(At, 0, 1); PG8_STAGE(PG8_SA(0, 0), a2, voffA);
;             PG8_BAR; PG8_WAIT_L(0); PG8_MMA(1, 0, At, B0); PG8_BAR; PG8_SCHED;
.LBB0_2556:
	ds_read_b128 v[148:151], v163
	ds_read_b128 v[170:173], v163 offset:1024
	ds_read_b128 v[174:177], v163 offset:2048
	ds_read_b128 v[178:181], v163 offset:3072
	s_add_u32 s22, s20, 0xfff80080
	s_addc_u32 s23, s21, -1
	s_cmp_eq_u32 s45, 28
	s_cselect_b32 s25, s13, s23
	s_cselect_b32 s24, s41, s22
	s_cselect_b32 s23, s11, s44
	s_cselect_b32 s22, s42, s43
	v_lshl_add_u64 v[214:215], s[20:21], 0, v[140:141]
	s_add_i32 m0, s29, 0xc000
	ds_read_b128 v[182:185], v167
	ds_read_b128 v[186:189], v167 offset:1024
	ds_read_b128 v[190:193], v167 offset:2048
	ds_read_b128 v[194:197], v167 offset:3072
	ds_read_b128 v[198:201], v167 offset:4096
	ds_read_b128 v[202:205], v167 offset:5120
	ds_read_b128 v[206:209], v167 offset:6144
	ds_read_b128 v[210:213], v167 offset:7168
	global_load_lds_dwordx4 v[214:215], off
	v_lshl_add_u64 v[214:215], s[20:21], 0, v[142:143]
	s_add_i32 m0, s29, 0xe000
	s_nop 0
	global_load_lds_dwordx4 v[214:215], off
	s_waitcnt lgkmcnt(8)
	s_barrier
	s_waitcnt lgkmcnt(0)
	s_setprio 1
	s_waitcnt lgkmcnt(0)
	v_mfma_f32_16x16x32_bf16 v[128:131], v[148:151], v[182:185], v[128:131]
	v_mfma_f32_16x16x32_bf16 v[124:127], v[174:177], v[182:185], v[124:127]
	v_mfma_f32_16x16x32_bf16 v[112:115], v[148:151], v[190:193], v[112:115]
	v_mfma_f32_16x16x32_bf16 v[108:111], v[174:177], v[190:193], v[108:111]
	v_mfma_f32_16x16x32_bf16 v[96:99], v[148:151], v[198:201], v[96:99]
	v_mfma_f32_16x16x32_bf16 v[92:95], v[174:177], v[198:201], v[92:95]
	v_mfma_f32_16x16x32_bf16 v[80:83], v[148:151], v[206:209], v[80:83]
	v_mfma_f32_16x16x32_bf16 v[76:79], v[174:177], v[206:209], v[76:79]
	v_mfma_f32_16x16x32_bf16 v[128:131], v[170:173], v[186:189], v[128:131]
	v_mfma_f32_16x16x32_bf16 v[124:127], v[178:181], v[186:189], v[124:127]
	v_mfma_f32_16x16x32_bf16 v[112:115], v[170:173], v[194:197], v[112:115]
	v_mfma_f32_16x16x32_bf16 v[108:111], v[178:181], v[194:197], v[108:111]
	v_mfma_f32_16x16x32_bf16 v[96:99], v[170:173], v[202:205], v[96:99]
	v_mfma_f32_16x16x32_bf16 v[92:95], v[178:181], v[202:205], v[92:95]
	v_mfma_f32_16x16x32_bf16 v[80:83], v[170:173], v[210:213], v[80:83]
	v_mfma_f32_16x16x32_bf16 v[76:79], v[178:181], v[210:213], v[76:79]
	s_setprio 0
	s_barrier
	s_add_i32 s46, s38, s28
	v_lshl_add_u64 v[232:233], s[22:23], 0, v[134:135]
	s_mov_b32 m0, s46
	ds_read_b128 v[214:217], v168
	ds_read_b128 v[218:221], v168 offset:1024
	ds_read_b128 v[222:225], v168 offset:2048
	ds_read_b128 v[226:229], v168 offset:3072
	global_load_lds_dwordx4 v[232:233], off
	v_lshl_add_u64 v[234:235], s[22:23], 0, v[138:139]
	s_add_i32 m0, s46, 0x2000
	s_nop 0
	global_load_lds_dwordx4 v[234:235], off
	s_barrier
	s_waitcnt lgkmcnt(0)
	s_setprio 1
	s_waitcnt lgkmcnt(0)
	v_mfma_f32_16x16x32_bf16 v[120:123], v[214:217], v[182:185], v[120:123]
	v_mfma_f32_16x16x32_bf16 v[116:119], v[222:225], v[182:185], v[116:119]
	v_mfma_f32_16x16x32_bf16 v[104:107], v[214:217], v[190:193], v[104:107]
	v_mfma_f32_16x16x32_bf16 v[100:103], v[222:225], v[190:193], v[100:103]
	v_mfma_f32_16x16x32_bf16 v[88:91], v[214:217], v[198:201], v[88:91]
	v_mfma_f32_16x16x32_bf16 v[84:87], v[222:225], v[198:201], v[84:87]
	v_mfma_f32_16x16x32_bf16 v[72:75], v[214:217], v[206:209], v[72:75]
	v_mfma_f32_16x16x32_bf16 v[68:71], v[222:225], v[206:209], v[68:71]
	v_mfma_f32_16x16x32_bf16 v[120:123], v[218:221], v[186:189], v[120:123]
	v_mfma_f32_16x16x32_bf16 v[116:119], v[226:229], v[186:189], v[116:119]
	v_mfma_f32_16x16x32_bf16 v[104:107], v[218:221], v[194:197], v[104:107]
	v_mfma_f32_16x16x32_bf16 v[100:103], v[226:229], v[194:197], v[100:103]
	v_mfma_f32_16x16x32_bf16 v[88:91], v[218:221], v[202:205], v[88:91]
	v_mfma_f32_16x16x32_bf16 v[84:87], v[226:229], v[202:205], v[84:87]
	v_mfma_f32_16x16x32_bf16 v[72:75], v[218:221], v[210:213], v[72:75]
	v_mfma_f32_16x16x32_bf16 v[68:71], v[226:229], v[210:213], v[68:71]
	s_setprio 0
	s_mov_b32 m0, s29
	v_lshl_add_u64 v[236:237], s[24:25], 0, v[132:133]
	s_barrier
	ds_read_b128 v[182:185], v167 offset:16384
	ds_read_b128 v[186:189], v167 offset:17408
	ds_read_b128 v[190:193], v167 offset:18432
	ds_read_b128 v[194:197], v167 offset:19456
	ds_read_b128 v[198:201], v167 offset:20480
	ds_read_b128 v[202:205], v167 offset:21504
	ds_read_b128 v[206:209], v167 offset:22528
	ds_read_b128 v[210:213], v167 offset:23552
	global_load_lds_dwordx4 v[236:237], off
	v_lshl_add_u64 v[238:239], s[24:25], 0, v[136:137]
	s_mov_b32 m0, s19
	s_nop 0
	global_load_lds_dwordx4 v[238:239], off
	s_barrier
	s_waitcnt lgkmcnt(0)
	s_setprio 1
	s_waitcnt lgkmcnt(0)
	v_mfma_f32_16x16x32_bf16 v[64:67], v[148:151], v[182:185], v[64:67]
	v_mfma_f32_16x16x32_bf16 v[60:63], v[174:177], v[182:185], v[60:63]
	v_mfma_f32_16x16x32_bf16 v[48:51], v[148:151], v[190:193], v[48:51]
	v_mfma_f32_16x16x32_bf16 v[44:47], v[174:177], v[190:193], v[44:47]
	v_mfma_f32_16x16x32_bf16 v[32:35], v[148:151], v[198:201], v[32:35]
	v_mfma_f32_16x16x32_bf16 v[28:31], v[174:177], v[198:201], v[28:31]
	v_mfma_f32_16x16x32_bf16 v[16:19], v[148:151], v[206:209], v[16:19]
	v_mfma_f32_16x16x32_bf16 v[12:15], v[174:177], v[206:209], v[12:15]
	v_mfma_f32_16x16x32_bf16 v[64:67], v[170:173], v[186:189], v[64:67]
	v_mfma_f32_16x16x32_bf16 v[60:63], v[178:181], v[186:189], v[60:63]
	v_mfma_f32_16x16x32_bf16 v[48:51], v[170:173], v[194:197], v[48:51]
	v_mfma_f32_16x16x32_bf16 v[44:47], v[178:181], v[194:197], v[44:47]
	v_mfma_f32_16x16x32_bf16 v[32:35], v[170:173], v[202:205], v[32:35]
	v_mfma_f32_16x16x32_bf16 v[28:31], v[178:181], v[202:205], v[28:31]
	v_mfma_f32_16x16x32_bf16 v[16:19], v[170:173], v[210:213], v[16:19]
	v_mfma_f32_16x16x32_bf16 v[12:15], v[178:181], v[210:213], v[12:15]
	s_setprio 0
	s_barrier
; #define PG8_STAGE(bufoff, gbase, voff) do { _Pragma("unroll") for (int _i = 0; _i < 2; ++_i) \
;         __builtin_amdgcn_global_load_lds((const unsigned*)((const char*)(gbase) + (voff)[_i]), (LAS unsigned*)(lds + (bufoff) + ldsw + _i * 8192), 16, 0, 0); } while (0)
; #define PG8_LDA(dst, b, h) do { _Pragma("unroll") for (int m = 0; m < 4; ++m) _Pragma("unroll") for (int k = 0; k < 2; ++k) dst[m][k] = *(const LAS bf16x8*)(lds + PG8_SA(b, h) + aoff + m * 2048 + k * 1024); } while (0)
; #define PG8_LDB(dst, b, h) do { _Pragma("unroll") for (int n = 0; n < 2; ++n) _Pragma("unroll") for (int k = 0; k < 2; ++k) dst[n][k] = *(const LAS bf16x8*)(lds + PG8_SB(b, h) + boff + n * 2048 + k * 1024); } while (0)
; #define PG8_MMA(ai, bj, At, Bt) do { __builtin_amdgcn_s_setprio(1); _Pragma("unroll") for (int m = 0; m < 4; ++m) _Pragma("unroll") for (int n = 0; n < 2; ++n) _Pragma("unroll") for (int k = 0; k < 2; ++k) \
;         acc[ai][bj][m][n] = __builtin_amdgcn_mfma_f32_16x16x32_bf16(Bt[n][k], At[m][k], acc[ai][bj][m][n], 0, 0, 0); __builtin_amdgcn_s_setprio(0); } while (0)
; #define PG8_WAIT_V(n) asm volatile("s_waitcnt vmcnt(" #n ")" ::: "memory")
; #define PG8_WAIT_L(n) asm volatile("s_waitcnt lgkmcnt(" #n ")" ::: "memory")
; #define PG8_BAR __builtin_amdgcn_s_barrier()
; #define PG8_SCHED __builtin_amdgcn_sched_barrier(0)
; template <class PT, class Epi>
; __device__ __forceinline__ void gemm_phase_once(LAS unsigned char* lds, const PT& S, const Epi& E, bool epi_on) {
;     ...
;             PG8_STAGE(PG8_SB(0, 1), b2 + hstepB, voffB);
;             PG8_WAIT_V(6); PG8_BAR; PG8_MMA(1, 1, At, B1); PG8_BAR;
;             PG8_LDB(B0, 1, 0); PG8_SCHED; PG8_LDA(At, 1, 0); PG8_STAGE(PG8_SA(0, 1), a2 + hstepA, voffA);
;             PG8_WAIT_L(8); PG8_BAR; PG8_WAIT_L(0); PG8_MMA(0, 0, At, B0); PG8_BAR; PG8_SCHED;
;             PG8_LDB(B1, 1, 1); PG8_STAGE(PG8_SB(1, 0), b3, voffB);
;             PG8_BAR; PG8_WAIT_L(0); PG8_MMA(0, 1, At, B1); PG8_BAR;
;             PG8_LDA(At, 1, 1); PG8_STAGE(PG8_SA(1, 0), a3, voffA);
;             PG8_BAR; PG8_WAIT_L(0); PG8_MMA(1, 0, At, B0); PG8_BAR; PG8_SCHED;
	s_add_u32 s46, s22, 0x80000
	s_addc_u32 s47, s23, 0
	s_add_i32 s48, s39, s28
	v_lshl_add_u64 v[148:149], s[46:47], 0, v[134:135]
	s_mov_b32 m0, s48
	s_nop 0
	global_load_lds_dwordx4 v[148:149], off
	v_lshl_add_u64 v[148:149], s[46:47], 0, v[138:139]
	s_add_i32 m0, s48, 0x2000
	s_nop 0
	global_load_lds_dwordx4 v[148:149], off
	s_waitcnt vmcnt(6)
	s_barrier
	s_setprio 1
	v_mfma_f32_16x16x32_bf16 v[56:59], v[214:217], v[182:185], v[56:59]
	v_mfma_f32_16x16x32_bf16 v[52:55], v[222:225], v[182:185], v[52:55]
	v_mfma_f32_16x16x32_bf16 v[40:43], v[214:217], v[190:193], v[40:43]
	v_mfma_f32_16x16x32_bf16 v[36:39], v[222:225], v[190:193], v[36:39]
	v_mfma_f32_16x16x32_bf16 v[24:27], v[214:217], v[198:201], v[24:27]
	v_mfma_f32_16x16x32_bf16 v[20:23], v[222:225], v[198:201], v[20:23]
	v_mfma_f32_16x16x32_bf16 v[8:11], v[214:217], v[206:209], v[8:11]
	v_mfma_f32_16x16x32_bf16 v[4:7], v[222:225], v[206:209], v[4:7]
	v_mfma_f32_16x16x32_bf16 v[56:59], v[218:221], v[186:189], v[56:59]
	v_mfma_f32_16x16x32_bf16 v[52:55], v[226:229], v[186:189], v[52:55]
	v_mfma_f32_16x16x32_bf16 v[40:43], v[218:221], v[194:197], v[40:43]
	v_mfma_f32_16x16x32_bf16 v[36:39], v[226:229], v[194:197], v[36:39]
	v_mfma_f32_16x16x32_bf16 v[24:27], v[218:221], v[202:205], v[24:27]
	v_mfma_f32_16x16x32_bf16 v[20:23], v[226:229], v[202:205], v[20:23]
	v_mfma_f32_16x16x32_bf16 v[8:11], v[218:221], v[210:213], v[8:11]
	v_mfma_f32_16x16x32_bf16 v[4:7], v[226:229], v[210:213], v[4:7]
	s_setprio 0
	s_add_i32 s46, 0, 0x18000
	v_add_u32_e32 v165, s46, v161
	s_barrier
	ds_read_b128 v[148:151], v165
	ds_read_b128 v[170:173], v165 offset:1024
	ds_read_b128 v[174:177], v165 offset:2048
	ds_read_b128 v[178:181], v165 offset:3072
	s_add_u32 s24, s24, 0x80000
	s_addc_u32 s25, s25, 0
	s_mov_b32 m0, s30
	v_lshl_add_u64 v[214:215], s[24:25], 0, v[132:133]
	ds_read_b128 v[182:185], v167 offset:32768
	ds_read_b128 v[186:189], v167 offset:33792
	ds_read_b128 v[190:193], v167 offset:34816
	ds_read_b128 v[194:197], v167 offset:35840
	ds_read_b128 v[198:201], v167 offset:36864
	ds_read_b128 v[202:205], v167 offset:37888
	ds_read_b128 v[206:209], v167 offset:38912
	ds_read_b128 v[210:213], v167 offset:39936
	global_load_lds_dwordx4 v[214:215], off
	v_lshl_add_u64 v[214:215], s[24:25], 0, v[136:137]
	s_mov_b32 m0, s31
	s_nop 0
	global_load_lds_dwordx4 v[214:215], off
	s_waitcnt lgkmcnt(8)
	s_barrier
	s_waitcnt lgkmcnt(0)
	s_setprio 1
	s_waitcnt lgkmcnt(0)
	v_mfma_f32_16x16x32_bf16 v[128:131], v[148:151], v[182:185], v[128:131]
	v_mfma_f32_16x16x32_bf16 v[124:127], v[174:177], v[182:185], v[124:127]
	v_mfma_f32_16x16x32_bf16 v[112:115], v[148:151], v[190:193], v[112:115]
	v_mfma_f32_16x16x32_bf16 v[108:111], v[174:177], v[190:193], v[108:111]
	v_mfma_f32_16x16x32_bf16 v[96:99], v[148:151], v[198:201], v[96:99]
	v_mfma_f32_16x16x32_bf16 v[92:95], v[174:177], v[198:201], v[92:95]
	v_mfma_f32_16x16x32_bf16 v[80:83], v[148:151], v[206:209], v[80:83]
	v_mfma_f32_16x16x32_bf16 v[76:79], v[174:177], v[206:209], v[76:79]
	v_mfma_f32_16x16x32_bf16 v[128:131], v[170:173], v[186:189], v[128:131]
	v_mfma_f32_16x16x32_bf16 v[124:127], v[178:181], v[186:189], v[124:127]
	v_mfma_f32_16x16x32_bf16 v[112:115], v[170:173], v[194:197], v[112:115]
	v_mfma_f32_16x16x32_bf16 v[108:111], v[178:181], v[194:197], v[108:111]
	v_mfma_f32_16x16x32_bf16 v[96:99], v[170:173], v[202:205], v[96:99]
	v_mfma_f32_16x16x32_bf16 v[92:95], v[178:181], v[202:205], v[92:95]
	v_mfma_f32_16x16x32_bf16 v[80:83], v[170:173], v[210:213], v[80:83]
	v_mfma_f32_16x16x32_bf16 v[76:79], v[178:181], v[210:213], v[76:79]
	s_setprio 0
	s_barrier
	s_add_i32 s24, 0, 0x1c000
	s_add_i32 s25, s46, s28
	v_add_u32_e32 v165, s24, v161
	v_lshl_add_u64 v[232:233], v[232:233], 0, s[8:9]
	s_mov_b32 m0, s25
	ds_read_b128 v[214:217], v165
	ds_read_b128 v[218:221], v165 offset:1024
	ds_read_b128 v[222:225], v165 offset:2048
	ds_read_b128 v[226:229], v165 offset:3072
	global_load_lds_dwordx4 v[232:233], off
	v_lshl_add_u64 v[232:233], v[234:235], 0, s[8:9]
	s_add_i32 m0, s25, 0x2000
	s_nop 0
	global_load_lds_dwordx4 v[232:233], off
	s_barrier
	s_waitcnt lgkmcnt(0)
	s_setprio 1
	s_waitcnt lgkmcnt(0)
	v_mfma_f32_16x16x32_bf16 v[120:123], v[214:217], v[182:185], v[120:123]
	v_mfma_f32_16x16x32_bf16 v[116:119], v[222:225], v[182:185], v[116:119]
	v_mfma_f32_16x16x32_bf16 v[104:107], v[214:217], v[190:193], v[104:107]
	v_mfma_f32_16x16x32_bf16 v[100:103], v[222:225], v[190:193], v[100:103]
	v_mfma_f32_16x16x32_bf16 v[88:91], v[214:217], v[198:201], v[88:91]
	v_mfma_f32_16x16x32_bf16 v[84:87], v[222:225], v[198:201], v[84:87]
	v_mfma_f32_16x16x32_bf16 v[72:75], v[214:217], v[206:209], v[72:75]
	v_mfma_f32_16x16x32_bf16 v[68:71], v[222:225], v[206:209], v[68:71]
	v_mfma_f32_16x16x32_bf16 v[120:123], v[218:221], v[186:189], v[120:123]
	v_mfma_f32_16x16x32_bf16 v[116:119], v[226:229], v[186:189], v[116:119]
	v_mfma_f32_16x16x32_bf16 v[104:107], v[218:221], v[194:197], v[104:107]
	v_mfma_f32_16x16x32_bf16 v[100:103], v[226:229], v[194:197], v[100:103]
	v_mfma_f32_16x16x32_bf16 v[88:91], v[218:221], v[202:205], v[88:91]
	v_mfma_f32_16x16x32_bf16 v[84:87], v[226:229], v[202:205], v[84:87]
	v_mfma_f32_16x16x32_bf16 v[72:75], v[218:221], v[210:213], v[72:75]
	v_mfma_f32_16x16x32_bf16 v[68:71], v[226:229], v[210:213], v[68:71]
	s_setprio 0
	s_mov_b32 m0, s35
	v_lshl_add_u64 v[232:233], v[236:237], 0, s[8:9]
	s_barrier
	ds_read_b128 v[182:185], v167 offset:49152
	ds_read_b128 v[186:189], v167 offset:50176
	ds_read_b128 v[190:193], v167 offset:51200
	ds_read_b128 v[194:197], v167 offset:52224
	ds_read_b128 v[198:201], v167 offset:53248
	ds_read_b128 v[202:205], v167 offset:54272
	ds_read_b128 v[206:209], v167 offset:55296
	ds_read_b128 v[210:213], v167 offset:56320
	global_load_lds_dwordx4 v[232:233], off
	v_lshl_add_u64 v[232:233], v[238:239], 0, s[8:9]
	s_mov_b32 m0, s36
	s_nop 0
	global_load_lds_dwordx4 v[232:233], off
	s_barrier
; #define PG8_STAGE(bufoff, gbase, voff) do { _Pragma("unroll") for (int _i = 0; _i < 2; ++_i) \
;         __builtin_amdgcn_global_load_lds((const unsigned*)((const char*)(gbase) + (voff)[_i]), (LAS unsigned*)(lds + (bufoff) + ldsw + _i * 8192), 16, 0, 0); } while (0)
; #define PG8_MMA(ai, bj, At, Bt) do { __builtin_amdgcn_s_setprio(1); _Pragma("unroll") for (int m = 0; m < 4; ++m) _Pragma("unroll") for (int n = 0; n < 2; ++n) _Pragma("unroll") for (int k = 0; k < 2; ++k) \
;         acc[ai][bj][m][n] = __builtin_amdgcn_mfma_f32_16x16x32_bf16(Bt[n][k], At[m][k], acc[ai][bj][m][n], 0, 0, 0); __builtin_amdgcn_s_setprio(0); } while (0)
; #define PG8_WAIT_V(n) asm volatile("s_waitcnt vmcnt(" #n ")" ::: "memory")
; #define PG8_WAIT_L(n) asm volatile("s_waitcnt lgkmcnt(" #n ")" ::: "memory")
; #define PG8_BAR __builtin_amdgcn_s_barrier()
; #define PG8_SCHED __builtin_amdgcn_sched_barrier(0)
;     __device__ __forceinline__ void operator()(const f32x4 (&acc)[2][2][4][2], const Unit& u, int wr, int wc, int fr, int fq) const {
;         const int row0 = u.pm * BM + wr * 64 + fr, col0 = u.pn * BM + wc * 32 + 8 * fq;
; #pragma unroll
;         for (int ai = 0; ai < 2; ++ai)
; #pragma unroll
;             for (int m = 0; m < 4; ++m) { const int row = row0 + ai * HALF + m * 16; const float rs = rowscale ? rowscale[row] : 1.f;
; #pragma unroll
;                 for (int bj = 0; bj < 2; ++bj) f(row, col0 + bj * HALF, acc[ai][bj][m][0] * rs, acc[ai][bj][m][1] * rs); }
; template <class PT, class Epi>
; __device__ __forceinline__ void gemm_phase_once(LAS unsigned char* lds, const PT& S, const Epi& E, bool epi_on) {
;     ...
;             PG8_BAR; PG8_WAIT_L(0); PG8_MMA(1, 0, At, B0); PG8_BAR; PG8_SCHED;
;             PG8_STAGE(PG8_SB(1, 1), b3 + hstepB, voffB);
;             PG8_WAIT_V(6); PG8_BAR; PG8_MMA(1, 1, At, B1); PG8_BAR;
	s_waitcnt lgkmcnt(0)
	s_setprio 1
	s_waitcnt lgkmcnt(0)
	v_mfma_f32_16x16x32_bf16 v[64:67], v[148:151], v[182:185], v[64:67]
	v_mfma_f32_16x16x32_bf16 v[60:63], v[174:177], v[182:185], v[60:63]
	v_mfma_f32_16x16x32_bf16 v[48:51], v[148:151], v[190:193], v[48:51]
	v_mfma_f32_16x16x32_bf16 v[44:47], v[174:177], v[190:193], v[44:47]
	v_mfma_f32_16x16x32_bf16 v[32:35], v[148:151], v[198:201], v[32:35]
	v_mfma_f32_16x16x32_bf16 v[28:31], v[174:177], v[198:201], v[28:31]
	v_mfma_f32_16x16x32_bf16 v[16:19], v[148:151], v[206:209], v[16:19]
	v_mfma_f32_16x16x32_bf16 v[12:15], v[174:177], v[206:209], v[12:15]
	v_mfma_f32_16x16x32_bf16 v[64:67], v[170:173], v[186:189], v[64:67]
	v_mfma_f32_16x16x32_bf16 v[60:63], v[178:181], v[186:189], v[60:63]
	v_mfma_f32_16x16x32_bf16 v[48:51], v[170:173], v[194:197], v[48:51]
	v_mfma_f32_16x16x32_bf16 v[44:47], v[178:181], v[194:197], v[44:47]
	v_mfma_f32_16x16x32_bf16 v[32:35], v[170:173], v[202:205], v[32:35]
	v_mfma_f32_16x16x32_bf16 v[28:31], v[178:181], v[202:205], v[28:31]
	v_mfma_f32_16x16x32_bf16 v[16:19], v[170:173], v[210:213], v[16:19]
	v_mfma_f32_16x16x32_bf16 v[12:15], v[178:181], v[210:213], v[12:15]
	s_setprio 0
	s_barrier
	s_add_u32 s22, s22, 0x80080
	s_addc_u32 s23, s23, 0
	s_add_i32 s24, s24, s28
	v_lshl_add_u64 v[148:149], s[22:23], 0, v[134:135]
	s_mov_b32 m0, s24
	s_nop 0
	global_load_lds_dwordx4 v[148:149], off
	v_lshl_add_u64 v[148:149], s[22:23], 0, v[138:139]
	s_add_i32 m0, s24, 0x2000
	s_nop 0
	global_load_lds_dwordx4 v[148:149], off
	s_waitcnt vmcnt(6)
	s_barrier
	s_setprio 1
	v_mfma_f32_16x16x32_bf16 v[56:59], v[214:217], v[182:185], v[56:59]
	v_mfma_f32_16x16x32_bf16 v[52:55], v[222:225], v[182:185], v[52:55]
	v_mfma_f32_16x16x32_bf16 v[40:43], v[214:217], v[190:193], v[40:43]
	v_mfma_f32_16x16x32_bf16 v[36:39], v[222:225], v[190:193], v[36:39]
	v_mfma_f32_16x16x32_bf16 v[24:27], v[214:217], v[198:201], v[24:27]
	v_mfma_f32_16x16x32_bf16 v[20:23], v[222:225], v[198:201], v[20:23]
	v_mfma_f32_16x16x32_bf16 v[8:11], v[214:217], v[206:209], v[8:11]
	v_mfma_f32_16x16x32_bf16 v[4:7], v[222:225], v[206:209], v[4:7]
	v_mfma_f32_16x16x32_bf16 v[56:59], v[218:221], v[186:189], v[56:59]
	v_mfma_f32_16x16x32_bf16 v[52:55], v[226:229], v[186:189], v[52:55]
	v_mfma_f32_16x16x32_bf16 v[40:43], v[218:221], v[194:197], v[40:43]
	v_mfma_f32_16x16x32_bf16 v[36:39], v[226:229], v[194:197], v[36:39]
	v_mfma_f32_16x16x32_bf16 v[24:27], v[218:221], v[202:205], v[24:27]
	v_mfma_f32_16x16x32_bf16 v[20:23], v[226:229], v[202:205], v[20:23]
	v_mfma_f32_16x16x32_bf16 v[8:11], v[218:221], v[210:213], v[8:11]
	v_mfma_f32_16x16x32_bf16 v[4:7], v[226:229], v[210:213], v[4:7]
	s_setprio 0
	s_add_i32 s45, s45, 2
	s_add_u32 s20, s20, 0x100
	s_addc_u32 s21, s21, 0
	s_add_u32 s43, s43, 0x100
	s_addc_u32 s44, s44, 0
	s_cmp_lt_u32 s45, 30
	s_barrier
	s_cbranch_scc1 .LBB0_2556
	v_lshl_add_u32 v150, s18, 8, v160
	v_ashrrev_i32_e32 v151, 31, v150
	v_lshl_add_u64 v[148:149], v[150:151], 2, s[90:91]
	global_load_dword v166, v[148:149], off
	global_load_dword v165, v[148:149], off offset:64
	global_load_dword v169, v[148:149], off offset:128
	global_load_dword v172, v[148:149], off offset:192
	global_load_dword v173, v[148:149], off offset:512
	global_load_dword v174, v[148:149], off offset:576
	global_load_dword v175, v[148:149], off offset:640
	global_load_dword v176, v[148:149], off offset:704
	v_lshl_or_b32 v170, s40, 8, v162
	v_readlane_b32 s20, v254, 44
	v_readlane_b32 s21, v254, 45
	v_ashrrev_i32_e32 v171, 31, v170
	s_mov_b32 s11, 0x20000
	s_mov_b32 s40, s10
	s_mov_b32 s18, s12
	s_mov_b64 s[22:23], s[16:17]
	s_waitcnt vmcnt(0)
	v_pk_mul_f32 v[130:131], v[130:131], v[166:167] op_sel_hi:[1,0]
	v_pk_mul_f32 v[128:129], v[128:129], v[166:167] op_sel_hi:[1,0]
	v_pk_mul_f32 v[124:125], v[124:125], v[166:167] op_sel_hi:[1,0]
	v_pk_mul_f32 v[126:127], v[126:127], v[166:167] op_sel_hi:[1,0]
	v_cvt_pk_bf16_f32 v128, v128, v129
	v_cvt_pk_bf16_f32 v129, v130, v131
	v_cvt_pk_bf16_f32 v130, v124, v125
	v_lshlrev_b64 v[124:125], 10, v[150:151]
	v_cvt_pk_bf16_f32 v131, v126, v127
	v_lshl_add_u64 v[124:125], s[20:21], 0, v[124:125]
	v_lshlrev_b64 v[126:127], 1, v[170:171]
	v_lshl_add_u64 v[124:125], v[124:125], 0, v[126:127]
	global_store_dwordx4 v[124:125], v[128:131], off
	v_pk_mul_f32 v[120:121], v[120:121], v[166:167] op_sel_hi:[1,0]
	v_pk_mul_f32 v[122:123], v[122:123], v[166:167] op_sel_hi:[1,0]
	v_pk_mul_f32 v[128:129], v[118:119], v[166:167] op_sel_hi:[1,0]
	v_pk_mul_f32 v[118:119], v[116:117], v[166:167] op_sel_hi:[1,0]
	v_cvt_pk_bf16_f32 v116, v120, v121
	v_cvt_pk_bf16_f32 v117, v122, v123
	s_nop 0
	v_cvt_pk_bf16_f32 v118, v118, v119
	v_cvt_pk_bf16_f32 v119, v128, v129
	global_store_dwordx4 v[124:125], v[116:119], off offset:256
	s_nop 1
	v_or_b32_e32 v116, 16, v150
	v_ashrrev_i32_e32 v117, 31, v116
	v_lshl_add_u64 v[118:119], v[116:117], 2, s[90:91]
	s_nop 1
	v_mov_b32_e32 v118, v165
	v_pk_mul_f32 v[112:113], v[112:113], v[118:119] op_sel_hi:[1,0]
	v_pk_mul_f32 v[120:121], v[110:111], v[118:119] op_sel_hi:[1,0]
	v_pk_mul_f32 v[110:111], v[108:109], v[118:119] op_sel_hi:[1,0]
	v_cvt_pk_bf16_f32 v108, v112, v113
	v_lshlrev_b64 v[112:113], 10, v[116:117]
	v_lshl_add_u64 v[112:113], s[20:21], 0, v[112:113]
	v_pk_mul_f32 v[114:115], v[114:115], v[118:119] op_sel_hi:[1,0]
	v_lshl_add_u64 v[112:113], v[112:113], 0, v[126:127]
	v_cvt_pk_bf16_f32 v109, v114, v115
	v_cvt_pk_bf16_f32 v110, v110, v111
	v_cvt_pk_bf16_f32 v111, v120, v121
	global_store_dwordx4 v[112:113], v[108:111], off
	v_pk_mul_f32 v[104:105], v[104:105], v[118:119] op_sel_hi:[1,0]
	v_pk_mul_f32 v[106:107], v[106:107], v[118:119] op_sel_hi:[1,0]
;     __device__ __forceinline__ void operator()(const f32x4 (&acc)[2][2][4][2], const Unit& u, int wr, int wc, int fr, int fq) const {
;         const int row0 = u.pm * BM + wr * 64 + fr, col0 = u.pn * BM + wc * 32 + 8 * fq;
; #pragma unroll
;         for (int ai = 0; ai < 2; ++ai)
; #pragma unroll
;             for (int m = 0; m < 4; ++m) { const int row = row0 + ai * HALF + m * 16; const float rs = rowscale ? rowscale[row] : 1.f;
; #pragma unroll
;                 for (int bj = 0; bj < 2; ++bj) f(row, col0 + bj * HALF, acc[ai][bj][m][0] * rs, acc[ai][bj][m][1] * rs); }
	v_pk_mul_f32 v[108:109], v[102:103], v[118:119] op_sel_hi:[1,0]
	v_pk_mul_f32 v[102:103], v[100:101], v[118:119] op_sel_hi:[1,0]
	v_cvt_pk_bf16_f32 v100, v104, v105
	v_cvt_pk_bf16_f32 v101, v106, v107
	s_nop 0
	v_cvt_pk_bf16_f32 v102, v102, v103
	v_cvt_pk_bf16_f32 v103, v108, v109
	global_store_dwordx4 v[112:113], v[100:103], off offset:256
	s_nop 1
	v_or_b32_e32 v100, 32, v150
	v_ashrrev_i32_e32 v101, 31, v100
	v_lshl_add_u64 v[102:103], v[100:101], 2, s[90:91]
	s_nop 1
	v_mov_b32_e32 v102, v169
	v_pk_mul_f32 v[96:97], v[96:97], v[102:103] op_sel_hi:[1,0]
	v_pk_mul_f32 v[104:105], v[94:95], v[102:103] op_sel_hi:[1,0]
	v_pk_mul_f32 v[94:95], v[92:93], v[102:103] op_sel_hi:[1,0]
	v_cvt_pk_bf16_f32 v92, v96, v97
	v_lshlrev_b64 v[96:97], 10, v[100:101]
	v_lshl_add_u64 v[96:97], s[20:21], 0, v[96:97]
	v_pk_mul_f32 v[98:99], v[98:99], v[102:103] op_sel_hi:[1,0]
	v_lshl_add_u64 v[96:97], v[96:97], 0, v[126:127]
	v_cvt_pk_bf16_f32 v93, v98, v99
	v_cvt_pk_bf16_f32 v94, v94, v95
	v_cvt_pk_bf16_f32 v95, v104, v105
	global_store_dwordx4 v[96:97], v[92:95], off
	v_pk_mul_f32 v[88:89], v[88:89], v[102:103] op_sel_hi:[1,0]
	v_pk_mul_f32 v[90:91], v[90:91], v[102:103] op_sel_hi:[1,0]
	v_pk_mul_f32 v[92:93], v[86:87], v[102:103] op_sel_hi:[1,0]
	v_pk_mul_f32 v[86:87], v[84:85], v[102:103] op_sel_hi:[1,0]
	v_cvt_pk_bf16_f32 v84, v88, v89
	v_cvt_pk_bf16_f32 v85, v90, v91
	s_nop 0
	v_cvt_pk_bf16_f32 v86, v86, v87
	v_cvt_pk_bf16_f32 v87, v92, v93
	global_store_dwordx4 v[96:97], v[84:87], off offset:256
	s_nop 1
	v_or_b32_e32 v84, 48, v150
	v_ashrrev_i32_e32 v85, 31, v84
	v_lshl_add_u64 v[86:87], v[84:85], 2, s[90:91]
	s_nop 1
	v_mov_b32_e32 v86, v172
	v_pk_mul_f32 v[80:81], v[80:81], v[86:87] op_sel_hi:[1,0]
	v_pk_mul_f32 v[88:89], v[78:79], v[86:87] op_sel_hi:[1,0]
	v_pk_mul_f32 v[78:79], v[76:77], v[86:87] op_sel_hi:[1,0]
	v_cvt_pk_bf16_f32 v76, v80, v81
	v_lshlrev_b64 v[80:81], 10, v[84:85]
	v_lshl_add_u64 v[80:81], s[20:21], 0, v[80:81]
	v_pk_mul_f32 v[82:83], v[82:83], v[86:87] op_sel_hi:[1,0]
	v_lshl_add_u64 v[80:81], v[80:81], 0, v[126:127]
	v_cvt_pk_bf16_f32 v77, v82, v83
	v_cvt_pk_bf16_f32 v78, v78, v79
	v_cvt_pk_bf16_f32 v79, v88, v89
	global_store_dwordx4 v[80:81], v[76:79], off
	v_pk_mul_f32 v[74:75], v[74:75], v[86:87] op_sel_hi:[1,0]
	v_pk_mul_f32 v[72:73], v[72:73], v[86:87] op_sel_hi:[1,0]
	v_pk_mul_f32 v[76:77], v[70:71], v[86:87] op_sel_hi:[1,0]
	v_pk_mul_f32 v[70:71], v[68:69], v[86:87] op_sel_hi:[1,0]
	v_cvt_pk_bf16_f32 v68, v72, v73
	v_cvt_pk_bf16_f32 v69, v74, v75
	s_mov_b64 s[20:21], 0x20000
	v_cvt_pk_bf16_f32 v70, v70, v71
	v_cvt_pk_bf16_f32 v71, v76, v77
	global_store_dwordx4 v[80:81], v[68:71], off offset:256
	s_nop 1
	v_mov_b32_e32 v68, v173
	v_pk_mul_f32 v[66:67], v[66:67], v[68:69] op_sel_hi:[1,0]
	v_pk_mul_f32 v[64:65], v[64:65], v[68:69] op_sel_hi:[1,0]
	v_pk_mul_f32 v[70:71], v[62:63], v[68:69] op_sel_hi:[1,0]
	v_pk_mul_f32 v[62:63], v[60:61], v[68:69] op_sel_hi:[1,0]
	v_cvt_pk_bf16_f32 v60, v64, v65
	v_cvt_pk_bf16_f32 v61, v66, v67
	v_add_co_u32_e32 v66, vcc, s11, v124
	v_cvt_pk_bf16_f32 v62, v62, v63
	v_cvt_pk_bf16_f32 v63, v70, v71
	v_lshl_add_u64 v[64:65], v[124:125], 0, s[20:21]
	s_nop 0
	v_addc_co_u32_e32 v67, vcc, 0, v125, vcc
	global_store_dwordx4 v[66:67], v[60:63], off
	v_pk_mul_f32 v[58:59], v[58:59], v[68:69] op_sel_hi:[1,0]
	v_pk_mul_f32 v[56:57], v[56:57], v[68:69] op_sel_hi:[1,0]
	v_pk_mul_f32 v[60:61], v[54:55], v[68:69] op_sel_hi:[1,0]
	v_pk_mul_f32 v[54:55], v[52:53], v[68:69] op_sel_hi:[1,0]
	v_cvt_pk_bf16_f32 v52, v56, v57
	v_cvt_pk_bf16_f32 v53, v58, v59
	s_mov_b32 s11, 0x24000
	v_cvt_pk_bf16_f32 v54, v54, v55
	v_cvt_pk_bf16_f32 v55, v60, v61
	global_store_dwordx4 v[64:65], v[52:55], off offset:256
	s_nop 1
	v_mov_b32_e32 v52, v174
	s_mov_b64 s[20:21], 0x24000
	v_pk_mul_f32 v[50:51], v[50:51], v[52:53] op_sel_hi:[1,0]
	v_pk_mul_f32 v[48:49], v[48:49], v[52:53] op_sel_hi:[1,0]
	v_pk_mul_f32 v[54:55], v[46:47], v[52:53] op_sel_hi:[1,0]
	v_pk_mul_f32 v[46:47], v[44:45], v[52:53] op_sel_hi:[1,0]
	v_cvt_pk_bf16_f32 v44, v48, v49
	v_cvt_pk_bf16_f32 v45, v50, v51
	v_add_co_u32_e32 v50, vcc, s11, v124
	v_cvt_pk_bf16_f32 v46, v46, v47
	v_cvt_pk_bf16_f32 v47, v54, v55
	v_lshl_add_u64 v[48:49], v[124:125], 0, s[20:21]
	s_nop 0
	v_addc_co_u32_e32 v51, vcc, 0, v125, vcc
	global_store_dwordx4 v[50:51], v[44:47], off
	v_pk_mul_f32 v[42:43], v[42:43], v[52:53] op_sel_hi:[1,0]
	v_pk_mul_f32 v[40:41], v[40:41], v[52:53] op_sel_hi:[1,0]
	v_pk_mul_f32 v[44:45], v[38:39], v[52:53] op_sel_hi:[1,0]
	v_pk_mul_f32 v[38:39], v[36:37], v[52:53] op_sel_hi:[1,0]
	v_cvt_pk_bf16_f32 v36, v40, v41
	v_cvt_pk_bf16_f32 v37, v42, v43
	s_mov_b32 s11, 0x28000
	v_cvt_pk_bf16_f32 v38, v38, v39
	v_cvt_pk_bf16_f32 v39, v44, v45
	global_store_dwordx4 v[48:49], v[36:39], off offset:256
	s_nop 1
	v_mov_b32_e32 v36, v175
	s_mov_b64 s[20:21], 0x28000
	v_pk_mul_f32 v[34:35], v[34:35], v[36:37] op_sel_hi:[1,0]
	v_pk_mul_f32 v[32:33], v[32:33], v[36:37] op_sel_hi:[1,0]
	v_pk_mul_f32 v[38:39], v[30:31], v[36:37] op_sel_hi:[1,0]
	v_pk_mul_f32 v[30:31], v[28:29], v[36:37] op_sel_hi:[1,0]
	v_cvt_pk_bf16_f32 v28, v32, v33
	v_cvt_pk_bf16_f32 v29, v34, v35
	v_add_co_u32_e32 v34, vcc, s11, v124
	v_cvt_pk_bf16_f32 v30, v30, v31
	v_cvt_pk_bf16_f32 v31, v38, v39
	v_lshl_add_u64 v[32:33], v[124:125], 0, s[20:21]
	s_nop 0
	v_addc_co_u32_e32 v35, vcc, 0, v125, vcc
	global_store_dwordx4 v[34:35], v[28:31], off
	v_pk_mul_f32 v[26:27], v[26:27], v[36:37] op_sel_hi:[1,0]
	v_pk_mul_f32 v[24:25], v[24:25], v[36:37] op_sel_hi:[1,0]
	v_pk_mul_f32 v[28:29], v[22:23], v[36:37] op_sel_hi:[1,0]
	v_pk_mul_f32 v[22:23], v[20:21], v[36:37] op_sel_hi:[1,0]
	v_cvt_pk_bf16_f32 v20, v24, v25
	v_cvt_pk_bf16_f32 v21, v26, v27
	s_mov_b32 s11, 0x2c000
	v_cvt_pk_bf16_f32 v22, v22, v23
	v_cvt_pk_bf16_f32 v23, v28, v29
	global_store_dwordx4 v[32:33], v[20:23], off offset:256
	s_nop 1
	v_mov_b32_e32 v20, v176
	s_mov_b64 s[20:21], 0x2c000
	v_pk_mul_f32 v[18:19], v[18:19], v[20:21] op_sel_hi:[1,0]
	v_pk_mul_f32 v[16:17], v[16:17], v[20:21] op_sel_hi:[1,0]
	v_pk_mul_f32 v[22:23], v[14:15], v[20:21] op_sel_hi:[1,0]
	v_pk_mul_f32 v[14:15], v[12:13], v[20:21] op_sel_hi:[1,0]
	v_cvt_pk_bf16_f32 v12, v16, v17
	v_cvt_pk_bf16_f32 v13, v18, v19
	v_add_co_u32_e32 v18, vcc, s11, v124
	v_cvt_pk_bf16_f32 v14, v14, v15
	v_cvt_pk_bf16_f32 v15, v22, v23
	v_lshl_add_u64 v[16:17], v[124:125], 0, s[20:21]
	s_nop 0
	v_addc_co_u32_e32 v19, vcc, 0, v125, vcc
	global_store_dwordx4 v[18:19], v[12:15], off
	s_andn2_b64 vcc, exec, s[0:1]
	s_mov_b64 s[20:21], s[14:15]
	v_pk_mul_f32 v[12:13], v[6:7], v[20:21] op_sel_hi:[1,0]
	v_pk_mul_f32 v[6:7], v[4:5], v[20:21] op_sel_hi:[1,0]
	v_pk_mul_f32 v[10:11], v[10:11], v[20:21] op_sel_hi:[1,0]
	v_pk_mul_f32 v[8:9], v[8:9], v[20:21] op_sel_hi:[1,0]
	s_nop 0
	v_cvt_pk_bf16_f32 v4, v8, v9
	v_cvt_pk_bf16_f32 v5, v10, v11
	v_cvt_pk_bf16_f32 v6, v6, v7
	v_cvt_pk_bf16_f32 v7, v12, v13
	global_store_dwordx4 v[16:17], v[4:7], off offset:256
	s_cbranch_vccnz .LBB0_2549
	s_waitcnt vmcnt(0)
	s_cmpk_gt_u32 s26, 0xff
	s_cbranch_scc1 .LBB0_2560
	s_barrier

; #define PG8_STAGE(bufoff, gbase, voff) do { _Pragma("unroll") for (int _i = 0; _i < 2; ++_i) \
;         __builtin_amdgcn_global_load_lds((const unsigned*)((const char*)(gbase) + (voff)[_i]), (LAS unsigned*)(lds + (bufoff) + ldsw + _i * 8192), 16, 0, 0); } while (0)
; #define PG8_LDA(dst, b, h) do { _Pragma("unroll") for (int m = 0; m < 4; ++m) _Pragma("unroll") for (int k = 0; k < 2; ++k) dst[m][k] = *(const LAS bf16x8*)(lds + PG8_SA(b, h) + aoff + m * 2048 + k * 1024); } while (0)
; #define PG8_LDB(dst, b, h) do { _Pragma("unroll") for (int n = 0; n < 2; ++n) _Pragma("unroll") for (int k = 0; k < 2; ++k) dst[n][k] = *(const LAS bf16x8*)(lds + PG8_SB(b, h) + boff + n * 2048 + k * 1024); } while (0)
; #define PG8_MMA(ai, bj, At, Bt) do { __builtin_amdgcn_s_setprio(1); _Pragma("unroll") for (int m = 0; m < 4; ++m) _Pragma("unroll") for (int n = 0; n < 2; ++n) _Pragma("unroll") for (int k = 0; k < 2; ++k) \
;         acc[ai][bj][m][n] = __builtin_amdgcn_mfma_f32_16x16x32_bf16(Bt[n][k], At[m][k], acc[ai][bj][m][n], 0, 0, 0); __builtin_amdgcn_s_setprio(0); } while (0)
; #define PG8_WAIT_L(n) asm volatile("s_waitcnt lgkmcnt(" #n ")" ::: "memory")
; #define PG8_BAR __builtin_amdgcn_s_barrier()
; #define PG8_SCHED __builtin_amdgcn_sched_barrier(0)
; template <class PT, class Epi>
; __device__ __forceinline__ void gemm_phase_once(LAS unsigned char* lds, const PT& S, const Epi& E, bool epi_on) {
;     ...
;             PG8_LDB(B0, 0, 0); PG8_SCHED; PG8_LDA(At, 0, 0); PG8_STAGE(PG8_SA(1, 1), a1 + hstepA, voffA);
;             PG8_WAIT_L(8); PG8_BAR; PG8_WAIT_L(0); PG8_MMA(0, 0, At, B0); PG8_BAR; PG8_SCHED;
;             PG8_LDB(B1, 0, 1); PG8_STAGE(PG8_SB(0, 0), b2, voffB);
;             PG8_BAR; PG8_WAIT_L(0); PG8_MMA(0, 1, At, B1); PG8_BAR;
;             PG8_LDA(At, 0, 1); PG8_STAGE(PG8_SA(0, 0), a2, voffA);
;             PG8_BAR; PG8_WAIT_L(0); PG8_MMA(1, 0, At, B0); PG8_BAR; PG8_SCHED;
.LBB0_3884:
	ds_read_b128 v[148:151], v163
	ds_read_b128 v[170:173], v163 offset:1024
	ds_read_b128 v[174:177], v163 offset:2048
	ds_read_b128 v[178:181], v163 offset:3072
	s_add_u32 s20, s18, 0xfff80080
	s_addc_u32 s21, s19, -1
	s_cmp_eq_u32 s43, 28
	s_cselect_b32 s23, s11, s21
	s_cselect_b32 s22, s39, s20
	s_cselect_b32 s21, s9, s42
	s_cselect_b32 s20, s40, s41
	v_lshl_add_u64 v[214:215], s[18:19], 0, v[140:141]
	s_add_i32 m0, s27, 0xc000
	ds_read_b128 v[182:185], v167
	ds_read_b128 v[186:189], v167 offset:1024
	ds_read_b128 v[190:193], v167 offset:2048
	ds_read_b128 v[194:197], v167 offset:3072
	ds_read_b128 v[198:201], v167 offset:4096
	ds_read_b128 v[202:205], v167 offset:5120
	ds_read_b128 v[206:209], v167 offset:6144
	ds_read_b128 v[210:213], v167 offset:7168
	global_load_lds_dwordx4 v[214:215], off
	v_lshl_add_u64 v[214:215], s[18:19], 0, v[142:143]
	s_add_i32 m0, s27, 0xe000
	s_nop 0
	global_load_lds_dwordx4 v[214:215], off
	s_waitcnt lgkmcnt(8)
	s_barrier
	s_waitcnt lgkmcnt(0)
	s_setprio 1
	s_waitcnt lgkmcnt(0)
	v_mfma_f32_16x16x32_bf16 v[128:131], v[148:151], v[182:185], v[128:131]
	v_mfma_f32_16x16x32_bf16 v[124:127], v[174:177], v[182:185], v[124:127]
	v_mfma_f32_16x16x32_bf16 v[112:115], v[148:151], v[190:193], v[112:115]
	v_mfma_f32_16x16x32_bf16 v[108:111], v[174:177], v[190:193], v[108:111]
	v_mfma_f32_16x16x32_bf16 v[96:99], v[148:151], v[198:201], v[96:99]
	v_mfma_f32_16x16x32_bf16 v[92:95], v[174:177], v[198:201], v[92:95]
	v_mfma_f32_16x16x32_bf16 v[80:83], v[148:151], v[206:209], v[80:83]
	v_mfma_f32_16x16x32_bf16 v[76:79], v[174:177], v[206:209], v[76:79]
	v_mfma_f32_16x16x32_bf16 v[128:131], v[170:173], v[186:189], v[128:131]
	v_mfma_f32_16x16x32_bf16 v[124:127], v[178:181], v[186:189], v[124:127]
	v_mfma_f32_16x16x32_bf16 v[112:115], v[170:173], v[194:197], v[112:115]
	v_mfma_f32_16x16x32_bf16 v[108:111], v[178:181], v[194:197], v[108:111]
	v_mfma_f32_16x16x32_bf16 v[96:99], v[170:173], v[202:205], v[96:99]
	v_mfma_f32_16x16x32_bf16 v[92:95], v[178:181], v[202:205], v[92:95]
	v_mfma_f32_16x16x32_bf16 v[80:83], v[170:173], v[210:213], v[80:83]
	v_mfma_f32_16x16x32_bf16 v[76:79], v[178:181], v[210:213], v[76:79]
	s_setprio 0
	s_barrier
	s_add_i32 s44, s36, s26
	v_lshl_add_u64 v[232:233], s[20:21], 0, v[134:135]
	s_mov_b32 m0, s44
	ds_read_b128 v[214:217], v168
	ds_read_b128 v[218:221], v168 offset:1024
	ds_read_b128 v[222:225], v168 offset:2048
	ds_read_b128 v[226:229], v168 offset:3072
	global_load_lds_dwordx4 v[232:233], off
	v_lshl_add_u64 v[234:235], s[20:21], 0, v[138:139]
	s_add_i32 m0, s44, 0x2000
	s_nop 0
	global_load_lds_dwordx4 v[234:235], off
	s_barrier
	s_waitcnt lgkmcnt(0)
	s_setprio 1
	s_waitcnt lgkmcnt(0)
	v_mfma_f32_16x16x32_bf16 v[120:123], v[214:217], v[182:185], v[120:123]
	v_mfma_f32_16x16x32_bf16 v[116:119], v[222:225], v[182:185], v[116:119]
	v_mfma_f32_16x16x32_bf16 v[104:107], v[214:217], v[190:193], v[104:107]
	v_mfma_f32_16x16x32_bf16 v[100:103], v[222:225], v[190:193], v[100:103]
	v_mfma_f32_16x16x32_bf16 v[88:91], v[214:217], v[198:201], v[88:91]
	v_mfma_f32_16x16x32_bf16 v[84:87], v[222:225], v[198:201], v[84:87]
	v_mfma_f32_16x16x32_bf16 v[72:75], v[214:217], v[206:209], v[72:75]
	v_mfma_f32_16x16x32_bf16 v[68:71], v[222:225], v[206:209], v[68:71]
	v_mfma_f32_16x16x32_bf16 v[120:123], v[218:221], v[186:189], v[120:123]
	v_mfma_f32_16x16x32_bf16 v[116:119], v[226:229], v[186:189], v[116:119]
	v_mfma_f32_16x16x32_bf16 v[104:107], v[218:221], v[194:197], v[104:107]
	v_mfma_f32_16x16x32_bf16 v[100:103], v[226:229], v[194:197], v[100:103]
	v_mfma_f32_16x16x32_bf16 v[88:91], v[218:221], v[202:205], v[88:91]
	v_mfma_f32_16x16x32_bf16 v[84:87], v[226:229], v[202:205], v[84:87]
	v_mfma_f32_16x16x32_bf16 v[72:75], v[218:221], v[210:213], v[72:75]
	v_mfma_f32_16x16x32_bf16 v[68:71], v[226:229], v[210:213], v[68:71]
	s_setprio 0
	s_mov_b32 m0, s27
	v_lshl_add_u64 v[236:237], s[22:23], 0, v[132:133]
	s_barrier
	ds_read_b128 v[182:185], v167 offset:16384
	ds_read_b128 v[186:189], v167 offset:17408
	ds_read_b128 v[190:193], v167 offset:18432
	ds_read_b128 v[194:197], v167 offset:19456
	ds_read_b128 v[198:201], v167 offset:20480
	ds_read_b128 v[202:205], v167 offset:21504
	ds_read_b128 v[206:209], v167 offset:22528
	ds_read_b128 v[210:213], v167 offset:23552
	global_load_lds_dwordx4 v[236:237], off
	v_lshl_add_u64 v[238:239], s[22:23], 0, v[136:137]
	s_mov_b32 m0, s17
	s_nop 0
	global_load_lds_dwordx4 v[238:239], off
	s_barrier
	s_waitcnt lgkmcnt(0)
	s_setprio 1
	s_waitcnt lgkmcnt(0)
	v_mfma_f32_16x16x32_bf16 v[64:67], v[148:151], v[182:185], v[64:67]
	v_mfma_f32_16x16x32_bf16 v[60:63], v[174:177], v[182:185], v[60:63]
	v_mfma_f32_16x16x32_bf16 v[48:51], v[148:151], v[190:193], v[48:51]
	v_mfma_f32_16x16x32_bf16 v[44:47], v[174:177], v[190:193], v[44:47]
	v_mfma_f32_16x16x32_bf16 v[32:35], v[148:151], v[198:201], v[32:35]
	v_mfma_f32_16x16x32_bf16 v[28:31], v[174:177], v[198:201], v[28:31]
	v_mfma_f32_16x16x32_bf16 v[16:19], v[148:151], v[206:209], v[16:19]
	v_mfma_f32_16x16x32_bf16 v[12:15], v[174:177], v[206:209], v[12:15]
	v_mfma_f32_16x16x32_bf16 v[64:67], v[170:173], v[186:189], v[64:67]
	v_mfma_f32_16x16x32_bf16 v[60:63], v[178:181], v[186:189], v[60:63]
	v_mfma_f32_16x16x32_bf16 v[48:51], v[170:173], v[194:197], v[48:51]
	v_mfma_f32_16x16x32_bf16 v[44:47], v[178:181], v[194:197], v[44:47]
	v_mfma_f32_16x16x32_bf16 v[32:35], v[170:173], v[202:205], v[32:35]
	v_mfma_f32_16x16x32_bf16 v[28:31], v[178:181], v[202:205], v[28:31]
	v_mfma_f32_16x16x32_bf16 v[16:19], v[170:173], v[210:213], v[16:19]
	v_mfma_f32_16x16x32_bf16 v[12:15], v[178:181], v[210:213], v[12:15]
	s_setprio 0
	s_barrier
; #define PG8_STAGE(bufoff, gbase, voff) do { _Pragma("unroll") for (int _i = 0; _i < 2; ++_i) \
;         __builtin_amdgcn_global_load_lds((const unsigned*)((const char*)(gbase) + (voff)[_i]), (LAS unsigned*)(lds + (bufoff) + ldsw + _i * 8192), 16, 0, 0); } while (0)
; #define PG8_LDA(dst, b, h) do { _Pragma("unroll") for (int m = 0; m < 4; ++m) _Pragma("unroll") for (int k = 0; k < 2; ++k) dst[m][k] = *(const LAS bf16x8*)(lds + PG8_SA(b, h) + aoff + m * 2048 + k * 1024); } while (0)
; #define PG8_LDB(dst, b, h) do { _Pragma("unroll") for (int n = 0; n < 2; ++n) _Pragma("unroll") for (int k = 0; k < 2; ++k) dst[n][k] = *(const LAS bf16x8*)(lds + PG8_SB(b, h) + boff + n * 2048 + k * 1024); } while (0)
; #define PG8_MMA(ai, bj, At, Bt) do { __builtin_amdgcn_s_setprio(1); _Pragma("unroll") for (int m = 0; m < 4; ++m) _Pragma("unroll") for (int n = 0; n < 2; ++n) _Pragma("unroll") for (int k = 0; k < 2; ++k) \
;         acc[ai][bj][m][n] = __builtin_amdgcn_mfma_f32_16x16x32_bf16(Bt[n][k], At[m][k], acc[ai][bj][m][n], 0, 0, 0); __builtin_amdgcn_s_setprio(0); } while (0)
; #define PG8_WAIT_V(n) asm volatile("s_waitcnt vmcnt(" #n ")" ::: "memory")
; #define PG8_WAIT_L(n) asm volatile("s_waitcnt lgkmcnt(" #n ")" ::: "memory")
; #define PG8_BAR __builtin_amdgcn_s_barrier()
; #define PG8_SCHED __builtin_amdgcn_sched_barrier(0)
; template <class PT, class Epi>
; __device__ __forceinline__ void gemm_phase_once(LAS unsigned char* lds, const PT& S, const Epi& E, bool epi_on) {
;     ...
;             PG8_STAGE(PG8_SB(0, 1), b2 + hstepB, voffB);
;             PG8_WAIT_V(6); PG8_BAR; PG8_MMA(1, 1, At, B1); PG8_BAR;
;             PG8_LDB(B0, 1, 0); PG8_SCHED; PG8_LDA(At, 1, 0); PG8_STAGE(PG8_SA(0, 1), a2 + hstepA, voffA);
;             PG8_WAIT_L(8); PG8_BAR; PG8_WAIT_L(0); PG8_MMA(0, 0, At, B0); PG8_BAR; PG8_SCHED;
;             PG8_LDB(B1, 1, 1); PG8_STAGE(PG8_SB(1, 0), b3, voffB);
;             PG8_BAR; PG8_WAIT_L(0); PG8_MMA(0, 1, At, B1); PG8_BAR;
;             PG8_LDA(At, 1, 1); PG8_STAGE(PG8_SA(1, 0), a3, voffA);
;             PG8_BAR; PG8_WAIT_L(0); PG8_MMA(1, 0, At, B0); PG8_BAR; PG8_SCHED;
	s_add_u32 s44, s20, 0x80000
	s_addc_u32 s45, s21, 0
	s_add_i32 s46, s37, s26
	v_lshl_add_u64 v[148:149], s[44:45], 0, v[134:135]
	s_mov_b32 m0, s46
	s_nop 0
	global_load_lds_dwordx4 v[148:149], off
	v_lshl_add_u64 v[148:149], s[44:45], 0, v[138:139]
	s_add_i32 m0, s46, 0x2000
	s_nop 0
	global_load_lds_dwordx4 v[148:149], off
	s_waitcnt vmcnt(6)
	s_barrier
	s_setprio 1
	v_mfma_f32_16x16x32_bf16 v[56:59], v[214:217], v[182:185], v[56:59]
	v_mfma_f32_16x16x32_bf16 v[52:55], v[222:225], v[182:185], v[52:55]
	v_mfma_f32_16x16x32_bf16 v[40:43], v[214:217], v[190:193], v[40:43]
	v_mfma_f32_16x16x32_bf16 v[36:39], v[222:225], v[190:193], v[36:39]
	v_mfma_f32_16x16x32_bf16 v[24:27], v[214:217], v[198:201], v[24:27]
	v_mfma_f32_16x16x32_bf16 v[20:23], v[222:225], v[198:201], v[20:23]
	v_mfma_f32_16x16x32_bf16 v[8:11], v[214:217], v[206:209], v[8:11]
	v_mfma_f32_16x16x32_bf16 v[4:7], v[222:225], v[206:209], v[4:7]
	v_mfma_f32_16x16x32_bf16 v[56:59], v[218:221], v[186:189], v[56:59]
	v_mfma_f32_16x16x32_bf16 v[52:55], v[226:229], v[186:189], v[52:55]
	v_mfma_f32_16x16x32_bf16 v[40:43], v[218:221], v[194:197], v[40:43]
	v_mfma_f32_16x16x32_bf16 v[36:39], v[226:229], v[194:197], v[36:39]
	v_mfma_f32_16x16x32_bf16 v[24:27], v[218:221], v[202:205], v[24:27]
	v_mfma_f32_16x16x32_bf16 v[20:23], v[226:229], v[202:205], v[20:23]
	v_mfma_f32_16x16x32_bf16 v[8:11], v[218:221], v[210:213], v[8:11]
	v_mfma_f32_16x16x32_bf16 v[4:7], v[226:229], v[210:213], v[4:7]
	s_setprio 0
	s_add_i32 s44, 0, 0x18000
	v_add_u32_e32 v165, s44, v161
	s_barrier
	ds_read_b128 v[148:151], v165
	ds_read_b128 v[170:173], v165 offset:1024
	ds_read_b128 v[174:177], v165 offset:2048
	ds_read_b128 v[178:181], v165 offset:3072
	s_add_u32 s22, s22, 0x80000
	s_addc_u32 s23, s23, 0
	s_mov_b32 m0, s28
	v_lshl_add_u64 v[214:215], s[22:23], 0, v[132:133]
	ds_read_b128 v[182:185], v167 offset:32768
	ds_read_b128 v[186:189], v167 offset:33792
	ds_read_b128 v[190:193], v167 offset:34816
	ds_read_b128 v[194:197], v167 offset:35840
	ds_read_b128 v[198:201], v167 offset:36864
	ds_read_b128 v[202:205], v167 offset:37888
	ds_read_b128 v[206:209], v167 offset:38912
	ds_read_b128 v[210:213], v167 offset:39936
	global_load_lds_dwordx4 v[214:215], off
	v_lshl_add_u64 v[214:215], s[22:23], 0, v[136:137]
	s_mov_b32 m0, s29
	s_nop 0
	global_load_lds_dwordx4 v[214:215], off
	s_waitcnt lgkmcnt(8)
	s_barrier
	s_waitcnt lgkmcnt(0)
	s_setprio 1
	s_waitcnt lgkmcnt(0)
	v_mfma_f32_16x16x32_bf16 v[128:131], v[148:151], v[182:185], v[128:131]
	v_mfma_f32_16x16x32_bf16 v[124:127], v[174:177], v[182:185], v[124:127]
	v_mfma_f32_16x16x32_bf16 v[112:115], v[148:151], v[190:193], v[112:115]
	v_mfma_f32_16x16x32_bf16 v[108:111], v[174:177], v[190:193], v[108:111]
	v_mfma_f32_16x16x32_bf16 v[96:99], v[148:151], v[198:201], v[96:99]
	v_mfma_f32_16x16x32_bf16 v[92:95], v[174:177], v[198:201], v[92:95]
	v_mfma_f32_16x16x32_bf16 v[80:83], v[148:151], v[206:209], v[80:83]
	v_mfma_f32_16x16x32_bf16 v[76:79], v[174:177], v[206:209], v[76:79]
	v_mfma_f32_16x16x32_bf16 v[128:131], v[170:173], v[186:189], v[128:131]
	v_mfma_f32_16x16x32_bf16 v[124:127], v[178:181], v[186:189], v[124:127]
	v_mfma_f32_16x16x32_bf16 v[112:115], v[170:173], v[194:197], v[112:115]
	v_mfma_f32_16x16x32_bf16 v[108:111], v[178:181], v[194:197], v[108:111]
	v_mfma_f32_16x16x32_bf16 v[96:99], v[170:173], v[202:205], v[96:99]
	v_mfma_f32_16x16x32_bf16 v[92:95], v[178:181], v[202:205], v[92:95]
	v_mfma_f32_16x16x32_bf16 v[80:83], v[170:173], v[210:213], v[80:83]
	v_mfma_f32_16x16x32_bf16 v[76:79], v[178:181], v[210:213], v[76:79]
	s_setprio 0
	s_barrier
	s_add_i32 s22, 0, 0x1c000
	s_add_i32 s23, s44, s26
	v_add_u32_e32 v165, s22, v161
	v_lshl_add_u64 v[232:233], v[232:233], 0, s[6:7]
	s_mov_b32 m0, s23
	ds_read_b128 v[214:217], v165
	ds_read_b128 v[218:221], v165 offset:1024
	ds_read_b128 v[222:225], v165 offset:2048
	ds_read_b128 v[226:229], v165 offset:3072
	global_load_lds_dwordx4 v[232:233], off
	v_lshl_add_u64 v[232:233], v[234:235], 0, s[6:7]
	s_add_i32 m0, s23, 0x2000
	s_nop 0
	global_load_lds_dwordx4 v[232:233], off
	s_barrier
	s_waitcnt lgkmcnt(0)
	s_setprio 1
	s_waitcnt lgkmcnt(0)
	v_mfma_f32_16x16x32_bf16 v[120:123], v[214:217], v[182:185], v[120:123]
	v_mfma_f32_16x16x32_bf16 v[116:119], v[222:225], v[182:185], v[116:119]
	v_mfma_f32_16x16x32_bf16 v[104:107], v[214:217], v[190:193], v[104:107]
	v_mfma_f32_16x16x32_bf16 v[100:103], v[222:225], v[190:193], v[100:103]
	v_mfma_f32_16x16x32_bf16 v[88:91], v[214:217], v[198:201], v[88:91]
	v_mfma_f32_16x16x32_bf16 v[84:87], v[222:225], v[198:201], v[84:87]
	v_mfma_f32_16x16x32_bf16 v[72:75], v[214:217], v[206:209], v[72:75]
	v_mfma_f32_16x16x32_bf16 v[68:71], v[222:225], v[206:209], v[68:71]
	v_mfma_f32_16x16x32_bf16 v[120:123], v[218:221], v[186:189], v[120:123]
	v_mfma_f32_16x16x32_bf16 v[116:119], v[226:229], v[186:189], v[116:119]
	v_mfma_f32_16x16x32_bf16 v[104:107], v[218:221], v[194:197], v[104:107]
	v_mfma_f32_16x16x32_bf16 v[100:103], v[226:229], v[194:197], v[100:103]
	v_mfma_f32_16x16x32_bf16 v[88:91], v[218:221], v[202:205], v[88:91]
	v_mfma_f32_16x16x32_bf16 v[84:87], v[226:229], v[202:205], v[84:87]
	v_mfma_f32_16x16x32_bf16 v[72:75], v[218:221], v[210:213], v[72:75]
	v_mfma_f32_16x16x32_bf16 v[68:71], v[226:229], v[210:213], v[68:71]
	s_setprio 0
	s_mov_b32 m0, s31
	v_lshl_add_u64 v[232:233], v[236:237], 0, s[6:7]
	s_barrier
	ds_read_b128 v[182:185], v167 offset:49152
	ds_read_b128 v[186:189], v167 offset:50176
	ds_read_b128 v[190:193], v167 offset:51200
	ds_read_b128 v[194:197], v167 offset:52224
	ds_read_b128 v[198:201], v167 offset:53248
	ds_read_b128 v[202:205], v167 offset:54272
	ds_read_b128 v[206:209], v167 offset:55296
	ds_read_b128 v[210:213], v167 offset:56320
	global_load_lds_dwordx4 v[232:233], off
	v_lshl_add_u64 v[232:233], v[238:239], 0, s[6:7]
	s_mov_b32 m0, s34
	s_nop 0
	global_load_lds_dwordx4 v[232:233], off
	s_barrier
; #define PG8_STAGE(bufoff, gbase, voff) do { _Pragma("unroll") for (int _i = 0; _i < 2; ++_i) \
;         __builtin_amdgcn_global_load_lds((const unsigned*)((const char*)(gbase) + (voff)[_i]), (LAS unsigned*)(lds + (bufoff) + ldsw + _i * 8192), 16, 0, 0); } while (0)
; #define PG8_MMA(ai, bj, At, Bt) do { __builtin_amdgcn_s_setprio(1); _Pragma("unroll") for (int m = 0; m < 4; ++m) _Pragma("unroll") for (int n = 0; n < 2; ++n) _Pragma("unroll") for (int k = 0; k < 2; ++k) \
;         acc[ai][bj][m][n] = __builtin_amdgcn_mfma_f32_16x16x32_bf16(Bt[n][k], At[m][k], acc[ai][bj][m][n], 0, 0, 0); __builtin_amdgcn_s_setprio(0); } while (0)
; #define PG8_WAIT_V(n) asm volatile("s_waitcnt vmcnt(" #n ")" ::: "memory")
; #define PG8_WAIT_L(n) asm volatile("s_waitcnt lgkmcnt(" #n ")" ::: "memory")
; #define PG8_BAR __builtin_amdgcn_s_barrier()
; #define PG8_SCHED __builtin_amdgcn_sched_barrier(0)
;     __device__ __forceinline__ void operator()(const f32x4 (&acc)[2][2][4][2], const Unit& u, int wr, int wc, int fr, int fq) const {
;         const int row0 = u.pm * BM + wr * 64 + fr, col0 = u.pn * BM + wc * 32 + 8 * fq;
; #pragma unroll
;         for (int ai = 0; ai < 2; ++ai)
; #pragma unroll
;             for (int m = 0; m < 4; ++m) { const int row = row0 + ai * HALF + m * 16; const float rs = rowscale ? rowscale[row] : 1.f;
; #pragma unroll
;                 for (int bj = 0; bj < 2; ++bj) f(row, col0 + bj * HALF, acc[ai][bj][m][0] * rs, acc[ai][bj][m][1] * rs); }
; template <class PT, class Epi>
; __device__ __forceinline__ void gemm_phase_once(LAS unsigned char* lds, const PT& S, const Epi& E, bool epi_on) {
;     ...
;             PG8_BAR; PG8_WAIT_L(0); PG8_MMA(1, 0, At, B0); PG8_BAR; PG8_SCHED;
;             PG8_STAGE(PG8_SB(1, 1), b3 + hstepB, voffB);
;             PG8_WAIT_V(6); PG8_BAR; PG8_MMA(1, 1, At, B1); PG8_BAR;
	s_waitcnt lgkmcnt(0)
	s_setprio 1
	s_waitcnt lgkmcnt(0)
	v_mfma_f32_16x16x32_bf16 v[64:67], v[148:151], v[182:185], v[64:67]
	v_mfma_f32_16x16x32_bf16 v[60:63], v[174:177], v[182:185], v[60:63]
	v_mfma_f32_16x16x32_bf16 v[48:51], v[148:151], v[190:193], v[48:51]
	v_mfma_f32_16x16x32_bf16 v[44:47], v[174:177], v[190:193], v[44:47]
	v_mfma_f32_16x16x32_bf16 v[32:35], v[148:151], v[198:201], v[32:35]
	v_mfma_f32_16x16x32_bf16 v[28:31], v[174:177], v[198:201], v[28:31]
	v_mfma_f32_16x16x32_bf16 v[16:19], v[148:151], v[206:209], v[16:19]
	v_mfma_f32_16x16x32_bf16 v[12:15], v[174:177], v[206:209], v[12:15]
	v_mfma_f32_16x16x32_bf16 v[64:67], v[170:173], v[186:189], v[64:67]
	v_mfma_f32_16x16x32_bf16 v[60:63], v[178:181], v[186:189], v[60:63]
	v_mfma_f32_16x16x32_bf16 v[48:51], v[170:173], v[194:197], v[48:51]
	v_mfma_f32_16x16x32_bf16 v[44:47], v[178:181], v[194:197], v[44:47]
	v_mfma_f32_16x16x32_bf16 v[32:35], v[170:173], v[202:205], v[32:35]
	v_mfma_f32_16x16x32_bf16 v[28:31], v[178:181], v[202:205], v[28:31]
	v_mfma_f32_16x16x32_bf16 v[16:19], v[170:173], v[210:213], v[16:19]
	v_mfma_f32_16x16x32_bf16 v[12:15], v[178:181], v[210:213], v[12:15]
	s_setprio 0
	s_barrier
	s_add_u32 s20, s20, 0x80080
	s_addc_u32 s21, s21, 0
	s_add_i32 s22, s22, s26
	v_lshl_add_u64 v[148:149], s[20:21], 0, v[134:135]
	s_mov_b32 m0, s22
	s_nop 0
	global_load_lds_dwordx4 v[148:149], off
	v_lshl_add_u64 v[148:149], s[20:21], 0, v[138:139]
	s_add_i32 m0, s22, 0x2000
	s_nop 0
	global_load_lds_dwordx4 v[148:149], off
	s_waitcnt vmcnt(6)
	s_barrier
	s_setprio 1
	v_mfma_f32_16x16x32_bf16 v[56:59], v[214:217], v[182:185], v[56:59]
	v_mfma_f32_16x16x32_bf16 v[52:55], v[222:225], v[182:185], v[52:55]
	v_mfma_f32_16x16x32_bf16 v[40:43], v[214:217], v[190:193], v[40:43]
	v_mfma_f32_16x16x32_bf16 v[36:39], v[222:225], v[190:193], v[36:39]
	v_mfma_f32_16x16x32_bf16 v[24:27], v[214:217], v[198:201], v[24:27]
	v_mfma_f32_16x16x32_bf16 v[20:23], v[222:225], v[198:201], v[20:23]
	v_mfma_f32_16x16x32_bf16 v[8:11], v[214:217], v[206:209], v[8:11]
	v_mfma_f32_16x16x32_bf16 v[4:7], v[222:225], v[206:209], v[4:7]
	v_mfma_f32_16x16x32_bf16 v[56:59], v[218:221], v[186:189], v[56:59]
	v_mfma_f32_16x16x32_bf16 v[52:55], v[226:229], v[186:189], v[52:55]
	v_mfma_f32_16x16x32_bf16 v[40:43], v[218:221], v[194:197], v[40:43]
	v_mfma_f32_16x16x32_bf16 v[36:39], v[226:229], v[194:197], v[36:39]
	v_mfma_f32_16x16x32_bf16 v[24:27], v[218:221], v[202:205], v[24:27]
	v_mfma_f32_16x16x32_bf16 v[20:23], v[226:229], v[202:205], v[20:23]
	v_mfma_f32_16x16x32_bf16 v[8:11], v[218:221], v[210:213], v[8:11]
	v_mfma_f32_16x16x32_bf16 v[4:7], v[226:229], v[210:213], v[4:7]
	s_setprio 0
	s_add_i32 s43, s43, 2
	s_add_u32 s18, s18, 0x100
	s_addc_u32 s19, s19, 0
	s_add_u32 s41, s41, 0x100
	s_addc_u32 s42, s42, 0
	s_cmp_lt_u32 s43, 30
	s_barrier
	s_cbranch_scc1 .LBB0_3884
	v_lshl_add_u32 v150, s16, 8, v160
	v_ashrrev_i32_e32 v151, 31, v150
	v_lshl_add_u64 v[148:149], v[150:151], 2, s[90:91]
	global_load_dword v166, v[148:149], off
	global_load_dword v165, v[148:149], off offset:64
	global_load_dword v169, v[148:149], off offset:128
	global_load_dword v172, v[148:149], off offset:192
	global_load_dword v173, v[148:149], off offset:512
	global_load_dword v174, v[148:149], off offset:576
	global_load_dword v175, v[148:149], off offset:640
	global_load_dword v176, v[148:149], off offset:704
	v_lshl_or_b32 v170, s38, 8, v162
	v_readlane_b32 s18, v254, 44
	v_readlane_b32 s19, v254, 45
	v_ashrrev_i32_e32 v171, 31, v170
	s_mov_b32 s9, 0x20000
	s_mov_b32 s38, s8
	s_mov_b32 s16, s10
	s_mov_b64 s[20:21], s[14:15]
	s_waitcnt vmcnt(0)
	v_pk_mul_f32 v[130:131], v[130:131], v[166:167] op_sel_hi:[1,0]
	v_pk_mul_f32 v[128:129], v[128:129], v[166:167] op_sel_hi:[1,0]
	v_pk_mul_f32 v[124:125], v[124:125], v[166:167] op_sel_hi:[1,0]
	v_pk_mul_f32 v[126:127], v[126:127], v[166:167] op_sel_hi:[1,0]
	v_cvt_pk_bf16_f32 v128, v128, v129
	v_cvt_pk_bf16_f32 v129, v130, v131
	v_cvt_pk_bf16_f32 v130, v124, v125
	v_lshlrev_b64 v[124:125], 10, v[150:151]
	v_cvt_pk_bf16_f32 v131, v126, v127
	v_lshl_add_u64 v[124:125], s[18:19], 0, v[124:125]
	v_lshlrev_b64 v[126:127], 1, v[170:171]
	v_lshl_add_u64 v[124:125], v[124:125], 0, v[126:127]
	global_store_dwordx4 v[124:125], v[128:131], off
	v_pk_mul_f32 v[120:121], v[120:121], v[166:167] op_sel_hi:[1,0]
	v_pk_mul_f32 v[122:123], v[122:123], v[166:167] op_sel_hi:[1,0]
	v_pk_mul_f32 v[128:129], v[118:119], v[166:167] op_sel_hi:[1,0]
	v_pk_mul_f32 v[118:119], v[116:117], v[166:167] op_sel_hi:[1,0]
	v_cvt_pk_bf16_f32 v116, v120, v121
	v_cvt_pk_bf16_f32 v117, v122, v123
	s_nop 0
	v_cvt_pk_bf16_f32 v118, v118, v119
	v_cvt_pk_bf16_f32 v119, v128, v129
	global_store_dwordx4 v[124:125], v[116:119], off offset:256
	s_nop 1
	v_or_b32_e32 v116, 16, v150
	v_ashrrev_i32_e32 v117, 31, v116
	v_lshl_add_u64 v[118:119], v[116:117], 2, s[90:91]
	s_nop 1
	v_mov_b32_e32 v118, v165
	v_pk_mul_f32 v[112:113], v[112:113], v[118:119] op_sel_hi:[1,0]
	v_pk_mul_f32 v[120:121], v[110:111], v[118:119] op_sel_hi:[1,0]
	v_pk_mul_f32 v[110:111], v[108:109], v[118:119] op_sel_hi:[1,0]
	v_cvt_pk_bf16_f32 v108, v112, v113
	v_lshlrev_b64 v[112:113], 10, v[116:117]
	v_lshl_add_u64 v[112:113], s[18:19], 0, v[112:113]
	v_pk_mul_f32 v[114:115], v[114:115], v[118:119] op_sel_hi:[1,0]
	v_lshl_add_u64 v[112:113], v[112:113], 0, v[126:127]
	v_cvt_pk_bf16_f32 v109, v114, v115
	v_cvt_pk_bf16_f32 v110, v110, v111
	v_cvt_pk_bf16_f32 v111, v120, v121
	global_store_dwordx4 v[112:113], v[108:111], off
	v_pk_mul_f32 v[104:105], v[104:105], v[118:119] op_sel_hi:[1,0]
	v_pk_mul_f32 v[106:107], v[106:107], v[118:119] op_sel_hi:[1,0]
;     __device__ __forceinline__ void operator()(const f32x4 (&acc)[2][2][4][2], const Unit& u, int wr, int wc, int fr, int fq) const {
;         const int row0 = u.pm * BM + wr * 64 + fr, col0 = u.pn * BM + wc * 32 + 8 * fq;
; #pragma unroll
;         for (int ai = 0; ai < 2; ++ai)
; #pragma unroll
;             for (int m = 0; m < 4; ++m) { const int row = row0 + ai * HALF + m * 16; const float rs = rowscale ? rowscale[row] : 1.f;
; #pragma unroll
;                 for (int bj = 0; bj < 2; ++bj) f(row, col0 + bj * HALF, acc[ai][bj][m][0] * rs, acc[ai][bj][m][1] * rs); }
	v_pk_mul_f32 v[108:109], v[102:103], v[118:119] op_sel_hi:[1,0]
	v_pk_mul_f32 v[102:103], v[100:101], v[118:119] op_sel_hi:[1,0]
	v_cvt_pk_bf16_f32 v100, v104, v105
	v_cvt_pk_bf16_f32 v101, v106, v107
	s_nop 0
	v_cvt_pk_bf16_f32 v102, v102, v103
	v_cvt_pk_bf16_f32 v103, v108, v109
	global_store_dwordx4 v[112:113], v[100:103], off offset:256
	s_nop 1
	v_or_b32_e32 v100, 32, v150
	v_ashrrev_i32_e32 v101, 31, v100
	v_lshl_add_u64 v[102:103], v[100:101], 2, s[90:91]
	s_nop 1
	v_mov_b32_e32 v102, v169
	v_pk_mul_f32 v[96:97], v[96:97], v[102:103] op_sel_hi:[1,0]
	v_pk_mul_f32 v[104:105], v[94:95], v[102:103] op_sel_hi:[1,0]
	v_pk_mul_f32 v[94:95], v[92:93], v[102:103] op_sel_hi:[1,0]
	v_cvt_pk_bf16_f32 v92, v96, v97
	v_lshlrev_b64 v[96:97], 10, v[100:101]
	v_lshl_add_u64 v[96:97], s[18:19], 0, v[96:97]
	v_pk_mul_f32 v[98:99], v[98:99], v[102:103] op_sel_hi:[1,0]
	v_lshl_add_u64 v[96:97], v[96:97], 0, v[126:127]
	v_cvt_pk_bf16_f32 v93, v98, v99
	v_cvt_pk_bf16_f32 v94, v94, v95
	v_cvt_pk_bf16_f32 v95, v104, v105
	global_store_dwordx4 v[96:97], v[92:95], off
	v_pk_mul_f32 v[88:89], v[88:89], v[102:103] op_sel_hi:[1,0]
	v_pk_mul_f32 v[90:91], v[90:91], v[102:103] op_sel_hi:[1,0]
	v_pk_mul_f32 v[92:93], v[86:87], v[102:103] op_sel_hi:[1,0]
	v_pk_mul_f32 v[86:87], v[84:85], v[102:103] op_sel_hi:[1,0]
	v_cvt_pk_bf16_f32 v84, v88, v89
	v_cvt_pk_bf16_f32 v85, v90, v91
	s_nop 0
	v_cvt_pk_bf16_f32 v86, v86, v87
	v_cvt_pk_bf16_f32 v87, v92, v93
	global_store_dwordx4 v[96:97], v[84:87], off offset:256
	s_nop 1
	v_or_b32_e32 v84, 48, v150
	v_ashrrev_i32_e32 v85, 31, v84
	v_lshl_add_u64 v[86:87], v[84:85], 2, s[90:91]
	s_nop 1
	v_mov_b32_e32 v86, v172
	v_pk_mul_f32 v[80:81], v[80:81], v[86:87] op_sel_hi:[1,0]
	v_pk_mul_f32 v[88:89], v[78:79], v[86:87] op_sel_hi:[1,0]
	v_pk_mul_f32 v[78:79], v[76:77], v[86:87] op_sel_hi:[1,0]
	v_cvt_pk_bf16_f32 v76, v80, v81
	v_lshlrev_b64 v[80:81], 10, v[84:85]
	v_lshl_add_u64 v[80:81], s[18:19], 0, v[80:81]
	v_pk_mul_f32 v[82:83], v[82:83], v[86:87] op_sel_hi:[1,0]
	v_lshl_add_u64 v[80:81], v[80:81], 0, v[126:127]
	v_cvt_pk_bf16_f32 v77, v82, v83
	v_cvt_pk_bf16_f32 v78, v78, v79
	v_cvt_pk_bf16_f32 v79, v88, v89
	global_store_dwordx4 v[80:81], v[76:79], off
	v_pk_mul_f32 v[74:75], v[74:75], v[86:87] op_sel_hi:[1,0]
	v_pk_mul_f32 v[72:73], v[72:73], v[86:87] op_sel_hi:[1,0]
	v_pk_mul_f32 v[76:77], v[70:71], v[86:87] op_sel_hi:[1,0]
	v_pk_mul_f32 v[70:71], v[68:69], v[86:87] op_sel_hi:[1,0]
	v_cvt_pk_bf16_f32 v68, v72, v73
	v_cvt_pk_bf16_f32 v69, v74, v75
	s_mov_b64 s[18:19], 0x20000
	v_cvt_pk_bf16_f32 v70, v70, v71
	v_cvt_pk_bf16_f32 v71, v76, v77
	global_store_dwordx4 v[80:81], v[68:71], off offset:256
	s_nop 1
	v_mov_b32_e32 v68, v173
	v_pk_mul_f32 v[66:67], v[66:67], v[68:69] op_sel_hi:[1,0]
	v_pk_mul_f32 v[64:65], v[64:65], v[68:69] op_sel_hi:[1,0]
	v_pk_mul_f32 v[70:71], v[62:63], v[68:69] op_sel_hi:[1,0]
	v_pk_mul_f32 v[62:63], v[60:61], v[68:69] op_sel_hi:[1,0]
	v_cvt_pk_bf16_f32 v60, v64, v65
	v_cvt_pk_bf16_f32 v61, v66, v67
	v_add_co_u32_e32 v66, vcc, s9, v124
	v_cvt_pk_bf16_f32 v62, v62, v63
	v_cvt_pk_bf16_f32 v63, v70, v71
	v_lshl_add_u64 v[64:65], v[124:125], 0, s[18:19]
	s_nop 0
	v_addc_co_u32_e32 v67, vcc, 0, v125, vcc
	global_store_dwordx4 v[66:67], v[60:63], off
	v_pk_mul_f32 v[58:59], v[58:59], v[68:69] op_sel_hi:[1,0]
	v_pk_mul_f32 v[56:57], v[56:57], v[68:69] op_sel_hi:[1,0]
	v_pk_mul_f32 v[60:61], v[54:55], v[68:69] op_sel_hi:[1,0]
	v_pk_mul_f32 v[54:55], v[52:53], v[68:69] op_sel_hi:[1,0]
	v_cvt_pk_bf16_f32 v52, v56, v57
	v_cvt_pk_bf16_f32 v53, v58, v59
	s_mov_b32 s9, 0x24000
	v_cvt_pk_bf16_f32 v54, v54, v55
	v_cvt_pk_bf16_f32 v55, v60, v61
	global_store_dwordx4 v[64:65], v[52:55], off offset:256
	s_nop 1
	v_mov_b32_e32 v52, v174
	s_mov_b64 s[18:19], 0x24000
	v_pk_mul_f32 v[50:51], v[50:51], v[52:53] op_sel_hi:[1,0]
	v_pk_mul_f32 v[48:49], v[48:49], v[52:53] op_sel_hi:[1,0]
	v_pk_mul_f32 v[54:55], v[46:47], v[52:53] op_sel_hi:[1,0]
	v_pk_mul_f32 v[46:47], v[44:45], v[52:53] op_sel_hi:[1,0]
	v_cvt_pk_bf16_f32 v44, v48, v49
	v_cvt_pk_bf16_f32 v45, v50, v51
	v_add_co_u32_e32 v50, vcc, s9, v124
	v_cvt_pk_bf16_f32 v46, v46, v47
	v_cvt_pk_bf16_f32 v47, v54, v55
	v_lshl_add_u64 v[48:49], v[124:125], 0, s[18:19]
	s_nop 0
	v_addc_co_u32_e32 v51, vcc, 0, v125, vcc
	global_store_dwordx4 v[50:51], v[44:47], off
	v_pk_mul_f32 v[42:43], v[42:43], v[52:53] op_sel_hi:[1,0]
	v_pk_mul_f32 v[40:41], v[40:41], v[52:53] op_sel_hi:[1,0]
	v_pk_mul_f32 v[44:45], v[38:39], v[52:53] op_sel_hi:[1,0]
	v_pk_mul_f32 v[38:39], v[36:37], v[52:53] op_sel_hi:[1,0]
	v_cvt_pk_bf16_f32 v36, v40, v41
	v_cvt_pk_bf16_f32 v37, v42, v43
	s_mov_b32 s9, 0x28000
	v_cvt_pk_bf16_f32 v38, v38, v39
	v_cvt_pk_bf16_f32 v39, v44, v45
	global_store_dwordx4 v[48:49], v[36:39], off offset:256
	s_nop 1
	v_mov_b32_e32 v36, v175
	s_mov_b64 s[18:19], 0x28000
	v_pk_mul_f32 v[34:35], v[34:35], v[36:37] op_sel_hi:[1,0]
	v_pk_mul_f32 v[32:33], v[32:33], v[36:37] op_sel_hi:[1,0]
	v_pk_mul_f32 v[38:39], v[30:31], v[36:37] op_sel_hi:[1,0]
	v_pk_mul_f32 v[30:31], v[28:29], v[36:37] op_sel_hi:[1,0]
	v_cvt_pk_bf16_f32 v28, v32, v33
	v_cvt_pk_bf16_f32 v29, v34, v35
	v_add_co_u32_e32 v34, vcc, s9, v124
	v_cvt_pk_bf16_f32 v30, v30, v31
	v_cvt_pk_bf16_f32 v31, v38, v39
	v_lshl_add_u64 v[32:33], v[124:125], 0, s[18:19]
	s_nop 0
	v_addc_co_u32_e32 v35, vcc, 0, v125, vcc
	global_store_dwordx4 v[34:35], v[28:31], off
	v_pk_mul_f32 v[26:27], v[26:27], v[36:37] op_sel_hi:[1,0]
	v_pk_mul_f32 v[24:25], v[24:25], v[36:37] op_sel_hi:[1,0]
	v_pk_mul_f32 v[28:29], v[22:23], v[36:37] op_sel_hi:[1,0]
	v_pk_mul_f32 v[22:23], v[20:21], v[36:37] op_sel_hi:[1,0]
	v_cvt_pk_bf16_f32 v20, v24, v25
	v_cvt_pk_bf16_f32 v21, v26, v27
	s_mov_b32 s9, 0x2c000
	v_cvt_pk_bf16_f32 v22, v22, v23
	v_cvt_pk_bf16_f32 v23, v28, v29
	global_store_dwordx4 v[32:33], v[20:23], off offset:256
	s_nop 1
	v_mov_b32_e32 v20, v176
	s_mov_b64 s[18:19], 0x2c000
	v_pk_mul_f32 v[18:19], v[18:19], v[20:21] op_sel_hi:[1,0]
	v_pk_mul_f32 v[16:17], v[16:17], v[20:21] op_sel_hi:[1,0]
	v_pk_mul_f32 v[22:23], v[14:15], v[20:21] op_sel_hi:[1,0]
	v_pk_mul_f32 v[14:15], v[12:13], v[20:21] op_sel_hi:[1,0]
	v_cvt_pk_bf16_f32 v12, v16, v17
	v_cvt_pk_bf16_f32 v13, v18, v19
	v_add_co_u32_e32 v18, vcc, s9, v124
	v_cvt_pk_bf16_f32 v14, v14, v15
	v_cvt_pk_bf16_f32 v15, v22, v23
	v_lshl_add_u64 v[16:17], v[124:125], 0, s[18:19]
	s_nop 0
	v_addc_co_u32_e32 v19, vcc, 0, v125, vcc
	global_store_dwordx4 v[18:19], v[12:15], off
	s_andn2_b64 vcc, exec, s[0:1]
	s_mov_b64 s[18:19], s[12:13]
	v_pk_mul_f32 v[12:13], v[6:7], v[20:21] op_sel_hi:[1,0]
	v_pk_mul_f32 v[6:7], v[4:5], v[20:21] op_sel_hi:[1,0]
	v_pk_mul_f32 v[10:11], v[10:11], v[20:21] op_sel_hi:[1,0]
	v_pk_mul_f32 v[8:9], v[8:9], v[20:21] op_sel_hi:[1,0]
	s_nop 0
	v_cvt_pk_bf16_f32 v4, v8, v9
	v_cvt_pk_bf16_f32 v5, v10, v11
	v_cvt_pk_bf16_f32 v6, v6, v7
	v_cvt_pk_bf16_f32 v7, v12, v13
	global_store_dwordx4 v[16:17], v[4:7], off offset:256
	s_cbranch_vccnz .LBB0_3877
	s_waitcnt vmcnt(0)
	s_cmpk_gt_u32 s24, 0xff
	s_cbranch_scc1 .LBB0_3888
	s_barrier

; #define PG8_STAGE(bufoff, gbase, voff) do { _Pragma("unroll") for (int _i = 0; _i < 2; ++_i) \
;         __builtin_amdgcn_global_load_lds((const unsigned*)((const char*)(gbase) + (voff)[_i]), (LAS unsigned*)(lds + (bufoff) + ldsw + _i * 8192), 16, 0, 0); } while (0)
; #define PG8_LDA(dst, b, h) do { _Pragma("unroll") for (int m = 0; m < 4; ++m) _Pragma("unroll") for (int k = 0; k < 2; ++k) dst[m][k] = *(const LAS bf16x8*)(lds + PG8_SA(b, h) + aoff + m * 2048 + k * 1024); } while (0)
; #define PG8_LDB(dst, b, h) do { _Pragma("unroll") for (int n = 0; n < 2; ++n) _Pragma("unroll") for (int k = 0; k < 2; ++k) dst[n][k] = *(const LAS bf16x8*)(lds + PG8_SB(b, h) + boff + n * 2048 + k * 1024); } while (0)
; #define PG8_MMA(ai, bj, At, Bt) do { __builtin_amdgcn_s_setprio(1); _Pragma("unroll") for (int m = 0; m < 4; ++m) _Pragma("unroll") for (int n = 0; n < 2; ++n) _Pragma("unroll") for (int k = 0; k < 2; ++k) \
;         acc[ai][bj][m][n] = __builtin_amdgcn_mfma_f32_16x16x32_bf16(Bt[n][k], At[m][k], acc[ai][bj][m][n], 0, 0, 0); __builtin_amdgcn_s_setprio(0); } while (0)
; #define PG8_WAIT_L(n) asm volatile("s_waitcnt lgkmcnt(" #n ")" ::: "memory")
; #define PG8_BAR __builtin_amdgcn_s_barrier()
; #define PG8_SCHED __builtin_amdgcn_sched_barrier(0)
; template <class PT, class Epi>
; __device__ __forceinline__ void gemm_phase_once(LAS unsigned char* lds, const PT& S, const Epi& E, bool epi_on) {
;     ...
;             PG8_LDB(B0, 0, 0); PG8_SCHED; PG8_LDA(At, 0, 0); PG8_STAGE(PG8_SA(1, 1), a1 + hstepA, voffA);
;             PG8_WAIT_L(8); PG8_BAR; PG8_WAIT_L(0); PG8_MMA(0, 0, At, B0); PG8_BAR; PG8_SCHED;
;             PG8_LDB(B1, 0, 1); PG8_STAGE(PG8_SB(0, 0), b2, voffB);
;             PG8_BAR; PG8_WAIT_L(0); PG8_MMA(0, 1, At, B1); PG8_BAR;
;             PG8_LDA(At, 0, 1); PG8_STAGE(PG8_SA(0, 0), a2, voffA);
;             PG8_BAR; PG8_WAIT_L(0); PG8_MMA(1, 0, At, B0); PG8_BAR; PG8_SCHED;
.LBB0_4818:
	ds_read_b128 v[140:143], v150
	ds_read_b128 v[144:147], v150 offset:1024
	ds_read_b128 v[154:157], v150 offset:2048
	ds_read_b128 v[158:161], v150 offset:3072
	s_add_u32 s16, s14, 0xfff80080
	s_addc_u32 s17, s15, -1
	s_cmp_eq_u32 s40, 28
	s_cselect_b32 s19, s13, s17
	s_cselect_b32 s18, s35, s16
	s_cselect_b32 s17, s36, s39
	s_cselect_b32 s16, s37, s38
	v_lshl_add_u64 v[162:163], s[14:15], 0, v[136:137]
	s_add_i32 m0, s22, 0xc000
	ds_read_b128 v[166:169], v151
	ds_read_b128 v[170:173], v151 offset:1024
	ds_read_b128 v[174:177], v151 offset:2048
	ds_read_b128 v[178:181], v151 offset:3072
	ds_read_b128 v[182:185], v151 offset:4096
	ds_read_b128 v[186:189], v151 offset:5120
	ds_read_b128 v[190:193], v151 offset:6144
	ds_read_b128 v[194:197], v151 offset:7168
	global_load_lds_dwordx4 v[162:163], off
	v_lshl_add_u64 v[162:163], s[14:15], 0, v[138:139]
	s_add_i32 m0, s22, 0xe000
	s_nop 0
	global_load_lds_dwordx4 v[162:163], off
	s_waitcnt lgkmcnt(8)
	s_barrier
	s_waitcnt lgkmcnt(0)
	s_setprio 1
	s_waitcnt lgkmcnt(0)
	v_mfma_f32_16x16x32_bf16 v[128:131], v[140:143], v[166:169], v[128:131]
	v_mfma_f32_16x16x32_bf16 v[124:127], v[154:157], v[166:169], v[124:127]
	v_mfma_f32_16x16x32_bf16 v[112:115], v[140:143], v[174:177], v[112:115]
	v_mfma_f32_16x16x32_bf16 v[108:111], v[154:157], v[174:177], v[108:111]
	v_mfma_f32_16x16x32_bf16 v[96:99], v[140:143], v[182:185], v[96:99]
	v_mfma_f32_16x16x32_bf16 v[92:95], v[154:157], v[182:185], v[92:95]
	v_mfma_f32_16x16x32_bf16 v[80:83], v[140:143], v[190:193], v[80:83]
	v_mfma_f32_16x16x32_bf16 v[76:79], v[154:157], v[190:193], v[76:79]
	v_mfma_f32_16x16x32_bf16 v[128:131], v[144:147], v[170:173], v[128:131]
	v_mfma_f32_16x16x32_bf16 v[124:127], v[158:161], v[170:173], v[124:127]
	v_mfma_f32_16x16x32_bf16 v[112:115], v[144:147], v[178:181], v[112:115]
	v_mfma_f32_16x16x32_bf16 v[108:111], v[158:161], v[178:181], v[108:111]
	v_mfma_f32_16x16x32_bf16 v[96:99], v[144:147], v[186:189], v[96:99]
	v_mfma_f32_16x16x32_bf16 v[92:95], v[158:161], v[186:189], v[92:95]
	v_mfma_f32_16x16x32_bf16 v[80:83], v[144:147], v[194:197], v[80:83]
	v_mfma_f32_16x16x32_bf16 v[76:79], v[158:161], v[194:197], v[76:79]
	s_setprio 0
	s_barrier
	s_add_i32 s41, s30, s21
	v_lshl_add_u64 v[162:163], s[16:17], 0, v[132:133]
	s_mov_b32 m0, s41
	ds_read_b128 v[198:201], v152
	ds_read_b128 v[202:205], v152 offset:1024
	ds_read_b128 v[206:209], v152 offset:2048
	ds_read_b128 v[210:213], v152 offset:3072
	global_load_lds_dwordx4 v[162:163], off
	v_lshl_add_u64 v[214:215], s[16:17], 0, v[134:135]
	s_add_i32 m0, s41, 0x2000
	s_nop 0
	global_load_lds_dwordx4 v[214:215], off
	s_barrier
	s_waitcnt lgkmcnt(0)
	s_setprio 1
	s_waitcnt lgkmcnt(0)
	v_mfma_f32_16x16x32_bf16 v[120:123], v[198:201], v[166:169], v[120:123]
	v_mfma_f32_16x16x32_bf16 v[116:119], v[206:209], v[166:169], v[116:119]
	v_mfma_f32_16x16x32_bf16 v[104:107], v[198:201], v[174:177], v[104:107]
	v_mfma_f32_16x16x32_bf16 v[100:103], v[206:209], v[174:177], v[100:103]
	v_mfma_f32_16x16x32_bf16 v[88:91], v[198:201], v[182:185], v[88:91]
	v_mfma_f32_16x16x32_bf16 v[84:87], v[206:209], v[182:185], v[84:87]
	v_mfma_f32_16x16x32_bf16 v[72:75], v[198:201], v[190:193], v[72:75]
	v_mfma_f32_16x16x32_bf16 v[68:71], v[206:209], v[190:193], v[68:71]
	v_mfma_f32_16x16x32_bf16 v[120:123], v[202:205], v[170:173], v[120:123]
	v_mfma_f32_16x16x32_bf16 v[116:119], v[210:213], v[170:173], v[116:119]
	v_mfma_f32_16x16x32_bf16 v[104:107], v[202:205], v[178:181], v[104:107]
	v_mfma_f32_16x16x32_bf16 v[100:103], v[210:213], v[178:181], v[100:103]
	v_mfma_f32_16x16x32_bf16 v[88:91], v[202:205], v[186:189], v[88:91]
	v_mfma_f32_16x16x32_bf16 v[84:87], v[210:213], v[186:189], v[84:87]
	v_mfma_f32_16x16x32_bf16 v[72:75], v[202:205], v[194:197], v[72:75]
	v_mfma_f32_16x16x32_bf16 v[68:71], v[210:213], v[194:197], v[68:71]
	s_setprio 0
	s_mov_b32 m0, s22
	v_lshl_add_u64 v[216:217], s[18:19], 0, v[132:133]
	s_barrier
	ds_read_b128 v[166:169], v151 offset:16384
	ds_read_b128 v[170:173], v151 offset:17408
	ds_read_b128 v[174:177], v151 offset:18432
	ds_read_b128 v[178:181], v151 offset:19456
	ds_read_b128 v[182:185], v151 offset:20480
	ds_read_b128 v[186:189], v151 offset:21504
	ds_read_b128 v[190:193], v151 offset:22528
	ds_read_b128 v[194:197], v151 offset:23552
	global_load_lds_dwordx4 v[216:217], off
	v_lshl_add_u64 v[218:219], s[18:19], 0, v[134:135]
	s_mov_b32 m0, s23
	s_nop 0
	global_load_lds_dwordx4 v[218:219], off
	s_barrier
	s_waitcnt lgkmcnt(0)
	s_setprio 1
	s_waitcnt lgkmcnt(0)
	v_mfma_f32_16x16x32_bf16 v[64:67], v[140:143], v[166:169], v[64:67]
	v_mfma_f32_16x16x32_bf16 v[60:63], v[154:157], v[166:169], v[60:63]
	v_mfma_f32_16x16x32_bf16 v[48:51], v[140:143], v[174:177], v[48:51]
	v_mfma_f32_16x16x32_bf16 v[44:47], v[154:157], v[174:177], v[44:47]
	v_mfma_f32_16x16x32_bf16 v[32:35], v[140:143], v[182:185], v[32:35]
	v_mfma_f32_16x16x32_bf16 v[28:31], v[154:157], v[182:185], v[28:31]
	v_mfma_f32_16x16x32_bf16 v[16:19], v[140:143], v[190:193], v[16:19]
	v_mfma_f32_16x16x32_bf16 v[12:15], v[154:157], v[190:193], v[12:15]
	v_mfma_f32_16x16x32_bf16 v[64:67], v[144:147], v[170:173], v[64:67]
	v_mfma_f32_16x16x32_bf16 v[60:63], v[158:161], v[170:173], v[60:63]
	v_mfma_f32_16x16x32_bf16 v[48:51], v[144:147], v[178:181], v[48:51]
	v_mfma_f32_16x16x32_bf16 v[44:47], v[158:161], v[178:181], v[44:47]
	v_mfma_f32_16x16x32_bf16 v[32:35], v[144:147], v[186:189], v[32:35]
	v_mfma_f32_16x16x32_bf16 v[28:31], v[158:161], v[186:189], v[28:31]
	v_mfma_f32_16x16x32_bf16 v[16:19], v[144:147], v[194:197], v[16:19]
	v_mfma_f32_16x16x32_bf16 v[12:15], v[158:161], v[194:197], v[12:15]
	s_setprio 0
	s_barrier
; #define PG8_STAGE(bufoff, gbase, voff) do { _Pragma("unroll") for (int _i = 0; _i < 2; ++_i) \
;         __builtin_amdgcn_global_load_lds((const unsigned*)((const char*)(gbase) + (voff)[_i]), (LAS unsigned*)(lds + (bufoff) + ldsw + _i * 8192), 16, 0, 0); } while (0)
; #define PG8_LDA(dst, b, h) do { _Pragma("unroll") for (int m = 0; m < 4; ++m) _Pragma("unroll") for (int k = 0; k < 2; ++k) dst[m][k] = *(const LAS bf16x8*)(lds + PG8_SA(b, h) + aoff + m * 2048 + k * 1024); } while (0)
; #define PG8_LDB(dst, b, h) do { _Pragma("unroll") for (int n = 0; n < 2; ++n) _Pragma("unroll") for (int k = 0; k < 2; ++k) dst[n][k] = *(const LAS bf16x8*)(lds + PG8_SB(b, h) + boff + n * 2048 + k * 1024); } while (0)
; #define PG8_WAIT_V(n) asm volatile("s_waitcnt vmcnt(" #n ")" ::: "memory")
; #define PG8_WAIT_L(n) asm volatile("s_waitcnt lgkmcnt(" #n ")" ::: "memory")
; #define PG8_BAR __builtin_amdgcn_s_barrier()
; #define PG8_SCHED __builtin_amdgcn_sched_barrier(0)
; template <class PT, class Epi>
; __device__ __forceinline__ void gemm_phase_once(LAS unsigned char* lds, const PT& S, const Epi& E, bool epi_on) {
;     ...
;             PG8_LDB(B0, 0, 0); PG8_SCHED; PG8_LDA(At, 0, 0); PG8_STAGE(PG8_SA(1, 1), a1 + hstepA, voffA);
;             PG8_WAIT_L(8); PG8_BAR; PG8_WAIT_L(0); PG8_MMA(0, 0, At, B0); PG8_BAR; PG8_SCHED;
;             PG8_LDB(B1, 0, 1); PG8_STAGE(PG8_SB(0, 0), b2, voffB);
;             PG8_BAR; PG8_WAIT_L(0); PG8_MMA(0, 1, At, B1); PG8_BAR;
;             PG8_LDA(At, 0, 1); PG8_STAGE(PG8_SA(0, 0), a2, voffA);
;             PG8_BAR; PG8_WAIT_L(0); PG8_MMA(1, 0, At, B0); PG8_BAR; PG8_SCHED;
;             PG8_STAGE(PG8_SB(0, 1), b2 + hstepB, voffB);
;             PG8_WAIT_V(6); PG8_BAR; PG8_MMA(1, 1, At, B1); PG8_BAR;
;             PG8_LDB(B0, 1, 0); PG8_SCHED; PG8_LDA(At, 1, 0); PG8_STAGE(PG8_SA(0, 1), a2 + hstepA, voffA);
;             PG8_WAIT_L(8); PG8_BAR; PG8_WAIT_L(0); PG8_MMA(0, 0, At, B0); PG8_BAR; PG8_SCHED;
;             PG8_LDB(B1, 1, 1); PG8_STAGE(PG8_SB(1, 0), b3, voffB);
;             PG8_BAR; PG8_WAIT_L(0); PG8_MMA(0, 1, At, B1); PG8_BAR;
;             PG8_LDA(At, 1, 1); PG8_STAGE(PG8_SA(1, 0), a3, voffA);
;             PG8_BAR; PG8_WAIT_L(0); PG8_MMA(1, 0, At, B0); PG8_BAR; PG8_SCHED;
;             PG8_STAGE(PG8_SB(1, 1), b3 + hstepB, voffB);
;             PG8_WAIT_V(6); PG8_BAR; PG8_MMA(1, 1, At, B1); PG8_BAR;
	s_add_u32 s42, s16, 0x80000
	s_addc_u32 s43, s17, 0
	s_add_i32 s41, s31, s21
	v_lshl_add_u64 v[140:141], s[42:43], 0, v[132:133]
	s_mov_b32 m0, s41
	s_nop 0
	global_load_lds_dwordx4 v[140:141], off
	v_lshl_add_u64 v[140:141], s[42:43], 0, v[134:135]
	s_add_i32 m0, s41, 0x2000
	s_nop 0
	global_load_lds_dwordx4 v[140:141], off
	s_waitcnt vmcnt(6)
	s_barrier
	s_setprio 1
	v_mfma_f32_16x16x32_bf16 v[56:59], v[198:201], v[166:169], v[56:59]
	v_mfma_f32_16x16x32_bf16 v[52:55], v[206:209], v[166:169], v[52:55]
	v_mfma_f32_16x16x32_bf16 v[40:43], v[198:201], v[174:177], v[40:43]
	v_mfma_f32_16x16x32_bf16 v[36:39], v[206:209], v[174:177], v[36:39]
	v_mfma_f32_16x16x32_bf16 v[24:27], v[198:201], v[182:185], v[24:27]
	v_mfma_f32_16x16x32_bf16 v[20:23], v[206:209], v[182:185], v[20:23]
	v_mfma_f32_16x16x32_bf16 v[8:11], v[198:201], v[190:193], v[8:11]
	v_mfma_f32_16x16x32_bf16 v[4:7], v[206:209], v[190:193], v[4:7]
	v_mfma_f32_16x16x32_bf16 v[56:59], v[202:205], v[170:173], v[56:59]
	v_mfma_f32_16x16x32_bf16 v[52:55], v[210:213], v[170:173], v[52:55]
	v_mfma_f32_16x16x32_bf16 v[40:43], v[202:205], v[178:181], v[40:43]
	v_mfma_f32_16x16x32_bf16 v[36:39], v[210:213], v[178:181], v[36:39]
	v_mfma_f32_16x16x32_bf16 v[24:27], v[202:205], v[186:189], v[24:27]
	v_mfma_f32_16x16x32_bf16 v[20:23], v[210:213], v[186:189], v[20:23]
	v_mfma_f32_16x16x32_bf16 v[8:11], v[202:205], v[194:197], v[8:11]
	v_mfma_f32_16x16x32_bf16 v[4:7], v[210:213], v[194:197], v[4:7]
	s_setprio 0
	s_add_i32 s41, 0, 0x18000
	v_add_u32_e32 v153, s41, v148
	s_barrier
	ds_read_b128 v[140:143], v153
	ds_read_b128 v[144:147], v153 offset:1024
	ds_read_b128 v[154:157], v153 offset:2048
	ds_read_b128 v[158:161], v153 offset:3072
	s_add_u32 s18, s18, 0x80000
	s_addc_u32 s19, s19, 0
	s_mov_b32 m0, s24
	v_lshl_add_u64 v[198:199], s[18:19], 0, v[132:133]
	ds_read_b128 v[166:169], v151 offset:32768
	ds_read_b128 v[170:173], v151 offset:33792
	ds_read_b128 v[174:177], v151 offset:34816
	ds_read_b128 v[178:181], v151 offset:35840
	ds_read_b128 v[182:185], v151 offset:36864
	ds_read_b128 v[186:189], v151 offset:37888
	ds_read_b128 v[190:193], v151 offset:38912
	ds_read_b128 v[194:197], v151 offset:39936
	global_load_lds_dwordx4 v[198:199], off
	v_lshl_add_u64 v[198:199], s[18:19], 0, v[134:135]
	s_mov_b32 m0, s25
	s_nop 0
	global_load_lds_dwordx4 v[198:199], off
	s_waitcnt lgkmcnt(8)
	s_barrier
	s_waitcnt lgkmcnt(0)
	s_setprio 1
	s_waitcnt lgkmcnt(0)
	v_mfma_f32_16x16x32_bf16 v[128:131], v[140:143], v[166:169], v[128:131]
	v_mfma_f32_16x16x32_bf16 v[124:127], v[154:157], v[166:169], v[124:127]
	v_mfma_f32_16x16x32_bf16 v[112:115], v[140:143], v[174:177], v[112:115]
	v_mfma_f32_16x16x32_bf16 v[108:111], v[154:157], v[174:177], v[108:111]
	v_mfma_f32_16x16x32_bf16 v[96:99], v[140:143], v[182:185], v[96:99]
	v_mfma_f32_16x16x32_bf16 v[92:95], v[154:157], v[182:185], v[92:95]
	v_mfma_f32_16x16x32_bf16 v[80:83], v[140:143], v[190:193], v[80:83]
	v_mfma_f32_16x16x32_bf16 v[76:79], v[154:157], v[190:193], v[76:79]
	v_mfma_f32_16x16x32_bf16 v[128:131], v[144:147], v[170:173], v[128:131]
	v_mfma_f32_16x16x32_bf16 v[124:127], v[158:161], v[170:173], v[124:127]
	v_mfma_f32_16x16x32_bf16 v[112:115], v[144:147], v[178:181], v[112:115]
	v_mfma_f32_16x16x32_bf16 v[108:111], v[158:161], v[178:181], v[108:111]
	v_mfma_f32_16x16x32_bf16 v[96:99], v[144:147], v[186:189], v[96:99]
	v_mfma_f32_16x16x32_bf16 v[92:95], v[158:161], v[186:189], v[92:95]
	v_mfma_f32_16x16x32_bf16 v[80:83], v[144:147], v[194:197], v[80:83]
	v_mfma_f32_16x16x32_bf16 v[76:79], v[158:161], v[194:197], v[76:79]
	s_setprio 0
	s_barrier
	s_add_i32 s18, 0, 0x1c000
	s_add_i32 s19, s41, s21
	v_add_u32_e32 v153, s18, v148
	v_lshl_add_u64 v[162:163], v[162:163], 0, s[10:11]
	s_mov_b32 m0, s19
	ds_read_b128 v[198:201], v153
	ds_read_b128 v[202:205], v153 offset:1024
	ds_read_b128 v[206:209], v153 offset:2048
	ds_read_b128 v[210:213], v153 offset:3072
	global_load_lds_dwordx4 v[162:163], off
	v_lshl_add_u64 v[162:163], v[214:215], 0, s[10:11]
	s_add_i32 m0, s19, 0x2000
	s_nop 0
	global_load_lds_dwordx4 v[162:163], off
	s_barrier
	s_waitcnt lgkmcnt(0)
	s_setprio 1
	s_waitcnt lgkmcnt(0)
	v_mfma_f32_16x16x32_bf16 v[120:123], v[198:201], v[166:169], v[120:123]
	v_mfma_f32_16x16x32_bf16 v[116:119], v[206:209], v[166:169], v[116:119]
	v_mfma_f32_16x16x32_bf16 v[104:107], v[198:201], v[174:177], v[104:107]
	v_mfma_f32_16x16x32_bf16 v[100:103], v[206:209], v[174:177], v[100:103]
	v_mfma_f32_16x16x32_bf16 v[88:91], v[198:201], v[182:185], v[88:91]
	v_mfma_f32_16x16x32_bf16 v[84:87], v[206:209], v[182:185], v[84:87]
	v_mfma_f32_16x16x32_bf16 v[72:75], v[198:201], v[190:193], v[72:75]
	v_mfma_f32_16x16x32_bf16 v[68:71], v[206:209], v[190:193], v[68:71]
	v_mfma_f32_16x16x32_bf16 v[120:123], v[202:205], v[170:173], v[120:123]
	v_mfma_f32_16x16x32_bf16 v[116:119], v[210:213], v[170:173], v[116:119]
	v_mfma_f32_16x16x32_bf16 v[104:107], v[202:205], v[178:181], v[104:107]
	v_mfma_f32_16x16x32_bf16 v[100:103], v[210:213], v[178:181], v[100:103]
	v_mfma_f32_16x16x32_bf16 v[88:91], v[202:205], v[186:189], v[88:91]
	v_mfma_f32_16x16x32_bf16 v[84:87], v[210:213], v[186:189], v[84:87]
	v_mfma_f32_16x16x32_bf16 v[72:75], v[202:205], v[194:197], v[72:75]
	v_mfma_f32_16x16x32_bf16 v[68:71], v[210:213], v[194:197], v[68:71]
	s_setprio 0
	s_mov_b32 m0, s26
	v_lshl_add_u64 v[162:163], v[216:217], 0, s[10:11]
	s_barrier
	ds_read_b128 v[166:169], v151 offset:49152
	ds_read_b128 v[170:173], v151 offset:50176
	ds_read_b128 v[174:177], v151 offset:51200
	ds_read_b128 v[178:181], v151 offset:52224
	ds_read_b128 v[182:185], v151 offset:53248
	ds_read_b128 v[186:189], v151 offset:54272
	ds_read_b128 v[190:193], v151 offset:55296
	ds_read_b128 v[194:197], v151 offset:56320
	global_load_lds_dwordx4 v[162:163], off
	v_lshl_add_u64 v[162:163], v[218:219], 0, s[10:11]
	s_mov_b32 m0, s27
	s_nop 0
	global_load_lds_dwordx4 v[162:163], off
	s_barrier
; #define PG8_STAGE(bufoff, gbase, voff) do { _Pragma("unroll") for (int _i = 0; _i < 2; ++_i) \
;         __builtin_amdgcn_global_load_lds((const unsigned*)((const char*)(gbase) + (voff)[_i]), (LAS unsigned*)(lds + (bufoff) + ldsw + _i * 8192), 16, 0, 0); } while (0)
; #define PG8_LDA(dst, b, h) do { _Pragma("unroll") for (int m = 0; m < 4; ++m) _Pragma("unroll") for (int k = 0; k < 2; ++k) dst[m][k] = *(const LAS bf16x8*)(lds + PG8_SA(b, h) + aoff + m * 2048 + k * 1024); } while (0)
; #define PG8_LDB(dst, b, h) do { _Pragma("unroll") for (int n = 0; n < 2; ++n) _Pragma("unroll") for (int k = 0; k < 2; ++k) dst[n][k] = *(const LAS bf16x8*)(lds + PG8_SB(b, h) + boff + n * 2048 + k * 1024); } while (0)
; #define PG8_WAIT_V(n) asm volatile("s_waitcnt vmcnt(" #n ")" ::: "memory")
; #define PG8_WAIT_L(n) asm volatile("s_waitcnt lgkmcnt(" #n ")" ::: "memory")
; #define PG8_BAR __builtin_amdgcn_s_barrier()
;     __device__ __forceinline__ void operator()(const f32x4 (&acc)[2][2][4][2], const Unit& u, int wr, int wc, int fr, int fq) const {
;         const int row0 = u.pm * BM + wr * 64 + fr, col0 = u.pn * BM + wc * 32 + 4 * fq;
; #pragma unroll
;         for (int ai = 0; ai < 2; ++ai)
; #pragma unroll
;             for (int m = 0; m < 4; ++m) { const int row = row0 + ai * HALF + m * 16; const float rs = rowscale ? rowscale[row] : 1.f;
; #pragma unroll
;                 for (int bj = 0; bj < 2; ++bj)
; #pragma unroll
;                     for (int n = 0; n < 2; ++n) f(row, col0 + bj * HALF + n * 16, acc[ai][bj][m][n] * rs); }
; template <class PT, class Epi>
; __device__ __forceinline__ void gemm_phase_once(LAS unsigned char* lds, const PT& S, const Epi& E, bool epi_on) {
;     ...
;             PG8_WAIT_V(6); PG8_BAR; PG8_MMA(1, 1, At, B1); PG8_BAR;
;             PG8_LDB(B0, 1, 0); PG8_SCHED; PG8_LDA(At, 1, 0); PG8_STAGE(PG8_SA(0, 1), a2 + hstepA, voffA);
;             PG8_WAIT_L(8); PG8_BAR; PG8_WAIT_L(0); PG8_MMA(0, 0, At, B0); PG8_BAR; PG8_SCHED;
;             PG8_LDB(B1, 1, 1); PG8_STAGE(PG8_SB(1, 0), b3, voffB);
;             PG8_BAR; PG8_WAIT_L(0); PG8_MMA(0, 1, At, B1); PG8_BAR;
;             PG8_LDA(At, 1, 1); PG8_STAGE(PG8_SA(1, 0), a3, voffA);
;             PG8_BAR; PG8_WAIT_L(0); PG8_MMA(1, 0, At, B0); PG8_BAR; PG8_SCHED;
;             PG8_STAGE(PG8_SB(1, 1), b3 + hstepB, voffB);
;             PG8_WAIT_V(6); PG8_BAR; PG8_MMA(1, 1, At, B1); PG8_BAR;
	s_waitcnt lgkmcnt(0)
	s_setprio 1
	s_waitcnt lgkmcnt(0)
	v_mfma_f32_16x16x32_bf16 v[64:67], v[140:143], v[166:169], v[64:67]
	v_mfma_f32_16x16x32_bf16 v[60:63], v[154:157], v[166:169], v[60:63]
	v_mfma_f32_16x16x32_bf16 v[48:51], v[140:143], v[174:177], v[48:51]
	v_mfma_f32_16x16x32_bf16 v[44:47], v[154:157], v[174:177], v[44:47]
	v_mfma_f32_16x16x32_bf16 v[32:35], v[140:143], v[182:185], v[32:35]
	v_mfma_f32_16x16x32_bf16 v[28:31], v[154:157], v[182:185], v[28:31]
	v_mfma_f32_16x16x32_bf16 v[16:19], v[140:143], v[190:193], v[16:19]
	v_mfma_f32_16x16x32_bf16 v[12:15], v[154:157], v[190:193], v[12:15]
	v_mfma_f32_16x16x32_bf16 v[64:67], v[144:147], v[170:173], v[64:67]
	v_mfma_f32_16x16x32_bf16 v[60:63], v[158:161], v[170:173], v[60:63]
	v_mfma_f32_16x16x32_bf16 v[48:51], v[144:147], v[178:181], v[48:51]
	v_mfma_f32_16x16x32_bf16 v[44:47], v[158:161], v[178:181], v[44:47]
	v_mfma_f32_16x16x32_bf16 v[32:35], v[144:147], v[186:189], v[32:35]
	v_mfma_f32_16x16x32_bf16 v[28:31], v[158:161], v[186:189], v[28:31]
	v_mfma_f32_16x16x32_bf16 v[16:19], v[144:147], v[194:197], v[16:19]
	v_mfma_f32_16x16x32_bf16 v[12:15], v[158:161], v[194:197], v[12:15]
	s_setprio 0
	s_barrier
	s_add_u32 s16, s16, 0x80080
	s_addc_u32 s17, s17, 0
	s_add_i32 s18, s18, s21
	v_lshl_add_u64 v[140:141], s[16:17], 0, v[132:133]
	s_mov_b32 m0, s18
	s_nop 0
	global_load_lds_dwordx4 v[140:141], off
	v_lshl_add_u64 v[140:141], s[16:17], 0, v[134:135]
	s_add_i32 m0, s18, 0x2000
	s_nop 0
	global_load_lds_dwordx4 v[140:141], off
	s_waitcnt vmcnt(6)
	s_barrier
	s_setprio 1
	v_mfma_f32_16x16x32_bf16 v[56:59], v[198:201], v[166:169], v[56:59]
	v_mfma_f32_16x16x32_bf16 v[52:55], v[206:209], v[166:169], v[52:55]
	v_mfma_f32_16x16x32_bf16 v[40:43], v[198:201], v[174:177], v[40:43]
	v_mfma_f32_16x16x32_bf16 v[36:39], v[206:209], v[174:177], v[36:39]
	v_mfma_f32_16x16x32_bf16 v[24:27], v[198:201], v[182:185], v[24:27]
	v_mfma_f32_16x16x32_bf16 v[20:23], v[206:209], v[182:185], v[20:23]
	v_mfma_f32_16x16x32_bf16 v[8:11], v[198:201], v[190:193], v[8:11]
	v_mfma_f32_16x16x32_bf16 v[4:7], v[206:209], v[190:193], v[4:7]
	v_mfma_f32_16x16x32_bf16 v[56:59], v[202:205], v[170:173], v[56:59]
	v_mfma_f32_16x16x32_bf16 v[52:55], v[210:213], v[170:173], v[52:55]
	v_mfma_f32_16x16x32_bf16 v[40:43], v[202:205], v[178:181], v[40:43]
	v_mfma_f32_16x16x32_bf16 v[36:39], v[210:213], v[178:181], v[36:39]
	v_mfma_f32_16x16x32_bf16 v[24:27], v[202:205], v[186:189], v[24:27]
	v_mfma_f32_16x16x32_bf16 v[20:23], v[210:213], v[186:189], v[20:23]
	v_mfma_f32_16x16x32_bf16 v[8:11], v[202:205], v[194:197], v[8:11]
	v_mfma_f32_16x16x32_bf16 v[4:7], v[210:213], v[194:197], v[4:7]
	s_setprio 0
	s_add_i32 s40, s40, 2
	s_add_u32 s14, s14, 0x100
	s_addc_u32 s15, s15, 0
	s_add_u32 s38, s38, 0x100
	s_addc_u32 s39, s39, 0
	s_cmp_lt_u32 s40, 30
	s_barrier
	s_cbranch_scc1 .LBB0_4818
	v_lshl_add_u32 v144, s12, 8, v3
	v_ashrrev_i32_e32 v145, 31, v144
	v_lshl_add_u64 v[140:141], v[144:145], 2, s[90:91]
	global_load_dword v154, v[140:141], off
	global_load_dword v153, v[140:141], off offset:64
	global_load_dword v160, v[140:141], off offset:128
	global_load_dword v161, v[140:141], off offset:192
	global_load_dword v162, v[140:141], off offset:512
	global_load_dword v163, v[140:141], off offset:576
	global_load_dword v165, v[140:141], off offset:640
	global_load_dword v166, v[140:141], off offset:704
	v_lshl_or_b32 v142, s34, 8, v149
	v_readlane_b32 s12, v254, 10
	v_ashrrev_i32_e32 v143, 31, v142
	v_lshlrev_b64 v[158:159], 13, v[144:145]
	v_readlane_b32 s13, v254, 11
	v_or_b32_e32 v156, 16, v144
	v_lshlrev_b64 v[146:147], 2, v[142:143]
	v_lshl_add_u64 v[142:143], s[12:13], 0, v[158:159]
	v_ashrrev_i32_e32 v157, 31, v156
	v_lshl_add_u64 v[142:143], v[142:143], 0, v[146:147]
	v_lshl_add_u64 v[158:159], v[156:157], 2, s[90:91]
	s_mov_b32 s14, 0x100000
	s_mov_b32 s16, 0x160000
	s_mov_b32 s34, s29
	s_waitcnt vmcnt(0)
	v_pk_mul_f32 v[130:131], v[130:131], v[154:155] op_sel_hi:[1,0]
	v_pk_mul_f32 v[128:129], v[128:129], v[154:155] op_sel_hi:[1,0]
	v_pk_mul_f32 v[126:127], v[126:127], v[154:155] op_sel_hi:[1,0]
	v_pk_mul_f32 v[124:125], v[124:125], v[154:155] op_sel_hi:[1,0]
	v_pk_mul_f32 v[122:123], v[122:123], v[154:155] op_sel_hi:[1,0]
	v_pk_mul_f32 v[120:121], v[120:121], v[154:155] op_sel_hi:[1,0]
	v_pk_mul_f32 v[118:119], v[118:119], v[154:155] op_sel_hi:[1,0]
	v_pk_mul_f32 v[116:117], v[116:117], v[154:155] op_sel_hi:[1,0]
	global_store_dwordx4 v[142:143], v[128:131], off
	global_store_dwordx4 v[142:143], v[124:127], off offset:64
	global_store_dwordx4 v[142:143], v[120:123], off offset:512
	global_store_dwordx4 v[142:143], v[116:119], off offset:576
	s_nop 1
	v_mov_b32_e32 v116, v153
	v_lshlrev_b64 v[120:121], 13, v[156:157]
	v_or_b32_e32 v118, 32, v144
	v_lshl_add_u64 v[120:121], s[12:13], 0, v[120:121]
	v_ashrrev_i32_e32 v119, 31, v118
	v_lshl_add_u64 v[120:121], v[120:121], 0, v[146:147]
	v_lshl_add_u64 v[122:123], v[118:119], 2, s[90:91]
	v_pk_mul_f32 v[114:115], v[114:115], v[116:117] op_sel_hi:[1,0]
	v_pk_mul_f32 v[112:113], v[112:113], v[116:117] op_sel_hi:[1,0]
	v_pk_mul_f32 v[110:111], v[110:111], v[116:117] op_sel_hi:[1,0]
	v_pk_mul_f32 v[108:109], v[108:109], v[116:117] op_sel_hi:[1,0]
	v_pk_mul_f32 v[106:107], v[106:107], v[116:117] op_sel_hi:[1,0]
	v_pk_mul_f32 v[104:105], v[104:105], v[116:117] op_sel_hi:[1,0]
	v_pk_mul_f32 v[102:103], v[102:103], v[116:117] op_sel_hi:[1,0]
	v_pk_mul_f32 v[100:101], v[100:101], v[116:117] op_sel_hi:[1,0]
	global_store_dwordx4 v[120:121], v[112:115], off
	global_store_dwordx4 v[120:121], v[108:111], off offset:64
	global_store_dwordx4 v[120:121], v[104:107], off offset:512
;     __device__ __forceinline__ void operator()(const f32x4 (&acc)[2][2][4][2], const Unit& u, int wr, int wc, int fr, int fq) const {
;         const int row0 = u.pm * BM + wr * 64 + fr, col0 = u.pn * BM + wc * 32 + 4 * fq;
; #pragma unroll
;         for (int ai = 0; ai < 2; ++ai)
; #pragma unroll
;             for (int m = 0; m < 4; ++m) { const int row = row0 + ai * HALF + m * 16; const float rs = rowscale ? rowscale[row] : 1.f;
; #pragma unroll
;                 for (int bj = 0; bj < 2; ++bj)
; #pragma unroll
;                     for (int n = 0; n < 2; ++n) f(row, col0 + bj * HALF + n * 16, acc[ai][bj][m][n] * rs); }
	global_store_dwordx4 v[120:121], v[100:103], off offset:576
	s_nop 1
	v_mov_b32_e32 v100, v160
	v_lshlrev_b64 v[104:105], 13, v[118:119]
	v_or_b32_e32 v102, 48, v144
	v_lshl_add_u64 v[104:105], s[12:13], 0, v[104:105]
	v_ashrrev_i32_e32 v103, 31, v102
	v_lshl_add_u64 v[104:105], v[104:105], 0, v[146:147]
	v_lshl_add_u64 v[106:107], v[102:103], 2, s[90:91]
	v_pk_mul_f32 v[98:99], v[98:99], v[100:101] op_sel_hi:[1,0]
	v_pk_mul_f32 v[96:97], v[96:97], v[100:101] op_sel_hi:[1,0]
	v_pk_mul_f32 v[94:95], v[94:95], v[100:101] op_sel_hi:[1,0]
	v_pk_mul_f32 v[92:93], v[92:93], v[100:101] op_sel_hi:[1,0]
	v_pk_mul_f32 v[90:91], v[90:91], v[100:101] op_sel_hi:[1,0]
	v_pk_mul_f32 v[88:89], v[88:89], v[100:101] op_sel_hi:[1,0]
	v_pk_mul_f32 v[86:87], v[86:87], v[100:101] op_sel_hi:[1,0]
	v_pk_mul_f32 v[84:85], v[84:85], v[100:101] op_sel_hi:[1,0]
	global_store_dwordx4 v[104:105], v[96:99], off
	global_store_dwordx4 v[104:105], v[92:95], off offset:64
	global_store_dwordx4 v[104:105], v[88:91], off offset:512
	global_store_dwordx4 v[104:105], v[84:87], off offset:576
	s_nop 1
	v_mov_b32_e32 v84, v161
	v_pk_mul_f32 v[82:83], v[82:83], v[84:85] op_sel_hi:[1,0]
	v_lshlrev_b64 v[86:87], 13, v[102:103]
	v_lshl_add_u64 v[86:87], s[12:13], 0, v[86:87]
	v_lshl_add_u64 v[86:87], v[86:87], 0, v[146:147]
	v_pk_mul_f32 v[80:81], v[80:81], v[84:85] op_sel_hi:[1,0]
	v_pk_mul_f32 v[78:79], v[78:79], v[84:85] op_sel_hi:[1,0]
	v_pk_mul_f32 v[76:77], v[76:77], v[84:85] op_sel_hi:[1,0]
	v_pk_mul_f32 v[74:75], v[74:75], v[84:85] op_sel_hi:[1,0]
	v_pk_mul_f32 v[72:73], v[72:73], v[84:85] op_sel_hi:[1,0]
	v_pk_mul_f32 v[70:71], v[70:71], v[84:85] op_sel_hi:[1,0]
	v_pk_mul_f32 v[68:69], v[68:69], v[84:85] op_sel_hi:[1,0]
	global_store_dwordx4 v[86:87], v[80:83], off
	global_store_dwordx4 v[86:87], v[76:79], off offset:64
	global_store_dwordx4 v[86:87], v[72:75], off offset:512
	global_store_dwordx4 v[86:87], v[68:71], off offset:576
	s_nop 1
	v_mov_b32_e32 v68, v162
	v_add_co_u32_e32 v72, vcc, s14, v142
	s_mov_b64 s[12:13], 0x100000
	s_nop 0
	v_addc_co_u32_e32 v73, vcc, 0, v143, vcc
	v_lshl_add_u64 v[70:71], v[142:143], 0, s[12:13]
	s_mov_b32 s14, 0x120000
	s_mov_b64 s[12:13], 0x120000
	v_pk_mul_f32 v[66:67], v[66:67], v[68:69] op_sel_hi:[1,0]
	v_pk_mul_f32 v[64:65], v[64:65], v[68:69] op_sel_hi:[1,0]
	v_pk_mul_f32 v[62:63], v[62:63], v[68:69] op_sel_hi:[1,0]
	v_pk_mul_f32 v[60:61], v[60:61], v[68:69] op_sel_hi:[1,0]
	v_pk_mul_f32 v[58:59], v[58:59], v[68:69] op_sel_hi:[1,0]
	v_pk_mul_f32 v[56:57], v[56:57], v[68:69] op_sel_hi:[1,0]
	v_pk_mul_f32 v[54:55], v[54:55], v[68:69] op_sel_hi:[1,0]
	v_pk_mul_f32 v[52:53], v[52:53], v[68:69] op_sel_hi:[1,0]
	global_store_dwordx4 v[72:73], v[64:67], off
	global_store_dwordx4 v[70:71], v[60:63], off offset:64
	global_store_dwordx4 v[70:71], v[56:59], off offset:512
	global_store_dwordx4 v[70:71], v[52:55], off offset:576
	s_nop 1
	v_mov_b32_e32 v52, v163
	v_add_co_u32_e32 v56, vcc, s14, v142
	v_lshl_add_u64 v[54:55], v[142:143], 0, s[12:13]
	s_nop 0
	v_addc_co_u32_e32 v57, vcc, 0, v143, vcc
	s_mov_b32 s14, 0x140000
	s_mov_b64 s[12:13], 0x140000
	v_pk_mul_f32 v[50:51], v[50:51], v[52:53] op_sel_hi:[1,0]
	v_pk_mul_f32 v[48:49], v[48:49], v[52:53] op_sel_hi:[1,0]
	v_pk_mul_f32 v[46:47], v[46:47], v[52:53] op_sel_hi:[1,0]
	v_pk_mul_f32 v[44:45], v[44:45], v[52:53] op_sel_hi:[1,0]
	v_pk_mul_f32 v[42:43], v[42:43], v[52:53] op_sel_hi:[1,0]
	v_pk_mul_f32 v[40:41], v[40:41], v[52:53] op_sel_hi:[1,0]
	v_pk_mul_f32 v[38:39], v[38:39], v[52:53] op_sel_hi:[1,0]
	v_pk_mul_f32 v[36:37], v[36:37], v[52:53] op_sel_hi:[1,0]
	global_store_dwordx4 v[56:57], v[48:51], off
	global_store_dwordx4 v[54:55], v[44:47], off offset:64
	global_store_dwordx4 v[54:55], v[40:43], off offset:512
	global_store_dwordx4 v[54:55], v[36:39], off offset:576
	s_nop 1
	v_mov_b32_e32 v36, v165
	v_add_co_u32_e32 v40, vcc, s14, v142
	v_lshl_add_u64 v[38:39], v[142:143], 0, s[12:13]
	s_nop 0
	v_addc_co_u32_e32 v41, vcc, 0, v143, vcc
	s_mov_b64 s[12:13], 0x160000
	s_andn2_b64 vcc, exec, s[0:1]
	s_mov_b64 s[14:15], 0
	v_pk_mul_f32 v[34:35], v[34:35], v[36:37] op_sel_hi:[1,0]
	v_pk_mul_f32 v[32:33], v[32:33], v[36:37] op_sel_hi:[1,0]
	v_pk_mul_f32 v[30:31], v[30:31], v[36:37] op_sel_hi:[1,0]
	v_pk_mul_f32 v[28:29], v[28:29], v[36:37] op_sel_hi:[1,0]
	v_pk_mul_f32 v[26:27], v[26:27], v[36:37] op_sel_hi:[1,0]
	v_pk_mul_f32 v[24:25], v[24:25], v[36:37] op_sel_hi:[1,0]
	v_pk_mul_f32 v[22:23], v[22:23], v[36:37] op_sel_hi:[1,0]
	v_pk_mul_f32 v[20:21], v[20:21], v[36:37] op_sel_hi:[1,0]
	global_store_dwordx4 v[40:41], v[32:35], off
	global_store_dwordx4 v[38:39], v[28:31], off offset:64
	global_store_dwordx4 v[38:39], v[24:27], off offset:512
	global_store_dwordx4 v[38:39], v[20:23], off offset:576
	s_nop 1
	v_mov_b32_e32 v20, v166
	v_add_co_u32_e64 v24, s[0:1], s16, v142
	v_lshl_add_u64 v[22:23], v[142:143], 0, s[12:13]
	s_nop 0
	v_addc_co_u32_e64 v25, s[0:1], 0, v143, s[0:1]
	s_mov_b32 s12, s28
	v_pk_mul_f32 v[18:19], v[18:19], v[20:21] op_sel_hi:[1,0]
	v_pk_mul_f32 v[16:17], v[16:17], v[20:21] op_sel_hi:[1,0]
	v_pk_mul_f32 v[14:15], v[14:15], v[20:21] op_sel_hi:[1,0]
	v_pk_mul_f32 v[12:13], v[12:13], v[20:21] op_sel_hi:[1,0]
	v_pk_mul_f32 v[10:11], v[10:11], v[20:21] op_sel_hi:[1,0]
	v_pk_mul_f32 v[8:9], v[8:9], v[20:21] op_sel_hi:[1,0]
	v_pk_mul_f32 v[6:7], v[6:7], v[20:21] op_sel_hi:[1,0]
	v_pk_mul_f32 v[4:5], v[4:5], v[20:21] op_sel_hi:[1,0]
	global_store_dwordx4 v[24:25], v[16:19], off
	global_store_dwordx4 v[22:23], v[12:15], off offset:64
	global_store_dwordx4 v[22:23], v[8:11], off offset:512
	global_store_dwordx4 v[22:23], v[4:7], off offset:576
	s_cbranch_vccnz .LBB0_4817
	s_waitcnt vmcnt(0)
	s_cmpk_gt_u32 s20, 0xff
	s_cbranch_scc1 .LBB0_4822
	s_barrier

; #define PG8_STAGE(bufoff, gbase, voff) do { _Pragma("unroll") for (int _i = 0; _i < 2; ++_i) \
;         __builtin_amdgcn_global_load_lds((const unsigned*)((const char*)(gbase) + (voff)[_i]), (LAS unsigned*)(lds + (bufoff) + ldsw + _i * 8192), 16, 0, 0); } while (0)
; #define PG8_LDA(dst, b, h) do { _Pragma("unroll") for (int m = 0; m < 4; ++m) _Pragma("unroll") for (int k = 0; k < 2; ++k) dst[m][k] = *(const LAS bf16x8*)(lds + PG8_SA(b, h) + aoff + m * 2048 + k * 1024); } while (0)
; #define PG8_LDB(dst, b, h) do { _Pragma("unroll") for (int n = 0; n < 2; ++n) _Pragma("unroll") for (int k = 0; k < 2; ++k) dst[n][k] = *(const LAS bf16x8*)(lds + PG8_SB(b, h) + boff + n * 2048 + k * 1024); } while (0)
; #define PG8_WAIT_V(n) asm volatile("s_waitcnt vmcnt(" #n ")" ::: "memory")
; #define PG8_WAIT_L(n) asm volatile("s_waitcnt lgkmcnt(" #n ")" ::: "memory")
; #define PG8_BAR __builtin_amdgcn_s_barrier()
; #define PG8_SCHED __builtin_amdgcn_sched_barrier(0)
; template <class PT, class Epi>
; __device__ __forceinline__ void gemm_phase_once(LAS unsigned char* lds, const PT& S, const Epi& E, bool epi_on) {
;     ...
;             PG8_LDB(B0, 0, 0); PG8_SCHED; PG8_LDA(At, 0, 0); PG8_STAGE(PG8_SA(1, 1), a1 + hstepA, voffA);
;             PG8_WAIT_L(8); PG8_BAR; PG8_WAIT_L(0); PG8_MMA(0, 0, At, B0); PG8_BAR; PG8_SCHED;
;             PG8_LDB(B1, 0, 1); PG8_STAGE(PG8_SB(0, 0), b2, voffB);
;             PG8_BAR; PG8_WAIT_L(0); PG8_MMA(0, 1, At, B1); PG8_BAR;
;             PG8_LDA(At, 0, 1); PG8_STAGE(PG8_SA(0, 0), a2, voffA);
;             PG8_BAR; PG8_WAIT_L(0); PG8_MMA(1, 0, At, B0); PG8_BAR; PG8_SCHED;
;             PG8_STAGE(PG8_SB(0, 1), b2 + hstepB, voffB);
;             PG8_WAIT_V(6); PG8_BAR; PG8_MMA(1, 1, At, B1); PG8_BAR;
;             PG8_LDB(B0, 1, 0); PG8_SCHED; PG8_LDA(At, 1, 0); PG8_STAGE(PG8_SA(0, 1), a2 + hstepA, voffA);
;             PG8_WAIT_L(8); PG8_BAR; PG8_WAIT_L(0); PG8_MMA(0, 0, At, B0); PG8_BAR; PG8_SCHED;
;             PG8_LDB(B1, 1, 1); PG8_STAGE(PG8_SB(1, 0), b3, voffB);
;             PG8_BAR; PG8_WAIT_L(0); PG8_MMA(0, 1, At, B1); PG8_BAR;
;             PG8_LDA(At, 1, 1); PG8_STAGE(PG8_SA(1, 0), a3, voffA);
;             PG8_BAR; PG8_WAIT_L(0); PG8_MMA(1, 0, At, B0); PG8_BAR; PG8_SCHED;
;             PG8_STAGE(PG8_SB(1, 1), b3 + hstepB, voffB);
;             PG8_WAIT_V(6); PG8_BAR; PG8_MMA(1, 1, At, B1); PG8_BAR;
.LBB0_5227:
	ds_read_b128 v[148:151], v162
	ds_read_b128 v[168:171], v162 offset:1024
	ds_read_b128 v[172:175], v162 offset:2048
	ds_read_b128 v[176:179], v162 offset:3072
	s_add_u32 s20, s18, 0xfff80080
	s_addc_u32 s21, s19, -1
	s_cmp_eq_u32 s44, 28
	s_cselect_b32 s23, s11, s21
	s_cselect_b32 s22, s40, s20
	s_cselect_b32 s21, s9, s43
	s_cselect_b32 s20, s41, s42
	v_lshl_add_u64 v[212:213], s[18:19], 0, v[140:141]
	s_add_i32 m0, s27, 0xc000
	ds_read_b128 v[180:183], v163
	ds_read_b128 v[184:187], v163 offset:1024
	ds_read_b128 v[188:191], v163 offset:2048
	ds_read_b128 v[192:195], v163 offset:3072
	ds_read_b128 v[196:199], v163 offset:4096
	ds_read_b128 v[200:203], v163 offset:5120
	ds_read_b128 v[204:207], v163 offset:6144
	ds_read_b128 v[208:211], v163 offset:7168
	global_load_lds_dwordx4 v[212:213], off
	v_lshl_add_u64 v[212:213], s[18:19], 0, v[142:143]
	s_add_i32 m0, s27, 0xe000
	s_nop 0
	global_load_lds_dwordx4 v[212:213], off
	s_waitcnt lgkmcnt(8)
	s_barrier
	s_waitcnt lgkmcnt(0)
	s_setprio 1
	s_waitcnt lgkmcnt(0)
	v_mfma_f32_16x16x32_bf16 v[128:131], v[148:151], v[180:183], v[128:131]
	v_mfma_f32_16x16x32_bf16 v[124:127], v[172:175], v[180:183], v[124:127]
	v_mfma_f32_16x16x32_bf16 v[112:115], v[148:151], v[188:191], v[112:115]
	v_mfma_f32_16x16x32_bf16 v[108:111], v[172:175], v[188:191], v[108:111]
	v_mfma_f32_16x16x32_bf16 v[96:99], v[148:151], v[196:199], v[96:99]
	v_mfma_f32_16x16x32_bf16 v[92:95], v[172:175], v[196:199], v[92:95]
	v_mfma_f32_16x16x32_bf16 v[80:83], v[148:151], v[204:207], v[80:83]
	v_mfma_f32_16x16x32_bf16 v[76:79], v[172:175], v[204:207], v[76:79]
	v_mfma_f32_16x16x32_bf16 v[128:131], v[168:171], v[184:187], v[128:131]
	v_mfma_f32_16x16x32_bf16 v[124:127], v[176:179], v[184:187], v[124:127]
	v_mfma_f32_16x16x32_bf16 v[112:115], v[168:171], v[192:195], v[112:115]
	v_mfma_f32_16x16x32_bf16 v[108:111], v[176:179], v[192:195], v[108:111]
	v_mfma_f32_16x16x32_bf16 v[96:99], v[168:171], v[200:203], v[96:99]
	v_mfma_f32_16x16x32_bf16 v[92:95], v[176:179], v[200:203], v[92:95]
	v_mfma_f32_16x16x32_bf16 v[80:83], v[168:171], v[208:211], v[80:83]
	v_mfma_f32_16x16x32_bf16 v[76:79], v[176:179], v[208:211], v[76:79]
	s_setprio 0
	s_barrier
	s_add_i32 s45, s36, s26
	v_lshl_add_u64 v[228:229], s[20:21], 0, v[134:135]
	s_mov_b32 m0, s45
	ds_read_b128 v[212:215], v167
	ds_read_b128 v[216:219], v167 offset:1024
	ds_read_b128 v[220:223], v167 offset:2048
	ds_read_b128 v[224:227], v167 offset:3072
	global_load_lds_dwordx4 v[228:229], off
	v_lshl_add_u64 v[232:233], s[20:21], 0, v[138:139]
	s_add_i32 m0, s45, 0x2000
	s_nop 0
	global_load_lds_dwordx4 v[232:233], off
	s_barrier
	s_waitcnt lgkmcnt(0)
	s_setprio 1
	s_waitcnt lgkmcnt(0)
	v_mfma_f32_16x16x32_bf16 v[120:123], v[212:215], v[180:183], v[120:123]
	v_mfma_f32_16x16x32_bf16 v[116:119], v[220:223], v[180:183], v[116:119]
	v_mfma_f32_16x16x32_bf16 v[104:107], v[212:215], v[188:191], v[104:107]
	v_mfma_f32_16x16x32_bf16 v[100:103], v[220:223], v[188:191], v[100:103]
	v_mfma_f32_16x16x32_bf16 v[88:91], v[212:215], v[196:199], v[88:91]
	v_mfma_f32_16x16x32_bf16 v[84:87], v[220:223], v[196:199], v[84:87]
	v_mfma_f32_16x16x32_bf16 v[72:75], v[212:215], v[204:207], v[72:75]
	v_mfma_f32_16x16x32_bf16 v[68:71], v[220:223], v[204:207], v[68:71]
	v_mfma_f32_16x16x32_bf16 v[120:123], v[216:219], v[184:187], v[120:123]
	v_mfma_f32_16x16x32_bf16 v[116:119], v[224:227], v[184:187], v[116:119]
	v_mfma_f32_16x16x32_bf16 v[104:107], v[216:219], v[192:195], v[104:107]
	v_mfma_f32_16x16x32_bf16 v[100:103], v[224:227], v[192:195], v[100:103]
	v_mfma_f32_16x16x32_bf16 v[88:91], v[216:219], v[200:203], v[88:91]
	v_mfma_f32_16x16x32_bf16 v[84:87], v[224:227], v[200:203], v[84:87]
	v_mfma_f32_16x16x32_bf16 v[72:75], v[216:219], v[208:211], v[72:75]
	v_mfma_f32_16x16x32_bf16 v[68:71], v[224:227], v[208:211], v[68:71]
	s_setprio 0
	s_mov_b32 m0, s27
	v_lshl_add_u64 v[234:235], s[22:23], 0, v[132:133]
	s_barrier
	ds_read_b128 v[180:183], v163 offset:16384
	ds_read_b128 v[184:187], v163 offset:17408
	ds_read_b128 v[188:191], v163 offset:18432
	ds_read_b128 v[192:195], v163 offset:19456
	ds_read_b128 v[196:199], v163 offset:20480
	ds_read_b128 v[200:203], v163 offset:21504
	ds_read_b128 v[204:207], v163 offset:22528
	ds_read_b128 v[208:211], v163 offset:23552
	global_load_lds_dwordx4 v[234:235], off
	v_lshl_add_u64 v[236:237], s[22:23], 0, v[136:137]
	s_mov_b32 m0, s17
	s_nop 0
	global_load_lds_dwordx4 v[236:237], off
	s_barrier
	s_waitcnt lgkmcnt(0)
	s_setprio 1
	s_waitcnt lgkmcnt(0)
	v_mfma_f32_16x16x32_bf16 v[64:67], v[148:151], v[180:183], v[64:67]
	v_mfma_f32_16x16x32_bf16 v[60:63], v[172:175], v[180:183], v[60:63]
	v_mfma_f32_16x16x32_bf16 v[48:51], v[148:151], v[188:191], v[48:51]
	v_mfma_f32_16x16x32_bf16 v[44:47], v[172:175], v[188:191], v[44:47]
	v_mfma_f32_16x16x32_bf16 v[32:35], v[148:151], v[196:199], v[32:35]
	v_mfma_f32_16x16x32_bf16 v[28:31], v[172:175], v[196:199], v[28:31]
	v_mfma_f32_16x16x32_bf16 v[16:19], v[148:151], v[204:207], v[16:19]
	v_mfma_f32_16x16x32_bf16 v[12:15], v[172:175], v[204:207], v[12:15]
	v_mfma_f32_16x16x32_bf16 v[64:67], v[168:171], v[184:187], v[64:67]
	v_mfma_f32_16x16x32_bf16 v[60:63], v[176:179], v[184:187], v[60:63]
	v_mfma_f32_16x16x32_bf16 v[48:51], v[168:171], v[192:195], v[48:51]
	v_mfma_f32_16x16x32_bf16 v[44:47], v[176:179], v[192:195], v[44:47]
	v_mfma_f32_16x16x32_bf16 v[32:35], v[168:171], v[200:203], v[32:35]
	v_mfma_f32_16x16x32_bf16 v[28:31], v[176:179], v[200:203], v[28:31]
	v_mfma_f32_16x16x32_bf16 v[16:19], v[168:171], v[208:211], v[16:19]
	v_mfma_f32_16x16x32_bf16 v[12:15], v[176:179], v[208:211], v[12:15]
	s_setprio 0
	s_barrier
; #define PG8_STAGE(bufoff, gbase, voff) do { _Pragma("unroll") for (int _i = 0; _i < 2; ++_i) \
;         __builtin_amdgcn_global_load_lds((const unsigned*)((const char*)(gbase) + (voff)[_i]), (LAS unsigned*)(lds + (bufoff) + ldsw + _i * 8192), 16, 0, 0); } while (0)
; #define PG8_LDA(dst, b, h) do { _Pragma("unroll") for (int m = 0; m < 4; ++m) _Pragma("unroll") for (int k = 0; k < 2; ++k) dst[m][k] = *(const LAS bf16x8*)(lds + PG8_SA(b, h) + aoff + m * 2048 + k * 1024); } while (0)
; #define PG8_LDB(dst, b, h) do { _Pragma("unroll") for (int n = 0; n < 2; ++n) _Pragma("unroll") for (int k = 0; k < 2; ++k) dst[n][k] = *(const LAS bf16x8*)(lds + PG8_SB(b, h) + boff + n * 2048 + k * 1024); } while (0)
; #define PG8_WAIT_V(n) asm volatile("s_waitcnt vmcnt(" #n ")" ::: "memory")
; #define PG8_WAIT_L(n) asm volatile("s_waitcnt lgkmcnt(" #n ")" ::: "memory")
; #define PG8_BAR __builtin_amdgcn_s_barrier()
; #define PG8_SCHED __builtin_amdgcn_sched_barrier(0)
; template <class PT, class Epi>
; __device__ __forceinline__ void gemm_phase_once(LAS unsigned char* lds, const PT& S, const Epi& E, bool epi_on) {
;     ...
;             PG8_LDB(B0, 0, 0); PG8_SCHED; PG8_LDA(At, 0, 0); PG8_STAGE(PG8_SA(1, 1), a1 + hstepA, voffA);
;             PG8_WAIT_L(8); PG8_BAR; PG8_WAIT_L(0); PG8_MMA(0, 0, At, B0); PG8_BAR; PG8_SCHED;
;             PG8_LDB(B1, 0, 1); PG8_STAGE(PG8_SB(0, 0), b2, voffB);
;             PG8_BAR; PG8_WAIT_L(0); PG8_MMA(0, 1, At, B1); PG8_BAR;
;             PG8_LDA(At, 0, 1); PG8_STAGE(PG8_SA(0, 0), a2, voffA);
;             PG8_BAR; PG8_WAIT_L(0); PG8_MMA(1, 0, At, B0); PG8_BAR; PG8_SCHED;
;             PG8_STAGE(PG8_SB(0, 1), b2 + hstepB, voffB);
;             PG8_WAIT_V(6); PG8_BAR; PG8_MMA(1, 1, At, B1); PG8_BAR;
;             PG8_LDB(B0, 1, 0); PG8_SCHED; PG8_LDA(At, 1, 0); PG8_STAGE(PG8_SA(0, 1), a2 + hstepA, voffA);
;             PG8_WAIT_L(8); PG8_BAR; PG8_WAIT_L(0); PG8_MMA(0, 0, At, B0); PG8_BAR; PG8_SCHED;
;             PG8_LDB(B1, 1, 1); PG8_STAGE(PG8_SB(1, 0), b3, voffB);
;             PG8_BAR; PG8_WAIT_L(0); PG8_MMA(0, 1, At, B1); PG8_BAR;
;             PG8_LDA(At, 1, 1); PG8_STAGE(PG8_SA(1, 0), a3, voffA);
;             PG8_BAR; PG8_WAIT_L(0); PG8_MMA(1, 0, At, B0); PG8_BAR; PG8_SCHED;
;             PG8_STAGE(PG8_SB(1, 1), b3 + hstepB, voffB);
;             PG8_WAIT_V(6); PG8_BAR; PG8_MMA(1, 1, At, B1); PG8_BAR;
	s_add_u32 s46, s20, 0x80000
	s_addc_u32 s47, s21, 0
	s_add_i32 s45, s37, s26
	v_lshl_add_u64 v[148:149], s[46:47], 0, v[134:135]
	s_mov_b32 m0, s45
	s_nop 0
	global_load_lds_dwordx4 v[148:149], off
	v_lshl_add_u64 v[148:149], s[46:47], 0, v[138:139]
	s_add_i32 m0, s45, 0x2000
	s_nop 0
	global_load_lds_dwordx4 v[148:149], off
	s_waitcnt vmcnt(6)
	s_barrier
	s_setprio 1
	v_mfma_f32_16x16x32_bf16 v[56:59], v[212:215], v[180:183], v[56:59]
	v_mfma_f32_16x16x32_bf16 v[52:55], v[220:223], v[180:183], v[52:55]
	v_mfma_f32_16x16x32_bf16 v[40:43], v[212:215], v[188:191], v[40:43]
	v_mfma_f32_16x16x32_bf16 v[36:39], v[220:223], v[188:191], v[36:39]
	v_mfma_f32_16x16x32_bf16 v[24:27], v[212:215], v[196:199], v[24:27]
	v_mfma_f32_16x16x32_bf16 v[20:23], v[220:223], v[196:199], v[20:23]
	v_mfma_f32_16x16x32_bf16 v[8:11], v[212:215], v[204:207], v[8:11]
	v_mfma_f32_16x16x32_bf16 v[4:7], v[220:223], v[204:207], v[4:7]
	v_mfma_f32_16x16x32_bf16 v[56:59], v[216:219], v[184:187], v[56:59]
	v_mfma_f32_16x16x32_bf16 v[52:55], v[224:227], v[184:187], v[52:55]
	v_mfma_f32_16x16x32_bf16 v[40:43], v[216:219], v[192:195], v[40:43]
	v_mfma_f32_16x16x32_bf16 v[36:39], v[224:227], v[192:195], v[36:39]
	v_mfma_f32_16x16x32_bf16 v[24:27], v[216:219], v[200:203], v[24:27]
	v_mfma_f32_16x16x32_bf16 v[20:23], v[224:227], v[200:203], v[20:23]
	v_mfma_f32_16x16x32_bf16 v[8:11], v[216:219], v[208:211], v[8:11]
	v_mfma_f32_16x16x32_bf16 v[4:7], v[224:227], v[208:211], v[4:7]
	s_setprio 0
	s_add_i32 s45, 0, 0x18000
	v_add_u32_e32 v165, s45, v160
	s_barrier
	ds_read_b128 v[148:151], v165
	ds_read_b128 v[168:171], v165 offset:1024
	ds_read_b128 v[172:175], v165 offset:2048
	ds_read_b128 v[176:179], v165 offset:3072
	s_add_u32 s22, s22, 0x80000
	s_addc_u32 s23, s23, 0
	s_mov_b32 m0, s28
	v_lshl_add_u64 v[212:213], s[22:23], 0, v[132:133]
	ds_read_b128 v[180:183], v163 offset:32768
	ds_read_b128 v[184:187], v163 offset:33792
	ds_read_b128 v[188:191], v163 offset:34816
	ds_read_b128 v[192:195], v163 offset:35840
	ds_read_b128 v[196:199], v163 offset:36864
	ds_read_b128 v[200:203], v163 offset:37888
	ds_read_b128 v[204:207], v163 offset:38912
	ds_read_b128 v[208:211], v163 offset:39936
	global_load_lds_dwordx4 v[212:213], off
	v_lshl_add_u64 v[212:213], s[22:23], 0, v[136:137]
	s_mov_b32 m0, s29
	s_nop 0
	global_load_lds_dwordx4 v[212:213], off
	s_waitcnt lgkmcnt(8)
	s_barrier
	s_waitcnt lgkmcnt(0)
	s_setprio 1
	s_waitcnt lgkmcnt(0)
	v_mfma_f32_16x16x32_bf16 v[128:131], v[148:151], v[180:183], v[128:131]
	v_mfma_f32_16x16x32_bf16 v[124:127], v[172:175], v[180:183], v[124:127]
	v_mfma_f32_16x16x32_bf16 v[112:115], v[148:151], v[188:191], v[112:115]
	v_mfma_f32_16x16x32_bf16 v[108:111], v[172:175], v[188:191], v[108:111]
	v_mfma_f32_16x16x32_bf16 v[96:99], v[148:151], v[196:199], v[96:99]
	v_mfma_f32_16x16x32_bf16 v[92:95], v[172:175], v[196:199], v[92:95]
	v_mfma_f32_16x16x32_bf16 v[80:83], v[148:151], v[204:207], v[80:83]
	v_mfma_f32_16x16x32_bf16 v[76:79], v[172:175], v[204:207], v[76:79]
	v_mfma_f32_16x16x32_bf16 v[128:131], v[168:171], v[184:187], v[128:131]
	v_mfma_f32_16x16x32_bf16 v[124:127], v[176:179], v[184:187], v[124:127]
	v_mfma_f32_16x16x32_bf16 v[112:115], v[168:171], v[192:195], v[112:115]
	v_mfma_f32_16x16x32_bf16 v[108:111], v[176:179], v[192:195], v[108:111]
	v_mfma_f32_16x16x32_bf16 v[96:99], v[168:171], v[200:203], v[96:99]
	v_mfma_f32_16x16x32_bf16 v[92:95], v[176:179], v[200:203], v[92:95]
	v_mfma_f32_16x16x32_bf16 v[80:83], v[168:171], v[208:211], v[80:83]
	v_mfma_f32_16x16x32_bf16 v[76:79], v[176:179], v[208:211], v[76:79]
	s_setprio 0
	s_barrier
	s_add_i32 s22, 0, 0x1c000
	s_add_i32 s23, s45, s26
	v_add_u32_e32 v165, s22, v160
	v_lshl_add_u64 v[228:229], v[228:229], 0, s[6:7]
	s_mov_b32 m0, s23
	ds_read_b128 v[212:215], v165
	ds_read_b128 v[216:219], v165 offset:1024
	ds_read_b128 v[220:223], v165 offset:2048
	ds_read_b128 v[224:227], v165 offset:3072
	global_load_lds_dwordx4 v[228:229], off
	v_lshl_add_u64 v[228:229], v[232:233], 0, s[6:7]
	s_add_i32 m0, s23, 0x2000
	s_nop 0
	global_load_lds_dwordx4 v[228:229], off
	s_barrier
	s_waitcnt lgkmcnt(0)
	s_setprio 1
	s_waitcnt lgkmcnt(0)
	v_mfma_f32_16x16x32_bf16 v[120:123], v[212:215], v[180:183], v[120:123]
	v_mfma_f32_16x16x32_bf16 v[116:119], v[220:223], v[180:183], v[116:119]
	v_mfma_f32_16x16x32_bf16 v[104:107], v[212:215], v[188:191], v[104:107]
	v_mfma_f32_16x16x32_bf16 v[100:103], v[220:223], v[188:191], v[100:103]
	v_mfma_f32_16x16x32_bf16 v[88:91], v[212:215], v[196:199], v[88:91]
	v_mfma_f32_16x16x32_bf16 v[84:87], v[220:223], v[196:199], v[84:87]
	v_mfma_f32_16x16x32_bf16 v[72:75], v[212:215], v[204:207], v[72:75]
	v_mfma_f32_16x16x32_bf16 v[68:71], v[220:223], v[204:207], v[68:71]
	v_mfma_f32_16x16x32_bf16 v[120:123], v[216:219], v[184:187], v[120:123]
	v_mfma_f32_16x16x32_bf16 v[116:119], v[224:227], v[184:187], v[116:119]
	v_mfma_f32_16x16x32_bf16 v[104:107], v[216:219], v[192:195], v[104:107]
	v_mfma_f32_16x16x32_bf16 v[100:103], v[224:227], v[192:195], v[100:103]
	v_mfma_f32_16x16x32_bf16 v[88:91], v[216:219], v[200:203], v[88:91]
	v_mfma_f32_16x16x32_bf16 v[84:87], v[224:227], v[200:203], v[84:87]
	v_mfma_f32_16x16x32_bf16 v[72:75], v[216:219], v[208:211], v[72:75]
	v_mfma_f32_16x16x32_bf16 v[68:71], v[224:227], v[208:211], v[68:71]
	s_setprio 0
	s_mov_b32 m0, s31
	v_lshl_add_u64 v[228:229], v[234:235], 0, s[6:7]
	s_barrier
	ds_read_b128 v[180:183], v163 offset:49152
	ds_read_b128 v[184:187], v163 offset:50176
	ds_read_b128 v[188:191], v163 offset:51200
	ds_read_b128 v[192:195], v163 offset:52224
	ds_read_b128 v[196:199], v163 offset:53248
	ds_read_b128 v[200:203], v163 offset:54272
	ds_read_b128 v[204:207], v163 offset:55296
	ds_read_b128 v[208:211], v163 offset:56320
	global_load_lds_dwordx4 v[228:229], off
	v_lshl_add_u64 v[228:229], v[236:237], 0, s[6:7]
	s_mov_b32 m0, s34
	s_nop 0
	global_load_lds_dwordx4 v[228:229], off
	s_barrier
; #define PG8_STAGE(bufoff, gbase, voff) do { _Pragma("unroll") for (int _i = 0; _i < 2; ++_i) \
;         __builtin_amdgcn_global_load_lds((const unsigned*)((const char*)(gbase) + (voff)[_i]), (LAS unsigned*)(lds + (bufoff) + ldsw + _i * 8192), 16, 0, 0); } while (0)
; #define PG8_LDA(dst, b, h) do { _Pragma("unroll") for (int m = 0; m < 4; ++m) _Pragma("unroll") for (int k = 0; k < 2; ++k) dst[m][k] = *(const LAS bf16x8*)(lds + PG8_SA(b, h) + aoff + m * 2048 + k * 1024); } while (0)
; #define PG8_LDB(dst, b, h) do { _Pragma("unroll") for (int n = 0; n < 2; ++n) _Pragma("unroll") for (int k = 0; k < 2; ++k) dst[n][k] = *(const LAS bf16x8*)(lds + PG8_SB(b, h) + boff + n * 2048 + k * 1024); } while (0)
; #define PG8_WAIT_V(n) asm volatile("s_waitcnt vmcnt(" #n ")" ::: "memory")
; #define PG8_WAIT_L(n) asm volatile("s_waitcnt lgkmcnt(" #n ")" ::: "memory")
; #define PG8_BAR __builtin_amdgcn_s_barrier()
; #define PG8_SCHED __builtin_amdgcn_sched_barrier(0)
;     __device__ __forceinline__ void operator()(const f32x4 (&acc)[2][2][4][2], const Unit& u, int wr, int wc, int fr, int fq) const {
;         const int row0 = u.pm * BM + wr * 64 + fr, col0 = u.pn * BM + wc * 32 + 8 * fq;
; #pragma unroll
;         for (int ai = 0; ai < 2; ++ai)
; #pragma unroll
;             for (int m = 0; m < 4; ++m) { const int row = row0 + ai * HALF + m * 16; const float rs = rowscale ? rowscale[row] : 1.f;
; #pragma unroll
;                 for (int bj = 0; bj < 2; ++bj) f(row, col0 + bj * HALF, acc[ai][bj][m][0] * rs, acc[ai][bj][m][1] * rs); }
; template <class PT, class Epi>
; __device__ __forceinline__ void gemm_phase_once(LAS unsigned char* lds, const PT& S, const Epi& E, bool epi_on) {
;     ...
;             PG8_WAIT_V(6); PG8_BAR; PG8_MMA(1, 1, At, B1); PG8_BAR;
;             PG8_LDB(B0, 1, 0); PG8_SCHED; PG8_LDA(At, 1, 0); PG8_STAGE(PG8_SA(0, 1), a2 + hstepA, voffA);
;             PG8_WAIT_L(8); PG8_BAR; PG8_WAIT_L(0); PG8_MMA(0, 0, At, B0); PG8_BAR; PG8_SCHED;
;             PG8_LDB(B1, 1, 1); PG8_STAGE(PG8_SB(1, 0), b3, voffB);
;             PG8_BAR; PG8_WAIT_L(0); PG8_MMA(0, 1, At, B1); PG8_BAR;
;             PG8_LDA(At, 1, 1); PG8_STAGE(PG8_SA(1, 0), a3, voffA);
;             PG8_BAR; PG8_WAIT_L(0); PG8_MMA(1, 0, At, B0); PG8_BAR; PG8_SCHED;
;             PG8_STAGE(PG8_SB(1, 1), b3 + hstepB, voffB);
;             PG8_WAIT_V(6); PG8_BAR; PG8_MMA(1, 1, At, B1); PG8_BAR;
	s_waitcnt lgkmcnt(0)
	s_setprio 1
	s_waitcnt lgkmcnt(0)
	v_mfma_f32_16x16x32_bf16 v[64:67], v[148:151], v[180:183], v[64:67]
	v_mfma_f32_16x16x32_bf16 v[60:63], v[172:175], v[180:183], v[60:63]
	v_mfma_f32_16x16x32_bf16 v[48:51], v[148:151], v[188:191], v[48:51]
	v_mfma_f32_16x16x32_bf16 v[44:47], v[172:175], v[188:191], v[44:47]
	v_mfma_f32_16x16x32_bf16 v[32:35], v[148:151], v[196:199], v[32:35]
	v_mfma_f32_16x16x32_bf16 v[28:31], v[172:175], v[196:199], v[28:31]
	v_mfma_f32_16x16x32_bf16 v[16:19], v[148:151], v[204:207], v[16:19]
	v_mfma_f32_16x16x32_bf16 v[12:15], v[172:175], v[204:207], v[12:15]
	v_mfma_f32_16x16x32_bf16 v[64:67], v[168:171], v[184:187], v[64:67]
	v_mfma_f32_16x16x32_bf16 v[60:63], v[176:179], v[184:187], v[60:63]
	v_mfma_f32_16x16x32_bf16 v[48:51], v[168:171], v[192:195], v[48:51]
	v_mfma_f32_16x16x32_bf16 v[44:47], v[176:179], v[192:195], v[44:47]
	v_mfma_f32_16x16x32_bf16 v[32:35], v[168:171], v[200:203], v[32:35]
	v_mfma_f32_16x16x32_bf16 v[28:31], v[176:179], v[200:203], v[28:31]
	v_mfma_f32_16x16x32_bf16 v[16:19], v[168:171], v[208:211], v[16:19]
	v_mfma_f32_16x16x32_bf16 v[12:15], v[176:179], v[208:211], v[12:15]
	s_setprio 0
	s_barrier
	s_add_u32 s20, s20, 0x80080
	s_addc_u32 s21, s21, 0
	s_add_i32 s22, s22, s26
	v_lshl_add_u64 v[148:149], s[20:21], 0, v[134:135]
	s_mov_b32 m0, s22
	s_nop 0
	global_load_lds_dwordx4 v[148:149], off
	v_lshl_add_u64 v[148:149], s[20:21], 0, v[138:139]
	s_add_i32 m0, s22, 0x2000
	s_nop 0
	global_load_lds_dwordx4 v[148:149], off
	s_waitcnt vmcnt(6)
	s_barrier
	s_setprio 1
	v_mfma_f32_16x16x32_bf16 v[56:59], v[212:215], v[180:183], v[56:59]
	v_mfma_f32_16x16x32_bf16 v[52:55], v[220:223], v[180:183], v[52:55]
	v_mfma_f32_16x16x32_bf16 v[40:43], v[212:215], v[188:191], v[40:43]
	v_mfma_f32_16x16x32_bf16 v[36:39], v[220:223], v[188:191], v[36:39]
	v_mfma_f32_16x16x32_bf16 v[24:27], v[212:215], v[196:199], v[24:27]
	v_mfma_f32_16x16x32_bf16 v[20:23], v[220:223], v[196:199], v[20:23]
	v_mfma_f32_16x16x32_bf16 v[8:11], v[212:215], v[204:207], v[8:11]
	v_mfma_f32_16x16x32_bf16 v[4:7], v[220:223], v[204:207], v[4:7]
	v_mfma_f32_16x16x32_bf16 v[56:59], v[216:219], v[184:187], v[56:59]
	v_mfma_f32_16x16x32_bf16 v[52:55], v[224:227], v[184:187], v[52:55]
	v_mfma_f32_16x16x32_bf16 v[40:43], v[216:219], v[192:195], v[40:43]
	v_mfma_f32_16x16x32_bf16 v[36:39], v[224:227], v[192:195], v[36:39]
	v_mfma_f32_16x16x32_bf16 v[24:27], v[216:219], v[200:203], v[24:27]
	v_mfma_f32_16x16x32_bf16 v[20:23], v[224:227], v[200:203], v[20:23]
	v_mfma_f32_16x16x32_bf16 v[8:11], v[216:219], v[208:211], v[8:11]
	v_mfma_f32_16x16x32_bf16 v[4:7], v[224:227], v[208:211], v[4:7]
	s_setprio 0
	s_add_i32 s44, s44, 2
	s_add_u32 s18, s18, 0x100
	s_addc_u32 s19, s19, 0
	s_add_u32 s42, s42, 0x100
	s_addc_u32 s43, s43, 0
	s_cmp_lt_u32 s44, 30
	s_barrier
	s_cbranch_scc1 .LBB0_5227
	v_lshl_add_u32 v168, s16, 8, v159
	v_ashrrev_i32_e32 v169, 31, v168
	v_lshl_add_u64 v[150:151], v[168:169], 2, s[90:91]
	global_load_dword v166, v[150:151], off
	global_load_dword v165, v[150:151], off offset:64
	global_load_dword v180, v[150:151], off offset:128
	global_load_dword v181, v[150:151], off offset:192
	global_load_dword v182, v[150:151], off offset:512
	global_load_dword v183, v[150:151], off offset:576
	global_load_dword v184, v[150:151], off offset:640
	global_load_dword v185, v[150:151], off offset:704
	v_lshl_or_b32 v148, s39, 8, v161
	v_readlane_b32 s18, v254, 44
	v_ashrrev_i32_e32 v149, 31, v148
	v_lshlrev_b64 v[172:173], 10, v[168:169]
	v_readlane_b32 s19, v254, 45
	v_or_b32_e32 v170, 16, v168
	v_lshlrev_b64 v[174:175], 1, v[148:149]
	v_lshl_add_u64 v[148:149], s[18:19], 0, v[172:173]
	v_ashrrev_i32_e32 v171, 31, v170
	v_lshl_add_u64 v[148:149], v[148:149], 0, v[174:175]
	v_lshl_add_u64 v[172:173], v[170:171], 2, s[90:91]
	s_mov_b32 s9, 0x20000
	s_mov_b64 s[20:21], s[14:15]
	s_mov_b64 s[14:15], 0x2c000
	s_mov_b32 s39, s8
	s_mov_b32 s16, s10
	s_waitcnt vmcnt(0)
	v_pk_mul_f32 v[130:131], v[130:131], v[166:167] op_sel_hi:[1,0]
	v_pk_mul_f32 v[128:129], v[128:129], v[166:167] op_sel_hi:[1,0]
	v_pk_mul_f32 v[126:127], v[126:127], v[166:167] op_sel_hi:[1,0]
	v_pk_mul_f32 v[124:125], v[124:125], v[166:167] op_sel_hi:[1,0]
	v_pk_mul_f32 v[176:177], v[118:119], v[166:167] op_sel_hi:[1,0]
	v_pk_mul_f32 v[178:179], v[116:117], v[166:167] op_sel_hi:[1,0]
	v_cvt_pk_bf16_f32 v116, v128, v129
	v_cvt_pk_bf16_f32 v117, v130, v131
	v_cvt_pk_bf16_f32 v118, v124, v125
	v_cvt_pk_bf16_f32 v119, v126, v127
	v_pk_mul_f32 v[122:123], v[122:123], v[166:167] op_sel_hi:[1,0]
	v_pk_mul_f32 v[120:121], v[120:121], v[166:167] op_sel_hi:[1,0]
	global_store_dwordx4 v[148:149], v[116:119], off
	s_nop 1
	v_cvt_pk_bf16_f32 v116, v120, v121
	v_cvt_pk_bf16_f32 v117, v122, v123
	v_cvt_pk_bf16_f32 v118, v178, v179
	v_cvt_pk_bf16_f32 v119, v176, v177
	global_store_dwordx4 v[148:149], v[116:119], off offset:256
	s_nop 1
	v_mov_b32_e32 v116, v165
	v_lshlrev_b64 v[120:121], 10, v[170:171]
	v_or_b32_e32 v118, 32, v168
	v_lshl_add_u64 v[120:121], s[18:19], 0, v[120:121]
	v_ashrrev_i32_e32 v119, 31, v118
	v_lshl_add_u64 v[120:121], v[120:121], 0, v[174:175]
	v_lshl_add_u64 v[122:123], v[118:119], 2, s[90:91]
	v_pk_mul_f32 v[114:115], v[114:115], v[116:117] op_sel_hi:[1,0]
	v_pk_mul_f32 v[112:113], v[112:113], v[116:117] op_sel_hi:[1,0]
	v_pk_mul_f32 v[110:111], v[110:111], v[116:117] op_sel_hi:[1,0]
	v_pk_mul_f32 v[108:109], v[108:109], v[116:117] op_sel_hi:[1,0]
	v_pk_mul_f32 v[106:107], v[106:107], v[116:117] op_sel_hi:[1,0]
	v_pk_mul_f32 v[104:105], v[104:105], v[116:117] op_sel_hi:[1,0]
	v_pk_mul_f32 v[124:125], v[102:103], v[116:117] op_sel_hi:[1,0]
;     __device__ __forceinline__ void operator()(const f32x4 (&acc)[2][2][4][2], const Unit& u, int wr, int wc, int fr, int fq) const {
;         const int row0 = u.pm * BM + wr * 64 + fr, col0 = u.pn * BM + wc * 32 + 8 * fq;
; #pragma unroll
;         for (int ai = 0; ai < 2; ++ai)
; #pragma unroll
;             for (int m = 0; m < 4; ++m) { const int row = row0 + ai * HALF + m * 16; const float rs = rowscale ? rowscale[row] : 1.f;
; #pragma unroll
;                 for (int bj = 0; bj < 2; ++bj) f(row, col0 + bj * HALF, acc[ai][bj][m][0] * rs, acc[ai][bj][m][1] * rs); }
	v_pk_mul_f32 v[116:117], v[100:101], v[116:117] op_sel_hi:[1,0]
	v_cvt_pk_bf16_f32 v100, v112, v113
	v_cvt_pk_bf16_f32 v101, v114, v115
	v_cvt_pk_bf16_f32 v102, v108, v109
	v_cvt_pk_bf16_f32 v103, v110, v111
	global_store_dwordx4 v[120:121], v[100:103], off
	s_nop 1
	v_cvt_pk_bf16_f32 v100, v104, v105
	v_cvt_pk_bf16_f32 v101, v106, v107
	v_cvt_pk_bf16_f32 v102, v116, v117
	v_cvt_pk_bf16_f32 v103, v124, v125
	global_store_dwordx4 v[120:121], v[100:103], off offset:256
	s_nop 1
	v_mov_b32_e32 v100, v180
	v_lshlrev_b64 v[104:105], 10, v[118:119]
	v_or_b32_e32 v102, 48, v168
	v_lshl_add_u64 v[104:105], s[18:19], 0, v[104:105]
	v_ashrrev_i32_e32 v103, 31, v102
	v_lshl_add_u64 v[104:105], v[104:105], 0, v[174:175]
	v_lshl_add_u64 v[106:107], v[102:103], 2, s[90:91]
	v_pk_mul_f32 v[98:99], v[98:99], v[100:101] op_sel_hi:[1,0]
	v_pk_mul_f32 v[96:97], v[96:97], v[100:101] op_sel_hi:[1,0]
	v_pk_mul_f32 v[94:95], v[94:95], v[100:101] op_sel_hi:[1,0]
	v_pk_mul_f32 v[92:93], v[92:93], v[100:101] op_sel_hi:[1,0]
	v_pk_mul_f32 v[90:91], v[90:91], v[100:101] op_sel_hi:[1,0]
	v_pk_mul_f32 v[88:89], v[88:89], v[100:101] op_sel_hi:[1,0]
	v_pk_mul_f32 v[108:109], v[86:87], v[100:101] op_sel_hi:[1,0]
	v_pk_mul_f32 v[100:101], v[84:85], v[100:101] op_sel_hi:[1,0]
	v_cvt_pk_bf16_f32 v84, v96, v97
	v_cvt_pk_bf16_f32 v85, v98, v99
	v_cvt_pk_bf16_f32 v86, v92, v93
	v_cvt_pk_bf16_f32 v87, v94, v95
	global_store_dwordx4 v[104:105], v[84:87], off
	s_nop 1
	v_cvt_pk_bf16_f32 v84, v88, v89
	v_cvt_pk_bf16_f32 v85, v90, v91
	v_cvt_pk_bf16_f32 v86, v100, v101
	v_cvt_pk_bf16_f32 v87, v108, v109
	global_store_dwordx4 v[104:105], v[84:87], off offset:256
	s_nop 1
	v_mov_b32_e32 v84, v181
	v_pk_mul_f32 v[82:83], v[82:83], v[84:85] op_sel_hi:[1,0]
	v_lshlrev_b64 v[86:87], 10, v[102:103]
	v_lshl_add_u64 v[86:87], s[18:19], 0, v[86:87]
	v_lshl_add_u64 v[86:87], v[86:87], 0, v[174:175]
	v_pk_mul_f32 v[80:81], v[80:81], v[84:85] op_sel_hi:[1,0]
	v_pk_mul_f32 v[78:79], v[78:79], v[84:85] op_sel_hi:[1,0]
	v_pk_mul_f32 v[76:77], v[76:77], v[84:85] op_sel_hi:[1,0]
	v_pk_mul_f32 v[74:75], v[74:75], v[84:85] op_sel_hi:[1,0]
	v_pk_mul_f32 v[72:73], v[72:73], v[84:85] op_sel_hi:[1,0]
	v_pk_mul_f32 v[88:89], v[70:71], v[84:85] op_sel_hi:[1,0]
	v_pk_mul_f32 v[84:85], v[68:69], v[84:85] op_sel_hi:[1,0]
	v_cvt_pk_bf16_f32 v68, v80, v81
	v_cvt_pk_bf16_f32 v69, v82, v83
	v_cvt_pk_bf16_f32 v70, v76, v77
	v_cvt_pk_bf16_f32 v71, v78, v79
	global_store_dwordx4 v[86:87], v[68:71], off
	s_mov_b64 s[18:19], 0x20000
	s_nop 0
	v_cvt_pk_bf16_f32 v68, v72, v73
	v_cvt_pk_bf16_f32 v69, v74, v75
	v_cvt_pk_bf16_f32 v70, v84, v85
	v_cvt_pk_bf16_f32 v71, v88, v89
	global_store_dwordx4 v[86:87], v[68:71], off offset:256
	s_nop 1
	v_mov_b32_e32 v68, v182
	v_add_co_u32_e32 v72, vcc, s9, v148
	v_lshl_add_u64 v[70:71], v[148:149], 0, s[18:19]
	s_nop 0
	v_addc_co_u32_e32 v73, vcc, 0, v149, vcc
	s_mov_b32 s9, 0x24000
	s_mov_b64 s[18:19], 0x24000
	v_pk_mul_f32 v[66:67], v[66:67], v[68:69] op_sel_hi:[1,0]
	v_pk_mul_f32 v[64:65], v[64:65], v[68:69] op_sel_hi:[1,0]
	v_pk_mul_f32 v[62:63], v[62:63], v[68:69] op_sel_hi:[1,0]
	v_pk_mul_f32 v[60:61], v[60:61], v[68:69] op_sel_hi:[1,0]
	v_pk_mul_f32 v[58:59], v[58:59], v[68:69] op_sel_hi:[1,0]
	v_pk_mul_f32 v[56:57], v[56:57], v[68:69] op_sel_hi:[1,0]
	v_pk_mul_f32 v[74:75], v[54:55], v[68:69] op_sel_hi:[1,0]
	v_pk_mul_f32 v[68:69], v[52:53], v[68:69] op_sel_hi:[1,0]
	v_cvt_pk_bf16_f32 v52, v64, v65
	v_cvt_pk_bf16_f32 v53, v66, v67
	v_cvt_pk_bf16_f32 v54, v60, v61
	v_cvt_pk_bf16_f32 v55, v62, v63
	global_store_dwordx4 v[72:73], v[52:55], off
	s_nop 1
	v_cvt_pk_bf16_f32 v52, v56, v57
	v_cvt_pk_bf16_f32 v53, v58, v59
	v_cvt_pk_bf16_f32 v54, v68, v69
	v_cvt_pk_bf16_f32 v55, v74, v75
	global_store_dwordx4 v[70:71], v[52:55], off offset:256
	s_nop 1
	v_mov_b32_e32 v52, v183
	v_add_co_u32_e32 v56, vcc, s9, v148
	v_lshl_add_u64 v[54:55], v[148:149], 0, s[18:19]
	s_nop 0
	v_addc_co_u32_e32 v57, vcc, 0, v149, vcc
	s_mov_b32 s9, 0x28000
	s_mov_b64 s[18:19], 0x28000
	v_pk_mul_f32 v[50:51], v[50:51], v[52:53] op_sel_hi:[1,0]
	v_pk_mul_f32 v[48:49], v[48:49], v[52:53] op_sel_hi:[1,0]
	v_pk_mul_f32 v[46:47], v[46:47], v[52:53] op_sel_hi:[1,0]
	v_pk_mul_f32 v[44:45], v[44:45], v[52:53] op_sel_hi:[1,0]
	v_pk_mul_f32 v[42:43], v[42:43], v[52:53] op_sel_hi:[1,0]
	v_pk_mul_f32 v[40:41], v[40:41], v[52:53] op_sel_hi:[1,0]
	v_pk_mul_f32 v[58:59], v[38:39], v[52:53] op_sel_hi:[1,0]
	v_pk_mul_f32 v[52:53], v[36:37], v[52:53] op_sel_hi:[1,0]
	v_cvt_pk_bf16_f32 v36, v48, v49
	v_cvt_pk_bf16_f32 v37, v50, v51
	v_cvt_pk_bf16_f32 v38, v44, v45
	v_cvt_pk_bf16_f32 v39, v46, v47
	global_store_dwordx4 v[56:57], v[36:39], off
	s_nop 1
	v_cvt_pk_bf16_f32 v36, v40, v41
	v_cvt_pk_bf16_f32 v37, v42, v43
	v_cvt_pk_bf16_f32 v38, v52, v53
	v_cvt_pk_bf16_f32 v39, v58, v59
	global_store_dwordx4 v[54:55], v[36:39], off offset:256
	s_nop 1
	v_mov_b32_e32 v36, v184
	v_add_co_u32_e32 v40, vcc, s9, v148
	v_lshl_add_u64 v[38:39], v[148:149], 0, s[18:19]
	s_nop 0
	v_addc_co_u32_e32 v41, vcc, 0, v149, vcc
	s_andn2_b64 vcc, exec, s[0:1]
	s_mov_b64 s[18:19], s[12:13]
	v_pk_mul_f32 v[34:35], v[34:35], v[36:37] op_sel_hi:[1,0]
	v_pk_mul_f32 v[32:33], v[32:33], v[36:37] op_sel_hi:[1,0]
	v_pk_mul_f32 v[30:31], v[30:31], v[36:37] op_sel_hi:[1,0]
	v_pk_mul_f32 v[28:29], v[28:29], v[36:37] op_sel_hi:[1,0]
	v_pk_mul_f32 v[26:27], v[26:27], v[36:37] op_sel_hi:[1,0]
	v_pk_mul_f32 v[24:25], v[24:25], v[36:37] op_sel_hi:[1,0]
	v_pk_mul_f32 v[42:43], v[22:23], v[36:37] op_sel_hi:[1,0]
	v_pk_mul_f32 v[36:37], v[20:21], v[36:37] op_sel_hi:[1,0]
	v_cvt_pk_bf16_f32 v20, v32, v33
	v_cvt_pk_bf16_f32 v21, v34, v35
	v_cvt_pk_bf16_f32 v22, v28, v29
	v_cvt_pk_bf16_f32 v23, v30, v31
	global_store_dwordx4 v[40:41], v[20:23], off
	s_nop 1
	v_cvt_pk_bf16_f32 v20, v24, v25
	v_cvt_pk_bf16_f32 v21, v26, v27
	v_cvt_pk_bf16_f32 v22, v36, v37
	v_cvt_pk_bf16_f32 v23, v42, v43
	global_store_dwordx4 v[38:39], v[20:23], off offset:256
	s_nop 1
	v_mov_b32_e32 v20, v185
	v_add_co_u32_e64 v24, s[0:1], s38, v148
	v_lshl_add_u64 v[22:23], v[148:149], 0, s[14:15]
	s_nop 0
	v_addc_co_u32_e64 v25, s[0:1], 0, v149, s[0:1]
	v_pk_mul_f32 v[18:19], v[18:19], v[20:21] op_sel_hi:[1,0]
	v_pk_mul_f32 v[16:17], v[16:17], v[20:21] op_sel_hi:[1,0]
	v_pk_mul_f32 v[14:15], v[14:15], v[20:21] op_sel_hi:[1,0]
	v_pk_mul_f32 v[12:13], v[12:13], v[20:21] op_sel_hi:[1,0]
	v_pk_mul_f32 v[10:11], v[10:11], v[20:21] op_sel_hi:[1,0]
	v_pk_mul_f32 v[8:9], v[8:9], v[20:21] op_sel_hi:[1,0]
	v_pk_mul_f32 v[26:27], v[6:7], v[20:21] op_sel_hi:[1,0]
	v_pk_mul_f32 v[20:21], v[4:5], v[20:21] op_sel_hi:[1,0]
	v_cvt_pk_bf16_f32 v4, v16, v17
	v_cvt_pk_bf16_f32 v5, v18, v19
	v_cvt_pk_bf16_f32 v6, v12, v13
	v_cvt_pk_bf16_f32 v7, v14, v15
	global_store_dwordx4 v[24:25], v[4:7], off
	s_nop 1
	v_cvt_pk_bf16_f32 v4, v8, v9
	v_cvt_pk_bf16_f32 v5, v10, v11
	v_cvt_pk_bf16_f32 v6, v20, v21
	v_cvt_pk_bf16_f32 v7, v26, v27
	global_store_dwordx4 v[22:23], v[4:7], off offset:256
	s_cbranch_vccnz .LBB0_5220
	s_waitcnt vmcnt(0)
	s_cmpk_gt_u32 s24, 0xff
	s_cbranch_scc1 .LBB0_5231
	s_barrier
